# v9
# baseline (speedup 1.0000x reference)
; #define PG8_STAGE(bufoff, gbase) PG8_STAGEV(bufoff, gbase, voff)
; #define PG8_STAGEB(bufoff, gbase) PG8_STAGEV(bufoff, gbase, voffB)
; #define PG8_LDA(dst, b, h) do { _Pragma("unroll") for (int m = 0; m < 4; ++m) _Pragma("unroll") for (int k = 0; k < 2; ++k) dst[m][k] = *(const LAS bf16x8*)(lds + PG8_SA(b, h) + aoff + m * 2048 + k * 1024); } while (0)
; #define PG8_LDB(dst, b, h) do { _Pragma("unroll") for (int n = 0; n < 2; ++n) _Pragma("unroll") for (int k = 0; k < 2; ++k) dst[n][k] = *(const LAS bf16x8*)(lds + PG8_SB(b, h) + boff + n * 2048 + k * 1024); } while (0)
; #define PG8_MMA(ai, bj, At, Bt) do { __builtin_amdgcn_s_setprio(1); _Pragma("unroll") for (int m = 0; m < 4; ++m) _Pragma("unroll") for (int n = 0; n < 2; ++n) _Pragma("unroll") for (int k = 0; k < 2; ++k) \
;         acc[ai][bj][m][n] = __builtin_amdgcn_mfma_f32_16x16x32_bf16(Bt[n][k], At[m][k], acc[ai][bj][m][n], 0, 0, 0); __builtin_amdgcn_s_setprio(0); } while (0)
; #define PG8_WAIT_V(n) asm volatile("s_waitcnt vmcnt(" #n ")" ::: "memory")
; #define PG8_WAIT_L(n) asm volatile("s_waitcnt lgkmcnt(" #n ")" ::: "memory")
; #define PG8_BAR __builtin_amdgcn_s_barrier()
; #define PG8_SCHED __builtin_amdgcn_sched_barrier(0)
; template <bool PERM, class Epi, class Sched>
; __device__ __forceinline__ void gemm_phase(LAS unsigned char* lds, const int K, const Sched& S, const Epi& E, const int wid0) {
;     ...
;             PG8_LDB(B0, 0, 0); PG8_LDB(B1, 0, 1); PG8_SCHED; PG8_LDA(At, 0, 0); PG8_STAGE(PG8_SA(1, 1), a1 + hstep);
;             PG8_WAIT_V(8); PG8_WAIT_L(0); PG8_BAR; PG8_MMA(0, 0, At, B0); PG8_MMA(0, 1, At, B1); PG8_BAR; PG8_SCHED;
;             PG8_LDA(At, 0, 1); PG8_STAGEB(PG8_SB(0, 0), b2); PG8_STAGEB(PG8_SB(0, 1), b2 + hstep); PG8_STAGE(PG8_SA(0, 0), a2);
;             PG8_WAIT_V(8); PG8_WAIT_L(0); PG8_BAR; PG8_MMA(1, 0, At, B0); PG8_MMA(1, 1, At, B1); PG8_BAR; PG8_SCHED;
.LBB0_104:
	ds_read_b128 v[0:3], v141
	ds_read_b128 v[4:7], v141 offset:1024
	ds_read_b128 v[8:11], v141 offset:2048
	ds_read_b128 v[12:15], v141 offset:3072
	ds_read_b128 v[16:19], v142
	ds_read_b128 v[20:23], v142 offset:1024
	ds_read_b128 v[24:27], v142 offset:2048
	ds_read_b128 v[28:31], v142 offset:3072
	s_ashr_i32 s53, s52, 31
	s_lshl_b64 s[40:41], s[52:53], 17
	v_readlane_b32 s42, v253, 29
	v_readlane_b32 s43, v253, 30
	s_add_u32 s40, s42, s40
	s_addc_u32 s41, s43, s41
	s_and_b64 s[42:43], s[0:1], exec
	s_cselect_b32 s51, s41, s45
	s_cselect_b32 s50, s40, s44
	s_ashr_i32 s37, s36, 31
	s_lshl_b64 s[42:43], s[36:37], 17
	s_add_u32 s42, s16, s42
	s_addc_u32 s43, s17, s43
	s_and_b64 s[48:49], s[0:1], exec
	s_cselect_b32 s49, s43, s47
	s_cselect_b32 s48, s42, s46
	s_add_u32 s62, s44, 0x10080
	s_addc_u32 s63, s45, 0
	s_add_i32 s65, s15, 0xc000
	v_lshl_add_u64 v[64:65], s[62:63], 0, v[128:129]
	s_mov_b32 m0, s65
	s_add_i32 s37, s15, 0xe000
	ds_read_b128 v[32:35], v143
	ds_read_b128 v[36:39], v143 offset:1024
	ds_read_b128 v[40:43], v143 offset:2048
	ds_read_b128 v[44:47], v143 offset:3072
	ds_read_b128 v[48:51], v143 offset:4096
	ds_read_b128 v[52:55], v143 offset:5120
	ds_read_b128 v[56:59], v143 offset:6144
	ds_read_b128 v[60:63], v143 offset:7168
	global_load_lds_dwordx4 v[64:65], off
	v_lshl_add_u64 v[64:65], s[62:63], 0, v[130:131]
	s_mov_b32 m0, s37
	s_nop 0
	global_load_lds_dwordx4 v[64:65], off
	s_waitcnt vmcnt(8)
	s_waitcnt lgkmcnt(0)
	s_barrier
	s_setprio 1
	s_waitcnt lgkmcnt(0)
	v_mfma_f32_16x16x32_bf16 v[64:67], v[0:3], v[32:35], 0
	v_mfma_f32_16x16x32_bf16 v[68:71], v[8:11], v[32:35], 0
	v_mfma_f32_16x16x32_bf16 v[72:75], v[0:3], v[40:43], 0
	v_mfma_f32_16x16x32_bf16 v[76:79], v[8:11], v[40:43], 0
	v_mfma_f32_16x16x32_bf16 v[80:83], v[0:3], v[48:51], 0
	v_mfma_f32_16x16x32_bf16 v[84:87], v[8:11], v[48:51], 0
	v_mfma_f32_16x16x32_bf16 v[88:91], v[0:3], v[56:59], 0
	v_mfma_f32_16x16x32_bf16 v[92:95], v[8:11], v[56:59], 0
	v_mfma_f32_16x16x32_bf16 v[64:67], v[4:7], v[36:39], v[64:67]
	v_mfma_f32_16x16x32_bf16 v[68:71], v[12:15], v[36:39], v[68:71]
	v_mfma_f32_16x16x32_bf16 v[72:75], v[4:7], v[44:47], v[72:75]
	v_mfma_f32_16x16x32_bf16 v[76:79], v[12:15], v[44:47], v[76:79]
	v_mfma_f32_16x16x32_bf16 v[80:83], v[4:7], v[52:55], v[80:83]
	v_mfma_f32_16x16x32_bf16 v[84:87], v[12:15], v[52:55], v[84:87]
	v_mfma_f32_16x16x32_bf16 v[88:91], v[4:7], v[60:63], v[88:91]
	v_mfma_f32_16x16x32_bf16 v[92:95], v[12:15], v[60:63], v[92:95]
	v_mfma_f32_16x16x32_bf16 v[96:99], v[16:19], v[32:35], 0
	v_mfma_f32_16x16x32_bf16 v[32:35], v[24:27], v[32:35], 0
	v_mfma_f32_16x16x32_bf16 v[96:99], v[20:23], v[36:39], v[96:99]
	v_mfma_f32_16x16x32_bf16 v[32:35], v[28:31], v[36:39], v[32:35]
	v_mfma_f32_16x16x32_bf16 v[36:39], v[16:19], v[40:43], 0
	v_mfma_f32_16x16x32_bf16 v[40:43], v[24:27], v[40:43], 0
	v_mfma_f32_16x16x32_bf16 v[36:39], v[20:23], v[44:47], v[36:39]
	v_mfma_f32_16x16x32_bf16 v[40:43], v[28:31], v[44:47], v[40:43]
	v_mfma_f32_16x16x32_bf16 v[44:47], v[16:19], v[48:51], 0
	v_mfma_f32_16x16x32_bf16 v[48:51], v[24:27], v[48:51], 0
	v_mfma_f32_16x16x32_bf16 v[44:47], v[20:23], v[52:55], v[44:47]
	v_mfma_f32_16x16x32_bf16 v[48:51], v[28:31], v[52:55], v[48:51]
	v_mfma_f32_16x16x32_bf16 v[52:55], v[16:19], v[56:59], 0
	v_mfma_f32_16x16x32_bf16 v[56:59], v[24:27], v[56:59], 0
	v_mfma_f32_16x16x32_bf16 v[52:55], v[20:23], v[60:63], v[52:55]
	v_mfma_f32_16x16x32_bf16 v[56:59], v[28:31], v[60:63], v[56:59]
	s_setprio 0
	s_barrier
	s_add_i32 s63, s59, s14
	v_lshl_add_u64 v[196:197], s[46:47], 0, v[128:129]
	s_add_i32 s53, s63, 0x2000
	v_lshl_add_u64 v[144:145], v[196:197], 0, s[20:21]
	s_mov_b32 m0, s63
	v_lshl_add_u64 v[212:213], s[46:47], 0, v[130:131]
	s_add_u32 s66, s46, 0x10100
	ds_read_b128 v[60:63], v143 offset:16384
	ds_read_b128 v[100:103], v143 offset:17408
	ds_read_b128 v[104:107], v143 offset:18432
	ds_read_b128 v[108:111], v143 offset:19456
	ds_read_b128 v[112:115], v143 offset:20480
	ds_read_b128 v[116:119], v143 offset:21504
	ds_read_b128 v[120:123], v143 offset:22528
	ds_read_b128 v[124:127], v143 offset:23552
	global_load_lds_dwordx4 v[144:145], off
	v_lshl_add_u64 v[144:145], v[212:213], 0, s[20:21]
	s_mov_b32 m0, s53
	s_addc_u32 s67, s47, 0
	s_add_i32 s61, s60, s14
	global_load_lds_dwordx4 v[144:145], off
	v_lshl_add_u64 v[144:145], s[66:67], 0, v[128:129]
	s_mov_b32 m0, s61
	s_add_i32 s62, s61, 0x2000
	global_load_lds_dwordx4 v[144:145], off
	v_lshl_add_u64 v[144:145], s[66:67], 0, v[130:131]
	s_mov_b32 m0, s62
	v_lshl_add_u64 v[214:215], s[44:45], 0, v[128:129]
	global_load_lds_dwordx4 v[144:145], off
	v_lshl_add_u64 v[144:145], v[214:215], 0, s[20:21]
	s_mov_b32 m0, s15
	v_lshl_add_u64 v[216:217], s[44:45], 0, v[130:131]
	global_load_lds_dwordx4 v[144:145], off
	v_lshl_add_u64 v[144:145], v[216:217], 0, s[20:21]
	s_mov_b32 m0, s38
	s_nop 0
	global_load_lds_dwordx4 v[144:145], off
	s_waitcnt vmcnt(8)
	s_waitcnt lgkmcnt(0)
	s_barrier
; #define PG8_STAGE(bufoff, gbase) PG8_STAGEV(bufoff, gbase, voff)
; #define PG8_LDA(dst, b, h) do { _Pragma("unroll") for (int m = 0; m < 4; ++m) _Pragma("unroll") for (int k = 0; k < 2; ++k) dst[m][k] = *(const LAS bf16x8*)(lds + PG8_SA(b, h) + aoff + m * 2048 + k * 1024); } while (0)
; #define PG8_LDB(dst, b, h) do { _Pragma("unroll") for (int n = 0; n < 2; ++n) _Pragma("unroll") for (int k = 0; k < 2; ++k) dst[n][k] = *(const LAS bf16x8*)(lds + PG8_SB(b, h) + boff + n * 2048 + k * 1024); } while (0)
; #define PG8_MMA(ai, bj, At, Bt) do { __builtin_amdgcn_s_setprio(1); _Pragma("unroll") for (int m = 0; m < 4; ++m) _Pragma("unroll") for (int n = 0; n < 2; ++n) _Pragma("unroll") for (int k = 0; k < 2; ++k) \
;         acc[ai][bj][m][n] = __builtin_amdgcn_mfma_f32_16x16x32_bf16(Bt[n][k], At[m][k], acc[ai][bj][m][n], 0, 0, 0); __builtin_amdgcn_s_setprio(0); } while (0)
; #define PG8_WAIT_V(n) asm volatile("s_waitcnt vmcnt(" #n ")" ::: "memory")
; #define PG8_WAIT_L(n) asm volatile("s_waitcnt lgkmcnt(" #n ")" ::: "memory")
; #define PG8_BAR __builtin_amdgcn_s_barrier()
; #define PG8_SCHED __builtin_amdgcn_sched_barrier(0)
; template <bool PERM, class Epi, class Sched>
; __device__ __forceinline__ void gemm_phase(LAS unsigned char* lds, const int K, const Sched& S, const Epi& E, const int wid0) {
;     ...
;             PG8_WAIT_V(8); PG8_WAIT_L(0); PG8_BAR; PG8_MMA(1, 0, At, B0); PG8_MMA(1, 1, At, B1); PG8_BAR; PG8_SCHED;
;             PG8_LDB(B0, 1, 0); PG8_LDB(B1, 1, 1); PG8_SCHED; PG8_LDA(At, 1, 0); PG8_STAGE(PG8_SA(0, 1), a2 + hstep);
;             PG8_WAIT_V(8); PG8_WAIT_L(0); PG8_BAR; PG8_MMA(0, 0, At, B0); PG8_MMA(0, 1, At, B1); PG8_BAR; PG8_SCHED;
	s_setprio 1
	s_waitcnt lgkmcnt(0)
	v_mfma_f32_16x16x32_bf16 v[144:147], v[0:3], v[60:63], 0
	v_mfma_f32_16x16x32_bf16 v[152:155], v[0:3], v[104:107], 0
	v_mfma_f32_16x16x32_bf16 v[160:163], v[0:3], v[112:115], 0
	v_mfma_f32_16x16x32_bf16 v[0:3], v[0:3], v[120:123], 0
	v_mfma_f32_16x16x32_bf16 v[144:147], v[4:7], v[100:103], v[144:147]
	v_mfma_f32_16x16x32_bf16 v[152:155], v[4:7], v[108:111], v[152:155]
	v_mfma_f32_16x16x32_bf16 v[160:163], v[4:7], v[116:119], v[160:163]
	v_mfma_f32_16x16x32_bf16 v[0:3], v[4:7], v[124:127], v[0:3]
	v_mfma_f32_16x16x32_bf16 v[4:7], v[8:11], v[120:123], 0
	v_mfma_f32_16x16x32_bf16 v[148:151], v[8:11], v[60:63], 0
	v_mfma_f32_16x16x32_bf16 v[156:159], v[8:11], v[104:107], 0
	v_mfma_f32_16x16x32_bf16 v[164:167], v[8:11], v[112:115], 0
	v_mfma_f32_16x16x32_bf16 v[4:7], v[12:15], v[124:127], v[4:7]
	v_mfma_f32_16x16x32_bf16 v[148:151], v[12:15], v[100:103], v[148:151]
	v_mfma_f32_16x16x32_bf16 v[156:159], v[12:15], v[108:111], v[156:159]
	v_mfma_f32_16x16x32_bf16 v[164:167], v[12:15], v[116:119], v[164:167]
	v_mfma_f32_16x16x32_bf16 v[8:11], v[16:19], v[60:63], 0
	v_mfma_f32_16x16x32_bf16 v[12:15], v[24:27], v[60:63], 0
	v_mfma_f32_16x16x32_bf16 v[8:11], v[20:23], v[100:103], v[8:11]
	v_mfma_f32_16x16x32_bf16 v[12:15], v[28:31], v[100:103], v[12:15]
	v_mfma_f32_16x16x32_bf16 v[60:63], v[16:19], v[104:107], 0
	v_mfma_f32_16x16x32_bf16 v[100:103], v[24:27], v[104:107], 0
	v_mfma_f32_16x16x32_bf16 v[104:107], v[16:19], v[112:115], 0
	v_mfma_f32_16x16x32_bf16 v[16:19], v[16:19], v[120:123], 0
	v_mfma_f32_16x16x32_bf16 v[60:63], v[20:23], v[108:111], v[60:63]
	v_mfma_f32_16x16x32_bf16 v[100:103], v[28:31], v[108:111], v[100:103]
	v_mfma_f32_16x16x32_bf16 v[104:107], v[20:23], v[116:119], v[104:107]
	v_mfma_f32_16x16x32_bf16 v[108:111], v[24:27], v[112:115], 0
	v_mfma_f32_16x16x32_bf16 v[16:19], v[20:23], v[124:127], v[16:19]
	v_mfma_f32_16x16x32_bf16 v[20:23], v[24:27], v[120:123], 0
	v_mfma_f32_16x16x32_bf16 v[108:111], v[28:31], v[116:119], v[108:111]
	v_mfma_f32_16x16x32_bf16 v[20:23], v[28:31], v[124:127], v[20:23]
	s_setprio 0
	s_barrier
	s_add_i32 s64, 0, 0x18000
	s_add_i32 s70, 0, 0x1c000
	v_add_u32_e32 v198, s64, v140
	v_add_u32_e32 v224, s70, v140
	ds_read_b128 v[24:27], v198
	ds_read_b128 v[28:31], v198 offset:1024
	ds_read_b128 v[112:115], v198 offset:2048
	ds_read_b128 v[116:119], v198 offset:3072
	ds_read_b128 v[120:123], v224
	ds_read_b128 v[124:127], v224 offset:1024
	ds_read_b128 v[168:171], v224 offset:2048
	ds_read_b128 v[172:175], v224 offset:3072
	s_add_u32 s66, s44, 0x10100
	s_addc_u32 s67, s45, 0
	s_mov_b32 m0, s39
	v_lshl_add_u64 v[218:219], s[66:67], 0, v[128:129]
	ds_read_b128 v[176:179], v143 offset:32768
	ds_read_b128 v[180:183], v143 offset:33792
	ds_read_b128 v[184:187], v143 offset:34816
	ds_read_b128 v[188:191], v143 offset:35840
	ds_read_b128 v[192:195], v143 offset:36864
	ds_read_b128 v[200:203], v143 offset:37888
	ds_read_b128 v[204:207], v143 offset:38912
	ds_read_b128 v[208:211], v143 offset:39936
	global_load_lds_dwordx4 v[218:219], off
	v_lshl_add_u64 v[218:219], s[66:67], 0, v[130:131]
	s_mov_b32 m0, s54
	s_nop 0
	global_load_lds_dwordx4 v[218:219], off
	s_waitcnt vmcnt(8)
	s_waitcnt lgkmcnt(0)
	s_barrier
	s_setprio 1
	s_waitcnt lgkmcnt(0)
	v_mfma_f32_16x16x32_bf16 v[64:67], v[24:27], v[176:179], v[64:67]
	v_mfma_f32_16x16x32_bf16 v[68:71], v[112:115], v[176:179], v[68:71]
	v_mfma_f32_16x16x32_bf16 v[72:75], v[24:27], v[184:187], v[72:75]
	v_mfma_f32_16x16x32_bf16 v[76:79], v[112:115], v[184:187], v[76:79]
	v_mfma_f32_16x16x32_bf16 v[80:83], v[24:27], v[192:195], v[80:83]
	v_mfma_f32_16x16x32_bf16 v[84:87], v[112:115], v[192:195], v[84:87]
	v_mfma_f32_16x16x32_bf16 v[88:91], v[24:27], v[204:207], v[88:91]
	v_mfma_f32_16x16x32_bf16 v[92:95], v[112:115], v[204:207], v[92:95]
	v_mfma_f32_16x16x32_bf16 v[64:67], v[28:31], v[180:183], v[64:67]
	v_mfma_f32_16x16x32_bf16 v[68:71], v[116:119], v[180:183], v[68:71]
	v_mfma_f32_16x16x32_bf16 v[72:75], v[28:31], v[188:191], v[72:75]
	v_mfma_f32_16x16x32_bf16 v[76:79], v[116:119], v[188:191], v[76:79]
	v_mfma_f32_16x16x32_bf16 v[80:83], v[28:31], v[200:203], v[80:83]
	v_mfma_f32_16x16x32_bf16 v[84:87], v[116:119], v[200:203], v[84:87]
	v_mfma_f32_16x16x32_bf16 v[88:91], v[28:31], v[208:211], v[88:91]
	v_mfma_f32_16x16x32_bf16 v[92:95], v[116:119], v[208:211], v[92:95]
	v_mfma_f32_16x16x32_bf16 v[96:99], v[120:123], v[176:179], v[96:99]
	v_mfma_f32_16x16x32_bf16 v[32:35], v[168:171], v[176:179], v[32:35]
	v_mfma_f32_16x16x32_bf16 v[36:39], v[120:123], v[184:187], v[36:39]
	v_mfma_f32_16x16x32_bf16 v[40:43], v[168:171], v[184:187], v[40:43]
	v_mfma_f32_16x16x32_bf16 v[44:47], v[120:123], v[192:195], v[44:47]
	v_mfma_f32_16x16x32_bf16 v[48:51], v[168:171], v[192:195], v[48:51]
	v_mfma_f32_16x16x32_bf16 v[52:55], v[120:123], v[204:207], v[52:55]
	v_mfma_f32_16x16x32_bf16 v[56:59], v[168:171], v[204:207], v[56:59]
	v_mfma_f32_16x16x32_bf16 v[96:99], v[124:127], v[180:183], v[96:99]
	v_mfma_f32_16x16x32_bf16 v[32:35], v[172:175], v[180:183], v[32:35]
	v_mfma_f32_16x16x32_bf16 v[36:39], v[124:127], v[188:191], v[36:39]
	v_mfma_f32_16x16x32_bf16 v[40:43], v[172:175], v[188:191], v[40:43]
	v_mfma_f32_16x16x32_bf16 v[44:47], v[124:127], v[200:203], v[44:47]
	v_mfma_f32_16x16x32_bf16 v[48:51], v[172:175], v[200:203], v[48:51]
	v_mfma_f32_16x16x32_bf16 v[52:55], v[124:127], v[208:211], v[52:55]
	v_mfma_f32_16x16x32_bf16 v[56:59], v[172:175], v[208:211], v[56:59]
	s_setprio 0
	s_barrier
; #define PG8_STAGE(bufoff, gbase) PG8_STAGEV(bufoff, gbase, voff)
; #define PG8_STAGEB(bufoff, gbase) PG8_STAGEV(bufoff, gbase, voffB)
; #define PG8_LDA(dst, b, h) do { _Pragma("unroll") for (int m = 0; m < 4; ++m) _Pragma("unroll") for (int k = 0; k < 2; ++k) dst[m][k] = *(const LAS bf16x8*)(lds + PG8_SA(b, h) + aoff + m * 2048 + k * 1024); } while (0)
; #define PG8_MMA(ai, bj, At, Bt) do { __builtin_amdgcn_s_setprio(1); _Pragma("unroll") for (int m = 0; m < 4; ++m) _Pragma("unroll") for (int n = 0; n < 2; ++n) _Pragma("unroll") for (int k = 0; k < 2; ++k) \
;         acc[ai][bj][m][n] = __builtin_amdgcn_mfma_f32_16x16x32_bf16(Bt[n][k], At[m][k], acc[ai][bj][m][n], 0, 0, 0); __builtin_amdgcn_s_setprio(0); } while (0)
; #define PG8_WAIT_V(n) asm volatile("s_waitcnt vmcnt(" #n ")" ::: "memory")
; #define PG8_WAIT_L(n) asm volatile("s_waitcnt lgkmcnt(" #n ")" ::: "memory")
; #define PG8_BAR __builtin_amdgcn_s_barrier()
; #define PG8_SCHED __builtin_amdgcn_sched_barrier(0)
; template <bool PERM, class Epi, class Sched>
; __device__ __forceinline__ void gemm_phase(LAS unsigned char* lds, const int K, const Sched& S, const Epi& E, const int wid0) {
;     ...
;             PG8_WAIT_V(8); PG8_WAIT_L(0); PG8_BAR; PG8_MMA(0, 0, At, B0); PG8_MMA(0, 1, At, B1); PG8_BAR; PG8_SCHED;
;             PG8_LDA(At, 1, 1); PG8_STAGEB(PG8_SB(1, 0), b3); PG8_STAGEB(PG8_SB(1, 1), b3 + hstep); PG8_STAGE(PG8_SA(1, 0), a3);
;             PG8_WAIT_V(8); PG8_WAIT_L(0); PG8_BAR; PG8_MMA(1, 0, At, B0); PG8_MMA(1, 1, At, B1); PG8_BAR; PG8_SCHED;
	s_add_i32 s66, s64, s14
	s_add_i32 s64, s66, 0x2000
	v_lshl_add_u64 v[196:197], v[196:197], 0, s[22:23]
	s_mov_b32 m0, s66
	s_add_u32 s68, s46, 0x10180
	ds_read_b128 v[176:179], v143 offset:49152
	ds_read_b128 v[180:183], v143 offset:50176
	ds_read_b128 v[184:187], v143 offset:51200
	ds_read_b128 v[188:191], v143 offset:52224
	ds_read_b128 v[192:195], v143 offset:53248
	ds_read_b128 v[200:203], v143 offset:54272
	ds_read_b128 v[204:207], v143 offset:55296
	ds_read_b128 v[208:211], v143 offset:56320
	global_load_lds_dwordx4 v[196:197], off
	v_lshl_add_u64 v[196:197], v[212:213], 0, s[22:23]
	s_mov_b32 m0, s64
	s_addc_u32 s69, s47, 0
	s_add_i32 s46, s70, s14
	global_load_lds_dwordx4 v[196:197], off
	v_lshl_add_u64 v[196:197], s[68:69], 0, v[128:129]
	s_mov_b32 m0, s46
	s_add_i32 s47, s46, 0x2000
	global_load_lds_dwordx4 v[196:197], off
	v_lshl_add_u64 v[196:197], s[68:69], 0, v[130:131]
	s_mov_b32 m0, s47
	s_nop 0
	global_load_lds_dwordx4 v[196:197], off
	v_lshl_add_u64 v[196:197], v[214:215], 0, s[22:23]
	s_mov_b32 m0, s55
	s_nop 0
	global_load_lds_dwordx4 v[196:197], off
	v_lshl_add_u64 v[196:197], v[216:217], 0, s[22:23]
	s_mov_b32 m0, s56
	s_nop 0
	global_load_lds_dwordx4 v[196:197], off
	s_waitcnt vmcnt(8)
	s_waitcnt lgkmcnt(0)
	s_barrier
	s_setprio 1
	s_waitcnt lgkmcnt(0)
	v_mfma_f32_16x16x32_bf16 v[0:3], v[24:27], v[204:207], v[0:3]
	v_mfma_f32_16x16x32_bf16 v[4:7], v[112:115], v[204:207], v[4:7]
	v_mfma_f32_16x16x32_bf16 v[144:147], v[24:27], v[176:179], v[144:147]
	v_mfma_f32_16x16x32_bf16 v[148:151], v[112:115], v[176:179], v[148:151]
	v_mfma_f32_16x16x32_bf16 v[152:155], v[24:27], v[184:187], v[152:155]
	v_mfma_f32_16x16x32_bf16 v[156:159], v[112:115], v[184:187], v[156:159]
	v_mfma_f32_16x16x32_bf16 v[160:163], v[24:27], v[192:195], v[160:163]
	v_mfma_f32_16x16x32_bf16 v[164:167], v[112:115], v[192:195], v[164:167]
	v_mfma_f32_16x16x32_bf16 v[0:3], v[28:31], v[208:211], v[0:3]
	v_mfma_f32_16x16x32_bf16 v[4:7], v[116:119], v[208:211], v[4:7]
	v_mfma_f32_16x16x32_bf16 v[144:147], v[28:31], v[180:183], v[144:147]
	v_mfma_f32_16x16x32_bf16 v[148:151], v[116:119], v[180:183], v[148:151]
	v_mfma_f32_16x16x32_bf16 v[152:155], v[28:31], v[188:191], v[152:155]
	v_mfma_f32_16x16x32_bf16 v[156:159], v[116:119], v[188:191], v[156:159]
	v_mfma_f32_16x16x32_bf16 v[160:163], v[28:31], v[200:203], v[160:163]
	v_mfma_f32_16x16x32_bf16 v[164:167], v[116:119], v[200:203], v[164:167]
	v_mfma_f32_16x16x32_bf16 v[8:11], v[120:123], v[176:179], v[8:11]
	v_mfma_f32_16x16x32_bf16 v[12:15], v[168:171], v[176:179], v[12:15]
	v_mfma_f32_16x16x32_bf16 v[24:27], v[120:123], v[184:187], v[60:63]
	v_mfma_f32_16x16x32_bf16 v[28:31], v[168:171], v[184:187], v[100:103]
	v_mfma_f32_16x16x32_bf16 v[60:63], v[120:123], v[192:195], v[104:107]
	v_mfma_f32_16x16x32_bf16 v[100:103], v[168:171], v[192:195], v[108:111]
	v_mfma_f32_16x16x32_bf16 v[16:19], v[120:123], v[204:207], v[16:19]
	v_mfma_f32_16x16x32_bf16 v[20:23], v[168:171], v[204:207], v[20:23]
	v_mfma_f32_16x16x32_bf16 v[8:11], v[124:127], v[180:183], v[8:11]
	v_mfma_f32_16x16x32_bf16 v[12:15], v[172:175], v[180:183], v[12:15]
	v_mfma_f32_16x16x32_bf16 v[24:27], v[124:127], v[188:191], v[24:27]
	v_mfma_f32_16x16x32_bf16 v[28:31], v[172:175], v[188:191], v[28:31]
	v_mfma_f32_16x16x32_bf16 v[60:63], v[124:127], v[200:203], v[60:63]
	v_mfma_f32_16x16x32_bf16 v[100:103], v[172:175], v[200:203], v[100:103]
	v_mfma_f32_16x16x32_bf16 v[16:19], v[124:127], v[208:211], v[16:19]
	v_mfma_f32_16x16x32_bf16 v[20:23], v[172:175], v[208:211], v[20:23]
	s_setprio 0
	s_barrier
	ds_read_b128 v[104:107], v141
	ds_read_b128 v[108:111], v141 offset:1024
	ds_read_b128 v[112:115], v141 offset:2048
	ds_read_b128 v[116:119], v141 offset:3072
	ds_read_b128 v[120:123], v142
	ds_read_b128 v[124:127], v142 offset:1024
	ds_read_b128 v[168:171], v142 offset:2048
	ds_read_b128 v[172:175], v142 offset:3072
	s_add_u32 s44, s44, 0x10180
	s_addc_u32 s45, s45, 0
	s_mov_b32 m0, s65
	v_lshl_add_u64 v[196:197], s[44:45], 0, v[128:129]
	ds_read_b128 v[176:179], v143
	ds_read_b128 v[180:183], v143 offset:1024
	ds_read_b128 v[184:187], v143 offset:2048
	ds_read_b128 v[188:191], v143 offset:3072
	ds_read_b128 v[192:195], v143 offset:4096
	ds_read_b128 v[200:203], v143 offset:5120
	ds_read_b128 v[204:207], v143 offset:6144
	ds_read_b128 v[208:211], v143 offset:7168
	global_load_lds_dwordx4 v[196:197], off
	v_lshl_add_u64 v[196:197], s[44:45], 0, v[130:131]
	s_mov_b32 m0, s37
	s_nop 0
	global_load_lds_dwordx4 v[196:197], off
	s_waitcnt vmcnt(8)
	s_waitcnt lgkmcnt(0)
	s_barrier
; #define PG8_STAGE(bufoff, gbase) PG8_STAGEV(bufoff, gbase, voff)
; #define PG8_STAGEB(bufoff, gbase) PG8_STAGEV(bufoff, gbase, voffB)
; #define PG8_LDA(dst, b, h) do { _Pragma("unroll") for (int m = 0; m < 4; ++m) _Pragma("unroll") for (int k = 0; k < 2; ++k) dst[m][k] = *(const LAS bf16x8*)(lds + PG8_SA(b, h) + aoff + m * 2048 + k * 1024); } while (0)
; #define PG8_LDB(dst, b, h) do { _Pragma("unroll") for (int n = 0; n < 2; ++n) _Pragma("unroll") for (int k = 0; k < 2; ++k) dst[n][k] = *(const LAS bf16x8*)(lds + PG8_SB(b, h) + boff + n * 2048 + k * 1024); } while (0)
; #define PG8_MMA(ai, bj, At, Bt) do { __builtin_amdgcn_s_setprio(1); _Pragma("unroll") for (int m = 0; m < 4; ++m) _Pragma("unroll") for (int n = 0; n < 2; ++n) _Pragma("unroll") for (int k = 0; k < 2; ++k) \
;         acc[ai][bj][m][n] = __builtin_amdgcn_mfma_f32_16x16x32_bf16(Bt[n][k], At[m][k], acc[ai][bj][m][n], 0, 0, 0); __builtin_amdgcn_s_setprio(0); } while (0)
; #define PG8_WAIT_V(n) asm volatile("s_waitcnt vmcnt(" #n ")" ::: "memory")
; #define PG8_WAIT_L(n) asm volatile("s_waitcnt lgkmcnt(" #n ")" ::: "memory")
; #define PG8_BAR __builtin_amdgcn_s_barrier()
; #define PG8_SCHED __builtin_amdgcn_sched_barrier(0)
; template <bool PERM, class Epi, class Sched>
; __device__ __forceinline__ void gemm_phase(LAS unsigned char* lds, const int K, const Sched& S, const Epi& E, const int wid0) {
;     ...
;             PG8_LDB(B0, 0, 0); PG8_LDB(B1, 0, 1); PG8_SCHED; PG8_LDA(At, 0, 0); PG8_STAGE(PG8_SA(1, 1), a1 + hstep);
;             PG8_WAIT_V(8); PG8_WAIT_L(0); PG8_BAR; PG8_MMA(0, 0, At, B0); PG8_MMA(0, 1, At, B1); PG8_BAR; PG8_SCHED;
;             PG8_LDA(At, 0, 1); PG8_STAGEB(PG8_SB(0, 0), b2); PG8_STAGEB(PG8_SB(0, 1), b2 + hstep); PG8_STAGE(PG8_SA(0, 0), a2);
;             PG8_WAIT_V(8); PG8_WAIT_L(0); PG8_BAR; PG8_MMA(1, 0, At, B0); PG8_MMA(1, 1, At, B1); PG8_BAR; PG8_SCHED;
	s_setprio 1
	s_waitcnt lgkmcnt(0)
	v_mfma_f32_16x16x32_bf16 v[64:67], v[104:107], v[176:179], v[64:67]
	v_mfma_f32_16x16x32_bf16 v[68:71], v[112:115], v[176:179], v[68:71]
	v_mfma_f32_16x16x32_bf16 v[72:75], v[104:107], v[184:187], v[72:75]
	v_mfma_f32_16x16x32_bf16 v[76:79], v[112:115], v[184:187], v[76:79]
	v_mfma_f32_16x16x32_bf16 v[80:83], v[104:107], v[192:195], v[80:83]
	v_mfma_f32_16x16x32_bf16 v[84:87], v[112:115], v[192:195], v[84:87]
	v_mfma_f32_16x16x32_bf16 v[88:91], v[104:107], v[204:207], v[88:91]
	v_mfma_f32_16x16x32_bf16 v[92:95], v[112:115], v[204:207], v[92:95]
	v_mfma_f32_16x16x32_bf16 v[64:67], v[108:111], v[180:183], v[64:67]
	v_mfma_f32_16x16x32_bf16 v[68:71], v[116:119], v[180:183], v[68:71]
	v_mfma_f32_16x16x32_bf16 v[72:75], v[108:111], v[188:191], v[72:75]
	v_mfma_f32_16x16x32_bf16 v[76:79], v[116:119], v[188:191], v[76:79]
	v_mfma_f32_16x16x32_bf16 v[80:83], v[108:111], v[200:203], v[80:83]
	v_mfma_f32_16x16x32_bf16 v[84:87], v[116:119], v[200:203], v[84:87]
	v_mfma_f32_16x16x32_bf16 v[88:91], v[108:111], v[208:211], v[88:91]
	v_mfma_f32_16x16x32_bf16 v[92:95], v[116:119], v[208:211], v[92:95]
	v_mfma_f32_16x16x32_bf16 v[32:35], v[168:171], v[176:179], v[32:35]
	v_mfma_f32_16x16x32_bf16 v[96:99], v[120:123], v[176:179], v[96:99]
	v_mfma_f32_16x16x32_bf16 v[176:179], v[172:175], v[180:183], v[32:35]
	v_mfma_f32_16x16x32_bf16 v[32:35], v[120:123], v[184:187], v[36:39]
	v_mfma_f32_16x16x32_bf16 v[212:215], v[124:127], v[180:183], v[96:99]
	v_mfma_f32_16x16x32_bf16 v[180:183], v[124:127], v[188:191], v[32:35]
	v_mfma_f32_16x16x32_bf16 v[32:35], v[168:171], v[184:187], v[40:43]
	v_mfma_f32_16x16x32_bf16 v[40:43], v[172:175], v[188:191], v[32:35]
	v_mfma_f32_16x16x32_bf16 v[32:35], v[120:123], v[192:195], v[44:47]
	v_mfma_f32_16x16x32_bf16 v[44:47], v[124:127], v[200:203], v[32:35]
	v_mfma_f32_16x16x32_bf16 v[32:35], v[168:171], v[192:195], v[48:51]
	v_mfma_f32_16x16x32_bf16 v[48:51], v[172:175], v[200:203], v[32:35]
	v_mfma_f32_16x16x32_bf16 v[32:35], v[120:123], v[204:207], v[52:55]
	v_mfma_f32_16x16x32_bf16 v[52:55], v[124:127], v[208:211], v[32:35]
	v_mfma_f32_16x16x32_bf16 v[32:35], v[168:171], v[204:207], v[56:59]
	v_mfma_f32_16x16x32_bf16 v[56:59], v[172:175], v[208:211], v[32:35]
	s_setprio 0
	s_barrier
	s_mov_b32 m0, s63
	v_lshl_add_u64 v[196:197], s[48:49], 0, v[128:129]
	s_add_u32 s44, s48, 0x10000
	s_nop 1
	ds_read_b128 v[32:35], v143 offset:16384
	ds_read_b128 v[36:39], v143 offset:17408
	ds_read_b128 v[96:99], v143 offset:18432
	ds_read_b128 v[184:187], v143 offset:19456
	ds_read_b128 v[188:191], v143 offset:20480
	ds_read_b128 v[192:195], v143 offset:21504
	ds_read_b128 v[200:203], v143 offset:22528
	ds_read_b128 v[204:207], v143 offset:23552
	global_load_lds_dwordx4 v[196:197], off
	v_lshl_add_u64 v[248:249], s[48:49], 0, v[130:131]
	s_mov_b32 m0, s53
	s_addc_u32 s45, s49, 0
	global_load_lds_dwordx4 v[248:249], off
	v_lshl_add_u64 v[208:209], s[44:45], 0, v[128:129]
	s_mov_b32 m0, s61
	v_lshl_add_u64 v[250:251], s[50:51], 0, v[128:129]
	global_load_lds_dwordx4 v[208:209], off
	v_lshl_add_u64 v[208:209], s[44:45], 0, v[130:131]
	s_mov_b32 m0, s62
	v_lshl_add_u64 v[134:135], s[50:51], 0, v[130:131]
	global_load_lds_dwordx4 v[208:209], off
	s_mov_b32 m0, s15
	s_nop 0
	global_load_lds_dwordx4 v[250:251], off
	s_mov_b32 m0, s38
	s_nop 0
	global_load_lds_dwordx4 v[134:135], off
	s_waitcnt vmcnt(8)
	s_waitcnt lgkmcnt(0)
	s_barrier
	s_setprio 1
	s_waitcnt lgkmcnt(0)
	v_mfma_f32_16x16x32_bf16 v[0:3], v[104:107], v[200:203], v[0:3]
	v_mfma_f32_16x16x32_bf16 v[144:147], v[104:107], v[32:35], v[144:147]
	v_mfma_f32_16x16x32_bf16 v[148:151], v[112:115], v[32:35], v[148:151]
	v_mfma_f32_16x16x32_bf16 v[152:155], v[104:107], v[96:99], v[152:155]
	v_mfma_f32_16x16x32_bf16 v[156:159], v[112:115], v[96:99], v[156:159]
	v_mfma_f32_16x16x32_bf16 v[160:163], v[104:107], v[188:191], v[160:163]
	v_mfma_f32_16x16x32_bf16 v[164:167], v[112:115], v[188:191], v[164:167]
	v_mfma_f32_16x16x32_bf16 v[0:3], v[108:111], v[204:207], v[0:3]
	v_mfma_f32_16x16x32_bf16 v[4:7], v[112:115], v[200:203], v[4:7]
	v_mfma_f32_16x16x32_bf16 v[144:147], v[108:111], v[36:39], v[144:147]
	v_mfma_f32_16x16x32_bf16 v[148:151], v[116:119], v[36:39], v[148:151]
	v_mfma_f32_16x16x32_bf16 v[152:155], v[108:111], v[184:187], v[152:155]
	v_mfma_f32_16x16x32_bf16 v[156:159], v[116:119], v[184:187], v[156:159]
	v_mfma_f32_16x16x32_bf16 v[160:163], v[108:111], v[192:195], v[160:163]
	v_mfma_f32_16x16x32_bf16 v[164:167], v[116:119], v[192:195], v[164:167]
	v_mfma_f32_16x16x32_bf16 v[208:211], v[116:119], v[204:207], v[4:7]
	v_mfma_f32_16x16x32_bf16 v[4:7], v[120:123], v[32:35], v[8:11]
	v_mfma_f32_16x16x32_bf16 v[8:11], v[124:127], v[36:39], v[4:7]
	v_mfma_f32_16x16x32_bf16 v[4:7], v[168:171], v[32:35], v[12:15]
	v_mfma_f32_16x16x32_bf16 v[12:15], v[172:175], v[36:39], v[4:7]
	v_mfma_f32_16x16x32_bf16 v[4:7], v[120:123], v[96:99], v[24:27]
	v_mfma_f32_16x16x32_bf16 v[24:27], v[124:127], v[184:187], v[4:7]
	v_mfma_f32_16x16x32_bf16 v[4:7], v[168:171], v[96:99], v[28:31]
	v_mfma_f32_16x16x32_bf16 v[28:31], v[172:175], v[184:187], v[4:7]
	v_mfma_f32_16x16x32_bf16 v[4:7], v[120:123], v[188:191], v[60:63]
	v_mfma_f32_16x16x32_bf16 v[184:187], v[124:127], v[192:195], v[4:7]
	v_mfma_f32_16x16x32_bf16 v[4:7], v[168:171], v[188:191], v[100:103]
	v_mfma_f32_16x16x32_bf16 v[188:191], v[172:175], v[192:195], v[4:7]
	v_mfma_f32_16x16x32_bf16 v[4:7], v[120:123], v[200:203], v[16:19]
	v_mfma_f32_16x16x32_bf16 v[192:195], v[124:127], v[204:207], v[4:7]
	v_mfma_f32_16x16x32_bf16 v[4:7], v[168:171], v[200:203], v[20:23]
	v_mfma_f32_16x16x32_bf16 v[168:171], v[172:175], v[204:207], v[4:7]
	s_setprio 0
	s_barrier
; #define PG8_STAGE(bufoff, gbase) PG8_STAGEV(bufoff, gbase, voff)
; #define PG8_STAGEB(bufoff, gbase) PG8_STAGEV(bufoff, gbase, voffB)
; #define PG8_LDA(dst, b, h) do { _Pragma("unroll") for (int m = 0; m < 4; ++m) _Pragma("unroll") for (int k = 0; k < 2; ++k) dst[m][k] = *(const LAS bf16x8*)(lds + PG8_SA(b, h) + aoff + m * 2048 + k * 1024); } while (0)
; #define PG8_LDB(dst, b, h) do { _Pragma("unroll") for (int n = 0; n < 2; ++n) _Pragma("unroll") for (int k = 0; k < 2; ++k) dst[n][k] = *(const LAS bf16x8*)(lds + PG8_SB(b, h) + boff + n * 2048 + k * 1024); } while (0)
; #define PG8_MMA(ai, bj, At, Bt) do { __builtin_amdgcn_s_setprio(1); _Pragma("unroll") for (int m = 0; m < 4; ++m) _Pragma("unroll") for (int n = 0; n < 2; ++n) _Pragma("unroll") for (int k = 0; k < 2; ++k) \
;         acc[ai][bj][m][n] = __builtin_amdgcn_mfma_f32_16x16x32_bf16(Bt[n][k], At[m][k], acc[ai][bj][m][n], 0, 0, 0); __builtin_amdgcn_s_setprio(0); } while (0)
; #define PG8_WAIT_V(n) asm volatile("s_waitcnt vmcnt(" #n ")" ::: "memory")
; #define PG8_WAIT_L(n) asm volatile("s_waitcnt lgkmcnt(" #n ")" ::: "memory")
; #define PG8_BAR __builtin_amdgcn_s_barrier()
; #define PG8_SCHED __builtin_amdgcn_sched_barrier(0)
; template <bool PERM, class Epi, class Sched>
; __device__ __forceinline__ void gemm_phase(LAS unsigned char* lds, const int K, const Sched& S, const Epi& E, const int wid0) {
;     ...
;             PG8_LDB(B0, 1, 0); PG8_LDB(B1, 1, 1); PG8_SCHED; PG8_LDA(At, 1, 0); PG8_STAGE(PG8_SA(0, 1), a2 + hstep);
;             PG8_WAIT_V(8); PG8_WAIT_L(0); PG8_BAR; PG8_MMA(0, 0, At, B0); PG8_MMA(0, 1, At, B1); PG8_BAR; PG8_SCHED;
;             PG8_LDA(At, 1, 1); PG8_STAGEB(PG8_SB(1, 0), b3); PG8_STAGEB(PG8_SB(1, 1), b3 + hstep); PG8_STAGE(PG8_SA(1, 0), a3);
;             PG8_WAIT_V(8); PG8_WAIT_L(0); PG8_BAR; PG8_MMA(1, 0, At, B0); PG8_MMA(1, 1, At, B1); PG8_BAR; PG8_SCHED;
;         }
;         if (wr == 0) PG8_BAR;
	s_nop 4
	ds_read_b128 v[4:7], v198
	ds_read_b128 v[60:63], v198 offset:1024
	ds_read_b128 v[172:175], v198 offset:2048
	ds_read_b128 v[200:203], v198 offset:3072
	ds_read_b128 v[204:207], v224
	ds_read_b128 v[216:219], v224 offset:1024
	ds_read_b128 v[220:223], v224 offset:2048
	ds_read_b128 v[224:227], v224 offset:3072
	s_add_u32 s44, s50, 0x10000
	s_addc_u32 s45, s51, 0
	s_mov_b32 m0, s39
	v_lshl_add_u64 v[32:33], s[44:45], 0, v[128:129]
	ds_read_b128 v[16:19], v143 offset:32768
	ds_read_b128 v[20:23], v143 offset:33792
	ds_read_b128 v[104:107], v143 offset:34816
	ds_read_b128 v[228:231], v143 offset:35840
	ds_read_b128 v[232:235], v143 offset:36864
	ds_read_b128 v[236:239], v143 offset:37888
	ds_read_b128 v[240:243], v143 offset:38912
	ds_read_b128 v[244:247], v143 offset:39936
	global_load_lds_dwordx4 v[32:33], off
	v_lshl_add_u64 v[32:33], s[44:45], 0, v[130:131]
	s_mov_b32 m0, s54
	s_nop 0
	global_load_lds_dwordx4 v[32:33], off
	s_waitcnt vmcnt(8)
	s_waitcnt lgkmcnt(0)
	s_barrier
	s_setprio 1
	s_waitcnt lgkmcnt(0)
	v_mfma_f32_16x16x32_bf16 v[32:35], v[4:7], v[16:19], v[64:67]
	v_mfma_f32_16x16x32_bf16 v[116:119], v[60:63], v[20:23], v[32:35]
	v_mfma_f32_16x16x32_bf16 v[32:35], v[172:175], v[16:19], v[68:71]
	v_mfma_f32_16x16x32_bf16 v[112:115], v[200:203], v[20:23], v[32:35]
	v_mfma_f32_16x16x32_bf16 v[32:35], v[4:7], v[104:107], v[72:75]
	v_mfma_f32_16x16x32_bf16 v[100:103], v[60:63], v[228:231], v[32:35]
	v_mfma_f32_16x16x32_bf16 v[32:35], v[172:175], v[104:107], v[76:79]
	v_mfma_f32_16x16x32_bf16 v[96:99], v[200:203], v[228:231], v[32:35]
	v_mfma_f32_16x16x32_bf16 v[32:35], v[4:7], v[232:235], v[80:83]
	v_mfma_f32_16x16x32_bf16 v[68:71], v[60:63], v[236:239], v[32:35]
	v_mfma_f32_16x16x32_bf16 v[32:35], v[172:175], v[232:235], v[84:87]
	v_mfma_f32_16x16x32_bf16 v[64:67], v[200:203], v[236:239], v[32:35]
	v_mfma_f32_16x16x32_bf16 v[32:35], v[4:7], v[240:243], v[88:91]
	v_mfma_f32_16x16x32_bf16 v[36:39], v[60:63], v[244:247], v[32:35]
	v_mfma_f32_16x16x32_bf16 v[32:35], v[172:175], v[240:243], v[92:95]
	v_mfma_f32_16x16x32_bf16 v[32:35], v[200:203], v[244:247], v[32:35]
	v_mfma_f32_16x16x32_bf16 v[72:75], v[204:207], v[16:19], v[212:215]
	v_mfma_f32_16x16x32_bf16 v[16:19], v[220:223], v[16:19], v[176:179]
	v_mfma_f32_16x16x32_bf16 v[120:123], v[224:227], v[20:23], v[16:19]
	v_mfma_f32_16x16x32_bf16 v[16:19], v[204:207], v[104:107], v[180:183]
	v_mfma_f32_16x16x32_bf16 v[108:111], v[216:219], v[228:231], v[16:19]
	v_mfma_f32_16x16x32_bf16 v[16:19], v[220:223], v[104:107], v[40:43]
	v_mfma_f32_16x16x32_bf16 v[104:107], v[224:227], v[228:231], v[16:19]
	v_mfma_f32_16x16x32_bf16 v[16:19], v[204:207], v[232:235], v[44:47]
	v_mfma_f32_16x16x32_bf16 v[80:83], v[216:219], v[236:239], v[16:19]
	v_mfma_f32_16x16x32_bf16 v[16:19], v[220:223], v[232:235], v[48:51]
	v_mfma_f32_16x16x32_bf16 v[76:79], v[224:227], v[236:239], v[16:19]
	v_mfma_f32_16x16x32_bf16 v[16:19], v[204:207], v[240:243], v[52:55]
	v_mfma_f32_16x16x32_bf16 v[48:51], v[216:219], v[244:247], v[16:19]
	v_mfma_f32_16x16x32_bf16 v[16:19], v[220:223], v[240:243], v[56:59]
	v_mfma_f32_16x16x32_bf16 v[124:127], v[216:219], v[20:23], v[72:75]
	v_mfma_f32_16x16x32_bf16 v[40:43], v[224:227], v[244:247], v[16:19]
	s_setprio 0
	s_barrier
	s_mov_b32 m0, s66
	s_nop 2
	v_lshl_add_u64 v[16:17], v[196:197], 0, s[8:9]
	s_add_u32 s44, s48, 0x10080
	ds_read_b128 v[56:59], v143 offset:49152
	ds_read_b128 v[88:91], v143 offset:50176
	ds_read_b128 v[176:179], v143 offset:51200
	ds_read_b128 v[180:183], v143 offset:52224
	ds_read_b128 v[212:215], v143 offset:53248
	ds_read_b128 v[228:231], v143 offset:54272
	ds_read_b128 v[232:235], v143 offset:55296
	ds_read_b128 v[236:239], v143 offset:56320
	global_load_lds_dwordx4 v[16:17], off
	v_lshl_add_u64 v[16:17], v[248:249], 0, s[8:9]
	s_mov_b32 m0, s64
	s_addc_u32 s45, s49, 0
	global_load_lds_dwordx4 v[16:17], off
	v_lshl_add_u64 v[16:17], s[44:45], 0, v[128:129]
	s_mov_b32 m0, s46
	s_nop 0
	global_load_lds_dwordx4 v[16:17], off
	v_lshl_add_u64 v[16:17], s[44:45], 0, v[130:131]
	s_mov_b32 m0, s47
	s_nop 0
	global_load_lds_dwordx4 v[16:17], off
	v_lshl_add_u64 v[16:17], v[250:251], 0, s[8:9]
	s_mov_b32 m0, s55
	s_nop 0
	global_load_lds_dwordx4 v[16:17], off
	v_lshl_add_u64 v[16:17], v[134:135], 0, s[8:9]
	s_mov_b32 m0, s56
	s_nop 0
	global_load_lds_dwordx4 v[16:17], off
	s_waitcnt vmcnt(8)
	s_waitcnt lgkmcnt(0)
	s_barrier
	s_setprio 1
	s_waitcnt lgkmcnt(0)
	v_mfma_f32_16x16x32_bf16 v[16:19], v[4:7], v[56:59], v[144:147]
	v_mfma_f32_16x16x32_bf16 v[84:87], v[60:63], v[88:91], v[16:19]
	v_mfma_f32_16x16x32_bf16 v[16:19], v[172:175], v[56:59], v[148:151]
	v_mfma_f32_16x16x32_bf16 v[72:75], v[200:203], v[88:91], v[16:19]
	v_mfma_f32_16x16x32_bf16 v[16:19], v[4:7], v[176:179], v[152:155]
	v_mfma_f32_16x16x32_bf16 v[52:55], v[60:63], v[180:183], v[16:19]
	v_mfma_f32_16x16x32_bf16 v[16:19], v[172:175], v[176:179], v[156:159]
	v_mfma_f32_16x16x32_bf16 v[44:47], v[200:203], v[180:183], v[16:19]
	v_mfma_f32_16x16x32_bf16 v[16:19], v[4:7], v[212:215], v[160:163]
	v_mfma_f32_16x16x32_bf16 v[0:3], v[4:7], v[232:235], v[0:3]
	v_mfma_f32_16x16x32_bf16 v[20:23], v[60:63], v[228:231], v[16:19]
	v_mfma_f32_16x16x32_bf16 v[16:19], v[172:175], v[212:215], v[164:167]
	v_mfma_f32_16x16x32_bf16 v[4:7], v[60:63], v[236:239], v[0:3]
	v_mfma_f32_16x16x32_bf16 v[0:3], v[172:175], v[232:235], v[208:211]
	v_mfma_f32_16x16x32_bf16 v[16:19], v[200:203], v[228:231], v[16:19]
	v_mfma_f32_16x16x32_bf16 v[0:3], v[200:203], v[236:239], v[0:3]
	v_mfma_f32_16x16x32_bf16 v[8:11], v[204:207], v[56:59], v[8:11]
	v_mfma_f32_16x16x32_bf16 v[92:95], v[216:219], v[88:91], v[8:11]
	v_mfma_f32_16x16x32_bf16 v[8:11], v[220:223], v[56:59], v[12:15]
	v_mfma_f32_16x16x32_bf16 v[88:91], v[224:227], v[88:91], v[8:11]
	v_mfma_f32_16x16x32_bf16 v[8:11], v[204:207], v[176:179], v[24:27]
	v_mfma_f32_16x16x32_bf16 v[60:63], v[216:219], v[180:183], v[8:11]
	v_mfma_f32_16x16x32_bf16 v[8:11], v[220:223], v[176:179], v[28:31]
	v_mfma_f32_16x16x32_bf16 v[56:59], v[224:227], v[180:183], v[8:11]
	v_mfma_f32_16x16x32_bf16 v[8:11], v[204:207], v[212:215], v[184:187]
	v_mfma_f32_16x16x32_bf16 v[28:31], v[216:219], v[228:231], v[8:11]
	v_mfma_f32_16x16x32_bf16 v[8:11], v[220:223], v[212:215], v[188:191]
	v_mfma_f32_16x16x32_bf16 v[24:27], v[224:227], v[228:231], v[8:11]
	v_mfma_f32_16x16x32_bf16 v[8:11], v[204:207], v[232:235], v[192:195]
	v_mfma_f32_16x16x32_bf16 v[12:15], v[216:219], v[236:239], v[8:11]
	v_mfma_f32_16x16x32_bf16 v[8:11], v[220:223], v[232:235], v[168:171]
	v_mfma_f32_16x16x32_bf16 v[8:11], v[224:227], v[236:239], v[8:11]
	s_setprio 0
	s_barrier
	s_andn2_b64 vcc, exec, s[10:11]
	s_cbranch_vccnz .LBB0_106
	s_barrier

; #define PG8_STAGE(bufoff, gbase) PG8_STAGEV(bufoff, gbase, voff)
; #define PG8_STAGEB(bufoff, gbase) PG8_STAGEV(bufoff, gbase, voffB)
; #define PG8_LDA(dst, b, h) do { _Pragma("unroll") for (int m = 0; m < 4; ++m) _Pragma("unroll") for (int k = 0; k < 2; ++k) dst[m][k] = *(const LAS bf16x8*)(lds + PG8_SA(b, h) + aoff + m * 2048 + k * 1024); } while (0)
; #define PG8_LDB(dst, b, h) do { _Pragma("unroll") for (int n = 0; n < 2; ++n) _Pragma("unroll") for (int k = 0; k < 2; ++k) dst[n][k] = *(const LAS bf16x8*)(lds + PG8_SB(b, h) + boff + n * 2048 + k * 1024); } while (0)
; #define PG8_MMA(ai, bj, At, Bt) do { __builtin_amdgcn_s_setprio(1); _Pragma("unroll") for (int m = 0; m < 4; ++m) _Pragma("unroll") for (int n = 0; n < 2; ++n) _Pragma("unroll") for (int k = 0; k < 2; ++k) \
;         acc[ai][bj][m][n] = __builtin_amdgcn_mfma_f32_16x16x32_bf16(Bt[n][k], At[m][k], acc[ai][bj][m][n], 0, 0, 0); __builtin_amdgcn_s_setprio(0); } while (0)
; #define PG8_WAIT_V(n) asm volatile("s_waitcnt vmcnt(" #n ")" ::: "memory")
; #define PG8_WAIT_L(n) asm volatile("s_waitcnt lgkmcnt(" #n ")" ::: "memory")
; #define PG8_BAR __builtin_amdgcn_s_barrier()
; #define PG8_SCHED __builtin_amdgcn_sched_barrier(0)
; template <bool PERM, class Epi, class Sched>
; __device__ __forceinline__ void gemm_phase(LAS unsigned char* lds, const int K, const Sched& S, const Epi& E, const int wid0) {
;     ...
;             const bool last = (t == nt - 2);
;             const char* a1 = cA + (size_t)(t + 1) * kstep;
;             const char* a2 = last ? nA : cA + (size_t)(t + 2) * kstep; const char* b2 = last ? nB : cB + (size_t)(t + 2) * kstep;
;             const char* a3 = a2 + kstep; const char* b3 = b2 + kstep;
;             PG8_LDB(B0, 0, 0); PG8_LDB(B1, 0, 1); PG8_SCHED; PG8_LDA(At, 0, 0); PG8_STAGE(PG8_SA(1, 1), a1 + hstep);
;             PG8_WAIT_V(8); PG8_WAIT_L(0); PG8_BAR; PG8_MMA(0, 0, At, B0); PG8_MMA(0, 1, At, B1); PG8_BAR; PG8_SCHED;
;             PG8_LDA(At, 0, 1); PG8_STAGEB(PG8_SB(0, 0), b2); PG8_STAGEB(PG8_SB(0, 1), b2 + hstep); PG8_STAGE(PG8_SA(0, 0), a2);
.LBB0_247:
	s_add_u32 s16, s8, 0xfff80080
	s_addc_u32 s17, s9, -1
	s_add_i32 s58, 0, 0x10000
	s_cmp_eq_u32 vcc_lo, 28
	s_cselect_b32 s81, s79, s17
	s_cselect_b32 s80, s78, s16
	v_add_u32_e32 v136, s58, v168
	s_cselect_b32 s69, s18, s77
	s_cselect_b32 s68, s46, s48
	s_add_i32 s59, 0, 0x14000
	ds_read_b128 v[128:131], v136
	ds_read_b128 v[132:135], v136 offset:1024
	ds_read_b128 v[154:157], v136 offset:2048
	ds_read_b128 v[158:161], v136 offset:3072
	v_add_u32_e32 v136, s59, v168
	ds_read_b128 v[162:165], v136
	ds_read_b128 v[174:177], v136 offset:1024
	ds_read_b128 v[178:181], v136 offset:2048
	ds_read_b128 v[186:189], v136 offset:3072
	v_lshl_add_u64 v[136:137], s[8:9], 0, v[150:151]
	s_add_i32 m0, s56, 0xc000
	ds_read_b128 v[190:193], v173
	ds_read_b128 v[194:197], v173 offset:1024
	ds_read_b128 v[222:225], v173 offset:2048
	ds_read_b128 v[226:229], v173 offset:3072
	ds_read_b128 v[230:233], v173 offset:4096
	ds_read_b128 v[234:237], v173 offset:5120
	ds_read_b128 v[238:241], v173 offset:6144
	ds_read_b128 v[242:245], v173 offset:7168
	global_load_lds_dwordx4 v[136:137], off
	v_lshl_add_u64 v[136:137], s[8:9], 0, v[152:153]
	s_add_i32 m0, s56, 0xe000
	s_nop 0
	global_load_lds_dwordx4 v[136:137], off
	s_waitcnt vmcnt(8)
	s_waitcnt lgkmcnt(0)
	s_barrier
	s_setprio 1
	s_waitcnt lgkmcnt(0)
	v_mfma_f32_16x16x32_bf16 v[124:127], v[128:131], v[190:193], v[124:127]
	v_mfma_f32_16x16x32_bf16 v[120:123], v[154:157], v[190:193], v[120:123]
	v_mfma_f32_16x16x32_bf16 v[108:111], v[128:131], v[222:225], v[108:111]
	v_mfma_f32_16x16x32_bf16 v[104:107], v[154:157], v[222:225], v[104:107]
	v_mfma_f32_16x16x32_bf16 v[92:95], v[128:131], v[230:233], v[92:95]
	v_mfma_f32_16x16x32_bf16 v[88:91], v[154:157], v[230:233], v[88:91]
	v_mfma_f32_16x16x32_bf16 v[76:79], v[128:131], v[238:241], v[76:79]
	v_mfma_f32_16x16x32_bf16 v[72:75], v[154:157], v[238:241], v[72:75]
	v_mfma_f32_16x16x32_bf16 v[124:127], v[132:135], v[194:197], v[124:127]
	v_mfma_f32_16x16x32_bf16 v[120:123], v[158:161], v[194:197], v[120:123]
	v_mfma_f32_16x16x32_bf16 v[108:111], v[132:135], v[226:229], v[108:111]
	v_mfma_f32_16x16x32_bf16 v[104:107], v[158:161], v[226:229], v[104:107]
	v_mfma_f32_16x16x32_bf16 v[92:95], v[132:135], v[234:237], v[92:95]
	v_mfma_f32_16x16x32_bf16 v[88:91], v[158:161], v[234:237], v[88:91]
	v_mfma_f32_16x16x32_bf16 v[76:79], v[132:135], v[242:245], v[76:79]
	v_mfma_f32_16x16x32_bf16 v[72:75], v[158:161], v[242:245], v[72:75]
	v_mfma_f32_16x16x32_bf16 v[116:119], v[162:165], v[190:193], v[116:119]
	v_mfma_f32_16x16x32_bf16 v[112:115], v[178:181], v[190:193], v[112:115]
	v_mfma_f32_16x16x32_bf16 v[100:103], v[162:165], v[222:225], v[100:103]
	v_mfma_f32_16x16x32_bf16 v[96:99], v[178:181], v[222:225], v[96:99]
	v_mfma_f32_16x16x32_bf16 v[84:87], v[162:165], v[230:233], v[84:87]
	v_mfma_f32_16x16x32_bf16 v[80:83], v[178:181], v[230:233], v[80:83]
	v_mfma_f32_16x16x32_bf16 v[68:71], v[162:165], v[238:241], v[68:71]
	v_mfma_f32_16x16x32_bf16 v[64:67], v[178:181], v[238:241], v[64:67]
	v_mfma_f32_16x16x32_bf16 v[116:119], v[174:177], v[194:197], v[116:119]
	v_mfma_f32_16x16x32_bf16 v[112:115], v[186:189], v[194:197], v[112:115]
	v_mfma_f32_16x16x32_bf16 v[100:103], v[174:177], v[226:229], v[100:103]
	v_mfma_f32_16x16x32_bf16 v[96:99], v[186:189], v[226:229], v[96:99]
	v_mfma_f32_16x16x32_bf16 v[84:87], v[174:177], v[234:237], v[84:87]
	v_mfma_f32_16x16x32_bf16 v[80:83], v[186:189], v[234:237], v[80:83]
	v_mfma_f32_16x16x32_bf16 v[68:71], v[174:177], v[242:245], v[68:71]
	v_mfma_f32_16x16x32_bf16 v[64:67], v[186:189], v[242:245], v[64:67]
	s_setprio 0
	s_barrier
	s_add_i32 s16, s58, s83
	v_lshl_add_u64 v[136:137], s[68:69], 0, v[140:141]
	s_mov_b32 m0, s16
	ds_read_b128 v[190:193], v173 offset:16384
	ds_read_b128 v[194:197], v173 offset:17408
	ds_read_b128 v[222:225], v173 offset:18432
	ds_read_b128 v[226:229], v173 offset:19456
	ds_read_b128 v[230:233], v173 offset:20480
	ds_read_b128 v[234:237], v173 offset:21504
	ds_read_b128 v[238:241], v173 offset:22528
	ds_read_b128 v[242:245], v173 offset:23552
	global_load_lds_dwordx4 v[136:137], off
	s_add_i32 m0, s16, 0x2000
	s_add_u32 s16, s68, 0x80000
	v_lshl_add_u64 v[166:167], s[68:69], 0, v[144:145]
	s_addc_u32 s17, s69, 0
	s_add_i32 s58, s59, s83
	global_load_lds_dwordx4 v[166:167], off
	v_lshl_add_u64 v[182:183], s[16:17], 0, v[140:141]
	s_mov_b32 m0, s58
	v_lshl_add_u64 v[246:247], s[80:81], 0, v[142:143]
	global_load_lds_dwordx4 v[182:183], off
	v_lshl_add_u64 v[182:183], s[16:17], 0, v[144:145]
	s_add_i32 m0, s58, 0x2000
	s_nop 0
	global_load_lds_dwordx4 v[182:183], off
	v_lshl_add_u64 v[182:183], s[80:81], 0, v[138:139]
	s_mov_b32 m0, s56
	s_nop 0
	global_load_lds_dwordx4 v[182:183], off
	s_mov_b32 m0, s54
	s_nop 0
	global_load_lds_dwordx4 v[246:247], off
	s_waitcnt vmcnt(8)
	s_waitcnt lgkmcnt(0)
	s_barrier
; #define PG8_STAGE(bufoff, gbase) PG8_STAGEV(bufoff, gbase, voff)
; #define PG8_STAGEB(bufoff, gbase) PG8_STAGEV(bufoff, gbase, voffB)
; #define PG8_LDA(dst, b, h) do { _Pragma("unroll") for (int m = 0; m < 4; ++m) _Pragma("unroll") for (int k = 0; k < 2; ++k) dst[m][k] = *(const LAS bf16x8*)(lds + PG8_SA(b, h) + aoff + m * 2048 + k * 1024); } while (0)
; #define PG8_LDB(dst, b, h) do { _Pragma("unroll") for (int n = 0; n < 2; ++n) _Pragma("unroll") for (int k = 0; k < 2; ++k) dst[n][k] = *(const LAS bf16x8*)(lds + PG8_SB(b, h) + boff + n * 2048 + k * 1024); } while (0)
; #define PG8_MMA(ai, bj, At, Bt) do { __builtin_amdgcn_s_setprio(1); _Pragma("unroll") for (int m = 0; m < 4; ++m) _Pragma("unroll") for (int n = 0; n < 2; ++n) _Pragma("unroll") for (int k = 0; k < 2; ++k) \
;         acc[ai][bj][m][n] = __builtin_amdgcn_mfma_f32_16x16x32_bf16(Bt[n][k], At[m][k], acc[ai][bj][m][n], 0, 0, 0); __builtin_amdgcn_s_setprio(0); } while (0)
; #define PG8_WAIT_V(n) asm volatile("s_waitcnt vmcnt(" #n ")" ::: "memory")
; #define PG8_WAIT_L(n) asm volatile("s_waitcnt lgkmcnt(" #n ")" ::: "memory")
; #define PG8_BAR __builtin_amdgcn_s_barrier()
; #define PG8_SCHED __builtin_amdgcn_sched_barrier(0)
; template <bool PERM, class Epi, class Sched>
; __device__ __forceinline__ void gemm_phase(LAS unsigned char* lds, const int K, const Sched& S, const Epi& E, const int wid0) {
;     ...
;             PG8_LDA(At, 0, 1); PG8_STAGEB(PG8_SB(0, 0), b2); PG8_STAGEB(PG8_SB(0, 1), b2 + hstep); PG8_STAGE(PG8_SA(0, 0), a2);
;             PG8_WAIT_V(8); PG8_WAIT_L(0); PG8_BAR; PG8_MMA(1, 0, At, B0); PG8_MMA(1, 1, At, B1); PG8_BAR; PG8_SCHED;
;             PG8_LDB(B0, 1, 0); PG8_LDB(B1, 1, 1); PG8_SCHED; PG8_LDA(At, 1, 0); PG8_STAGE(PG8_SA(0, 1), a2 + hstep);
;             PG8_WAIT_V(8); PG8_WAIT_L(0); PG8_BAR; PG8_MMA(0, 0, At, B0); PG8_MMA(0, 1, At, B1); PG8_BAR; PG8_SCHED;
	s_setprio 1
	s_waitcnt lgkmcnt(0)
	v_mfma_f32_16x16x32_bf16 v[60:63], v[128:131], v[190:193], v[60:63]
	v_mfma_f32_16x16x32_bf16 v[56:59], v[154:157], v[190:193], v[56:59]
	v_mfma_f32_16x16x32_bf16 v[44:47], v[128:131], v[222:225], v[44:47]
	v_mfma_f32_16x16x32_bf16 v[40:43], v[154:157], v[222:225], v[40:43]
	v_mfma_f32_16x16x32_bf16 v[28:31], v[128:131], v[230:233], v[28:31]
	v_mfma_f32_16x16x32_bf16 v[24:27], v[154:157], v[230:233], v[24:27]
	v_mfma_f32_16x16x32_bf16 v[12:15], v[128:131], v[238:241], v[12:15]
	v_mfma_f32_16x16x32_bf16 v[8:11], v[154:157], v[238:241], v[8:11]
	v_mfma_f32_16x16x32_bf16 v[60:63], v[132:135], v[194:197], v[60:63]
	v_mfma_f32_16x16x32_bf16 v[56:59], v[158:161], v[194:197], v[56:59]
	v_mfma_f32_16x16x32_bf16 v[44:47], v[132:135], v[226:229], v[44:47]
	v_mfma_f32_16x16x32_bf16 v[40:43], v[158:161], v[226:229], v[40:43]
	v_mfma_f32_16x16x32_bf16 v[28:31], v[132:135], v[234:237], v[28:31]
	v_mfma_f32_16x16x32_bf16 v[24:27], v[158:161], v[234:237], v[24:27]
	v_mfma_f32_16x16x32_bf16 v[12:15], v[132:135], v[242:245], v[12:15]
	v_mfma_f32_16x16x32_bf16 v[8:11], v[158:161], v[242:245], v[8:11]
	v_mfma_f32_16x16x32_bf16 v[52:55], v[162:165], v[190:193], v[52:55]
	v_mfma_f32_16x16x32_bf16 v[48:51], v[178:181], v[190:193], v[48:51]
	v_mfma_f32_16x16x32_bf16 v[36:39], v[162:165], v[222:225], v[36:39]
	v_mfma_f32_16x16x32_bf16 v[32:35], v[178:181], v[222:225], v[32:35]
	v_mfma_f32_16x16x32_bf16 v[20:23], v[162:165], v[230:233], v[20:23]
	v_mfma_f32_16x16x32_bf16 v[16:19], v[178:181], v[230:233], v[16:19]
	v_mfma_f32_16x16x32_bf16 v[4:7], v[162:165], v[238:241], v[4:7]
	v_mfma_f32_16x16x32_bf16 v[0:3], v[178:181], v[238:241], v[0:3]
	v_mfma_f32_16x16x32_bf16 v[52:55], v[174:177], v[194:197], v[52:55]
	v_mfma_f32_16x16x32_bf16 v[48:51], v[186:189], v[194:197], v[48:51]
	v_mfma_f32_16x16x32_bf16 v[36:39], v[174:177], v[226:229], v[36:39]
	v_mfma_f32_16x16x32_bf16 v[32:35], v[186:189], v[226:229], v[32:35]
	v_mfma_f32_16x16x32_bf16 v[20:23], v[174:177], v[234:237], v[20:23]
	v_mfma_f32_16x16x32_bf16 v[16:19], v[186:189], v[234:237], v[16:19]
	v_mfma_f32_16x16x32_bf16 v[4:7], v[174:177], v[242:245], v[4:7]
	v_mfma_f32_16x16x32_bf16 v[0:3], v[186:189], v[242:245], v[0:3]
	s_setprio 0
	s_barrier
	s_add_i32 s58, 0, 0x18000
	s_add_i32 s59, 0, 0x1c000
	v_add_u32_e32 v158, s58, v168
	v_add_u32_e32 v184, s59, v168
	ds_read_b128 v[128:131], v158
	ds_read_b128 v[132:135], v158 offset:1024
	ds_read_b128 v[154:157], v158 offset:2048
	ds_read_b128 v[158:161], v158 offset:3072
	ds_read_b128 v[162:165], v184
	ds_read_b128 v[174:177], v184 offset:1024
	ds_read_b128 v[178:181], v184 offset:2048
	ds_read_b128 v[186:189], v184 offset:3072
	s_add_u32 s16, s80, 0x80000
	s_addc_u32 s17, s81, 0
	s_mov_b32 m0, s55
	v_lshl_add_u64 v[248:249], s[16:17], 0, v[138:139]
	ds_read_b128 v[190:193], v173 offset:32768
	ds_read_b128 v[194:197], v173 offset:33792
	ds_read_b128 v[222:225], v173 offset:34816
	ds_read_b128 v[226:229], v173 offset:35840
	ds_read_b128 v[230:233], v173 offset:36864
	ds_read_b128 v[234:237], v173 offset:37888
	ds_read_b128 v[238:241], v173 offset:38912
	ds_read_b128 v[242:245], v173 offset:39936
	global_load_lds_dwordx4 v[248:249], off
	v_lshl_add_u64 v[248:249], s[16:17], 0, v[142:143]
	s_mov_b32 m0, s66
	s_nop 0
	global_load_lds_dwordx4 v[248:249], off
	s_waitcnt vmcnt(8)
	s_waitcnt lgkmcnt(0)
	s_barrier
	s_setprio 1
	s_waitcnt lgkmcnt(0)
	v_mfma_f32_16x16x32_bf16 v[124:127], v[128:131], v[190:193], v[124:127]
	v_mfma_f32_16x16x32_bf16 v[120:123], v[154:157], v[190:193], v[120:123]
	v_mfma_f32_16x16x32_bf16 v[108:111], v[128:131], v[222:225], v[108:111]
	v_mfma_f32_16x16x32_bf16 v[104:107], v[154:157], v[222:225], v[104:107]
	v_mfma_f32_16x16x32_bf16 v[92:95], v[128:131], v[230:233], v[92:95]
	v_mfma_f32_16x16x32_bf16 v[88:91], v[154:157], v[230:233], v[88:91]
	v_mfma_f32_16x16x32_bf16 v[76:79], v[128:131], v[238:241], v[76:79]
	v_mfma_f32_16x16x32_bf16 v[72:75], v[154:157], v[238:241], v[72:75]
	v_mfma_f32_16x16x32_bf16 v[124:127], v[132:135], v[194:197], v[124:127]
	v_mfma_f32_16x16x32_bf16 v[120:123], v[158:161], v[194:197], v[120:123]
	v_mfma_f32_16x16x32_bf16 v[108:111], v[132:135], v[226:229], v[108:111]
	v_mfma_f32_16x16x32_bf16 v[104:107], v[158:161], v[226:229], v[104:107]
	v_mfma_f32_16x16x32_bf16 v[92:95], v[132:135], v[234:237], v[92:95]
	v_mfma_f32_16x16x32_bf16 v[88:91], v[158:161], v[234:237], v[88:91]
	v_mfma_f32_16x16x32_bf16 v[76:79], v[132:135], v[242:245], v[76:79]
	v_mfma_f32_16x16x32_bf16 v[72:75], v[158:161], v[242:245], v[72:75]
	v_mfma_f32_16x16x32_bf16 v[116:119], v[162:165], v[190:193], v[116:119]
	v_mfma_f32_16x16x32_bf16 v[112:115], v[178:181], v[190:193], v[112:115]
	v_mfma_f32_16x16x32_bf16 v[100:103], v[162:165], v[222:225], v[100:103]
	v_mfma_f32_16x16x32_bf16 v[96:99], v[178:181], v[222:225], v[96:99]
	v_mfma_f32_16x16x32_bf16 v[84:87], v[162:165], v[230:233], v[84:87]
	v_mfma_f32_16x16x32_bf16 v[80:83], v[178:181], v[230:233], v[80:83]
	v_mfma_f32_16x16x32_bf16 v[68:71], v[162:165], v[238:241], v[68:71]
	v_mfma_f32_16x16x32_bf16 v[64:67], v[178:181], v[238:241], v[64:67]
	v_mfma_f32_16x16x32_bf16 v[116:119], v[174:177], v[194:197], v[116:119]
	v_mfma_f32_16x16x32_bf16 v[112:115], v[186:189], v[194:197], v[112:115]
	v_mfma_f32_16x16x32_bf16 v[100:103], v[174:177], v[226:229], v[100:103]
	v_mfma_f32_16x16x32_bf16 v[96:99], v[186:189], v[226:229], v[96:99]
	v_mfma_f32_16x16x32_bf16 v[84:87], v[174:177], v[234:237], v[84:87]
	v_mfma_f32_16x16x32_bf16 v[80:83], v[186:189], v[234:237], v[80:83]
	v_mfma_f32_16x16x32_bf16 v[68:71], v[174:177], v[242:245], v[68:71]
	v_mfma_f32_16x16x32_bf16 v[64:67], v[186:189], v[242:245], v[64:67]
	s_setprio 0
	s_barrier
; #define PG8_STAGE(bufoff, gbase) PG8_STAGEV(bufoff, gbase, voff)
; #define PG8_STAGEB(bufoff, gbase) PG8_STAGEV(bufoff, gbase, voffB)
; #define PG8_LDA(dst, b, h) do { _Pragma("unroll") for (int m = 0; m < 4; ++m) _Pragma("unroll") for (int k = 0; k < 2; ++k) dst[m][k] = *(const LAS bf16x8*)(lds + PG8_SA(b, h) + aoff + m * 2048 + k * 1024); } while (0)
; #define PG8_MMA(ai, bj, At, Bt) do { __builtin_amdgcn_s_setprio(1); _Pragma("unroll") for (int m = 0; m < 4; ++m) _Pragma("unroll") for (int n = 0; n < 2; ++n) _Pragma("unroll") for (int k = 0; k < 2; ++k) \
;         acc[ai][bj][m][n] = __builtin_amdgcn_mfma_f32_16x16x32_bf16(Bt[n][k], At[m][k], acc[ai][bj][m][n], 0, 0, 0); __builtin_amdgcn_s_setprio(0); } while (0)
; #define PG8_WAIT_V(n) asm volatile("s_waitcnt vmcnt(" #n ")" ::: "memory")
; #define PG8_WAIT_L(n) asm volatile("s_waitcnt lgkmcnt(" #n ")" ::: "memory")
; #define PG8_BAR __builtin_amdgcn_s_barrier()
; #define PG8_SCHED __builtin_amdgcn_sched_barrier(0)
; template <bool PERM, class Epi, class Sched>
; __device__ __forceinline__ void gemm_phase(LAS unsigned char* lds, const int K, const Sched& S, const Epi& E, const int wid0) {
;     ...
;             PG8_WAIT_V(8); PG8_WAIT_L(0); PG8_BAR; PG8_MMA(0, 0, At, B0); PG8_MMA(0, 1, At, B1); PG8_BAR; PG8_SCHED;
;             PG8_LDA(At, 1, 1); PG8_STAGEB(PG8_SB(1, 0), b3); PG8_STAGEB(PG8_SB(1, 1), b3 + hstep); PG8_STAGE(PG8_SA(1, 0), a3);
;             PG8_WAIT_V(8); PG8_WAIT_L(0); PG8_BAR; PG8_MMA(1, 0, At, B0); PG8_MMA(1, 1, At, B1); PG8_BAR; PG8_SCHED;
;         }
	s_add_i32 s16, s58, s83
	v_lshl_add_u64 v[136:137], v[136:137], 0, s[42:43]
	s_mov_b32 m0, s16
	ds_read_b128 v[190:193], v173 offset:49152
	ds_read_b128 v[194:197], v173 offset:50176
	ds_read_b128 v[222:225], v173 offset:51200
	ds_read_b128 v[226:229], v173 offset:52224
	ds_read_b128 v[230:233], v173 offset:53248
	ds_read_b128 v[234:237], v173 offset:54272
	ds_read_b128 v[238:241], v173 offset:55296
	ds_read_b128 v[242:245], v173 offset:56320
	global_load_lds_dwordx4 v[136:137], off
	s_add_i32 m0, s16, 0x2000
	s_add_u32 s16, s68, 0x80080
	v_lshl_add_u64 v[136:137], v[166:167], 0, s[42:43]
	s_addc_u32 s17, s69, 0
	s_add_i32 s58, s59, s83
	global_load_lds_dwordx4 v[136:137], off
	v_lshl_add_u64 v[136:137], s[16:17], 0, v[140:141]
	s_mov_b32 m0, s58
	s_nop 0
	global_load_lds_dwordx4 v[136:137], off
	v_lshl_add_u64 v[136:137], s[16:17], 0, v[144:145]
	s_add_i32 m0, s58, 0x2000
	s_nop 0
	global_load_lds_dwordx4 v[136:137], off
	v_lshl_add_u64 v[136:137], v[182:183], 0, s[42:43]
	s_mov_b32 m0, s53
	s_nop 0
	global_load_lds_dwordx4 v[136:137], off
	v_lshl_add_u64 v[136:137], v[246:247], 0, s[42:43]
	s_mov_b32 m0, s92
	s_nop 0
	global_load_lds_dwordx4 v[136:137], off
	s_waitcnt vmcnt(8)
	s_waitcnt lgkmcnt(0)
	s_barrier
	s_setprio 1
	s_waitcnt lgkmcnt(0)
	v_mfma_f32_16x16x32_bf16 v[60:63], v[128:131], v[190:193], v[60:63]
	v_mfma_f32_16x16x32_bf16 v[56:59], v[154:157], v[190:193], v[56:59]
	v_mfma_f32_16x16x32_bf16 v[44:47], v[128:131], v[222:225], v[44:47]
	v_mfma_f32_16x16x32_bf16 v[40:43], v[154:157], v[222:225], v[40:43]
	v_mfma_f32_16x16x32_bf16 v[28:31], v[128:131], v[230:233], v[28:31]
	v_mfma_f32_16x16x32_bf16 v[24:27], v[154:157], v[230:233], v[24:27]
	v_mfma_f32_16x16x32_bf16 v[12:15], v[128:131], v[238:241], v[12:15]
	v_mfma_f32_16x16x32_bf16 v[8:11], v[154:157], v[238:241], v[8:11]
	v_mfma_f32_16x16x32_bf16 v[60:63], v[132:135], v[194:197], v[60:63]
	v_mfma_f32_16x16x32_bf16 v[56:59], v[158:161], v[194:197], v[56:59]
	v_mfma_f32_16x16x32_bf16 v[44:47], v[132:135], v[226:229], v[44:47]
	v_mfma_f32_16x16x32_bf16 v[40:43], v[158:161], v[226:229], v[40:43]
	v_mfma_f32_16x16x32_bf16 v[28:31], v[132:135], v[234:237], v[28:31]
	v_mfma_f32_16x16x32_bf16 v[24:27], v[158:161], v[234:237], v[24:27]
	v_mfma_f32_16x16x32_bf16 v[12:15], v[132:135], v[242:245], v[12:15]
	v_mfma_f32_16x16x32_bf16 v[8:11], v[158:161], v[242:245], v[8:11]
	v_mfma_f32_16x16x32_bf16 v[52:55], v[162:165], v[190:193], v[52:55]
	v_mfma_f32_16x16x32_bf16 v[48:51], v[178:181], v[190:193], v[48:51]
	v_mfma_f32_16x16x32_bf16 v[36:39], v[162:165], v[222:225], v[36:39]
	v_mfma_f32_16x16x32_bf16 v[32:35], v[178:181], v[222:225], v[32:35]
	v_mfma_f32_16x16x32_bf16 v[20:23], v[162:165], v[230:233], v[20:23]
	v_mfma_f32_16x16x32_bf16 v[16:19], v[178:181], v[230:233], v[16:19]
	v_mfma_f32_16x16x32_bf16 v[4:7], v[162:165], v[238:241], v[4:7]
	v_mfma_f32_16x16x32_bf16 v[0:3], v[178:181], v[238:241], v[0:3]
	v_mfma_f32_16x16x32_bf16 v[52:55], v[174:177], v[194:197], v[52:55]
	v_mfma_f32_16x16x32_bf16 v[48:51], v[186:189], v[194:197], v[48:51]
	v_mfma_f32_16x16x32_bf16 v[36:39], v[174:177], v[226:229], v[36:39]
	v_mfma_f32_16x16x32_bf16 v[32:35], v[186:189], v[226:229], v[32:35]
	v_mfma_f32_16x16x32_bf16 v[20:23], v[174:177], v[234:237], v[20:23]
	v_mfma_f32_16x16x32_bf16 v[16:19], v[186:189], v[234:237], v[16:19]
	v_mfma_f32_16x16x32_bf16 v[4:7], v[174:177], v[242:245], v[4:7]
	v_mfma_f32_16x16x32_bf16 v[0:3], v[186:189], v[242:245], v[0:3]
	s_setprio 0
	s_barrier
	s_add_i32 vcc_lo, vcc_lo, 2
	s_add_u32 s8, s8, 0x100
	s_addc_u32 s9, s9, 0
	s_add_u32 s48, s48, 0x100
	s_addc_u32 s77, s77, 0
	s_cmp_gt_u32 vcc_lo, 29
	s_cbranch_scc0 .LBB0_247
	s_and_b64 vcc, exec, s[74:75]
	s_cbranch_vccnz .LBB0_252
	s_cmp_gt_i32 s0, 7
	s_mov_b64 s[8:9], -1
	s_cbranch_scc1 .LBB0_253

; #define LAS __attribute__((address_space(3)))
; #define MFMA32(a, b, c) __builtin_amdgcn_mfma_f32_32x32x16_bf16((a), (b), (c), 0, 0, 0)
; DI void attn_unit(LAS unsigned char* lds, const bf16_t* QK, const bf16_t* VT, bf16_t* O, int mp, int h, int q0, int kt0, int kt1, int coff, int wid0) {
;     ...
; #pragma unroll
;             for (int j = 0; j < 8; ++j) pf[a][b][j] = 0;
;     __syncthreads();
;     f32x16 sa0, sa1, sb0, sb1;
; #pragma unroll
;     for (int r = 0; r < 16; ++r) { sa0[r] = 0.f; sa1[r] = 0.f; }
; #pragma unroll
;     for (int ks = 0; ks < 4; ++ks) {
;         const bf16x8 k0 = *(const LAS bf16x8*)(lds + koff + ks * 32), k1 = *(const LAS bf16x8*)(lds + koff + 32 * KP * 2 + ks * 32);
;         sa0 = MFMA32(k0, qf[ks], sa0); sa1 = MFMA32(k1, qf[ks], sa1);
;     }
;     for (int t = 0; t < nkt; t += 2) {
.LBB0_456:
	s_or_b64 exec, exec, s[8:9]
	s_movk_i32 s5, 0x48
	v_mad_u32_u24 v4, v4, s5, v7
	v_lshl_add_u32 v196, v4, 1, 0
	s_waitcnt lgkmcnt(0)
	s_barrier
	ds_read_b128 v[8:11], v196
	ds_read_b128 v[12:15], v196 offset:32
	s_waitcnt lgkmcnt(1)
	v_mfma_f32_32x32x16_bf16 v[96:111], v[8:11], v[128:131], 0
	ds_read_b128 v[8:11], v196 offset:4608
	v_readlane_b32 s8, v253, 56
	v_readlane_b32 s9, v253, 57
	v_add_u32_e32 v2, s4, v2
	s_mov_b32 s5, 0x8400
	v_mov_b64_e32 v[4:5], s[8:9]
	v_mad_i64_i32 v[4:5], s[8:9], v2, s5, v[4:5]
	v_and_b32_e32 v2, 48, v3
	v_add_u32_e32 v1, v1, v2
	v_and_or_b32 v1, v6, 4, v1
	ds_read_b128 v[16:19], v196 offset:4640
	v_lshlrev_b32_e32 v28, 1, v1
	v_mov_b32_e32 v1, v185
	v_lshl_add_u64 v[190:191], v[4:5], 0, v[0:1]
	ds_read_b128 v[0:3], v196 offset:64
	s_waitcnt lgkmcnt(2)
	v_mfma_f32_32x32x16_bf16 v[64:79], v[8:11], v[128:131], 0
	s_mov_b32 s68, 0
	s_mov_b32 s69, s68
	s_mov_b32 s70, s68
	s_mov_b32 s71, s68
	s_mov_b32 s72, s68
	s_mov_b32 s73, s68
	s_mov_b32 s74, s68
	v_mfma_f32_32x32x16_bf16 v[96:111], v[12:15], v[132:135], v[96:111]
	s_mov_b32 s75, s68
	s_mov_b32 s76, s68
	s_mov_b32 s77, s68
	s_mov_b32 s78, s68
	s_mov_b32 s79, s68
	s_mov_b32 s80, s68
	s_mov_b32 s81, s68
	s_waitcnt lgkmcnt(1)
	v_mfma_f32_32x32x16_bf16 v[64:79], v[16:19], v[132:135], v[64:79]
	ds_read_b128 v[16:19], v196 offset:4672
	ds_read_b128 v[20:23], v196 offset:96
	ds_read_b128 v[24:27], v196 offset:4704
	s_mov_b32 s82, s68
	s_mov_b32 s83, s68
	v_mov_b32_e32 v221, 0
	v_add_u32_e32 v197, 0, v28
	v_add_u32_e32 v244, 0x4800, v197
	v_add_u32_e32 v245, 0x6800, v197
	v_add_u32_e32 v246, 0x9000, v197
	v_add_u32_e32 v247, 0xb000, v197
	v_lshl_add_u64 v[192:193], v[190:191], 0, s[84:85]
	s_waitcnt lgkmcnt(3)
	v_mfma_f32_32x32x16_bf16 v[96:111], v[0:3], v[136:139], v[96:111]
	v_mov_b64_e32 v[0:1], s[68:69]
	v_mov_b64_e32 v[14:15], s[82:83]
	v_mov_b64_e32 v[2:3], s[70:71]
	v_mov_b64_e32 v[4:5], s[72:73]
	v_mov_b64_e32 v[6:7], s[74:75]
	v_mov_b64_e32 v[8:9], s[76:77]
	v_mov_b64_e32 v[10:11], s[78:79]
	s_waitcnt lgkmcnt(2)
	v_mfma_f32_32x32x16_bf16 v[64:79], v[16:19], v[136:139], v[64:79]
	v_mov_b64_e32 v[12:13], s[80:81]
	v_mov_b64_e32 v[46:47], v[14:15]
	v_mov_b64_e32 v[62:63], v[14:15]
	v_mov_b32_e32 v156, 0
	v_mov_b32_e32 v157, 0
	v_mov_b32_e32 v158, 0
	v_mov_b32_e32 v159, 0
	s_waitcnt lgkmcnt(1)
	v_mfma_f32_32x32x16_bf16 v[96:111], v[20:23], v[140:143], v[96:111]
	v_mov_b32_e32 v152, 0
	v_mov_b32_e32 v153, 0
	v_mov_b32_e32 v154, 0
	v_mov_b32_e32 v155, 0
	v_mov_b32_e32 v144, 0
	v_mov_b32_e32 v145, 0
	v_mov_b32_e32 v146, 0
	s_waitcnt lgkmcnt(0)
	v_mfma_f32_32x32x16_bf16 v[64:79], v[24:27], v[140:143], v[64:79]
	v_mov_b64_e32 v[30:31], v[14:15]
	v_mov_b32_e32 v147, 0
	v_mov_b32_e32 v148, 0
	v_mov_b32_e32 v149, 0
	v_mov_b32_e32 v150, 0
	v_mov_b32_e32 v151, 0
	v_mov_b64_e32 v[28:29], v[12:13]
	v_mov_b64_e32 v[26:27], v[10:11]
	v_mov_b64_e32 v[24:25], v[8:9]
	v_mov_b64_e32 v[22:23], v[6:7]
	v_mov_b64_e32 v[20:21], v[4:5]
	v_mov_b64_e32 v[18:19], v[2:3]
	v_mov_b64_e32 v[16:17], v[0:1]
	v_mov_b64_e32 v[44:45], v[12:13]
	v_mov_b64_e32 v[42:43], v[10:11]
	v_mov_b64_e32 v[40:41], v[8:9]
	v_mov_b64_e32 v[38:39], v[6:7]
	v_mov_b64_e32 v[36:37], v[4:5]
	v_mov_b64_e32 v[34:35], v[2:3]
	v_mov_b64_e32 v[32:33], v[0:1]
	v_mov_b64_e32 v[60:61], v[12:13]
	v_mov_b64_e32 v[58:59], v[10:11]
	v_mov_b64_e32 v[56:57], v[8:9]
	v_mov_b64_e32 v[54:55], v[6:7]
	v_mov_b64_e32 v[52:53], v[4:5]
	v_mov_b64_e32 v[50:51], v[2:3]
	v_mov_b64_e32 v[48:49], v[0:1]
	v_mov_b32_e32 v198, 0
	v_mov_b32_e32 v112, 0
	v_mov_b32_e32 v113, v221
	v_mov_b32_e32 v114, v221
	v_mov_b32_e32 v115, v221
	v_mov_b32_e32 v116, v221
	v_mov_b32_e32 v117, v221
	v_mov_b32_e32 v118, v221
	v_mov_b32_e32 v119, v221
	v_mov_b32_e32 v120, v221
	v_mov_b32_e32 v121, v221
	v_mov_b32_e32 v122, v221
	v_mov_b32_e32 v123, v221
	v_mov_b32_e32 v124, v221
	v_mov_b32_e32 v125, v221
	v_mov_b32_e32 v126, v221
	v_mov_b32_e32 v127, v221
	v_mov_b32_e32 v194, 1.0
	v_cmp_lt_u32_e32 vcc, 0xff, v199
	s_nop 1
	s_cmp_lg_u64 vcc, 0
	s_cbranch_scc1 .LBB0_457
	ds_read_b128 v[172:175], v196 offset:36864
	ds_read_b128 v[176:179], v196 offset:36896
	ds_read_b128 v[180:183], v196 offset:36928
	ds_read_b128 v[88:91], v196 offset:36960
	s_branch .Lg1_457

; #define PG8_STAGE(bufoff, gbase) PG8_STAGEV(bufoff, gbase, voff)
; #define PG8_STAGEB(bufoff, gbase) PG8_STAGEV(bufoff, gbase, voffB)
; #define PG8_LDA(dst, b, h) do { _Pragma("unroll") for (int m = 0; m < 4; ++m) _Pragma("unroll") for (int k = 0; k < 2; ++k) dst[m][k] = *(const LAS bf16x8*)(lds + PG8_SA(b, h) + aoff + m * 2048 + k * 1024); } while (0)
; #define PG8_LDB(dst, b, h) do { _Pragma("unroll") for (int n = 0; n < 2; ++n) _Pragma("unroll") for (int k = 0; k < 2; ++k) dst[n][k] = *(const LAS bf16x8*)(lds + PG8_SB(b, h) + boff + n * 2048 + k * 1024); } while (0)
; #define PG8_MMA(ai, bj, At, Bt) do { __builtin_amdgcn_s_setprio(1); _Pragma("unroll") for (int m = 0; m < 4; ++m) _Pragma("unroll") for (int n = 0; n < 2; ++n) _Pragma("unroll") for (int k = 0; k < 2; ++k) \
;         acc[ai][bj][m][n] = __builtin_amdgcn_mfma_f32_16x16x32_bf16(Bt[n][k], At[m][k], acc[ai][bj][m][n], 0, 0, 0); __builtin_amdgcn_s_setprio(0); } while (0)
; #define PG8_WAIT_V(n) asm volatile("s_waitcnt vmcnt(" #n ")" ::: "memory")
; #define PG8_WAIT_L(n) asm volatile("s_waitcnt lgkmcnt(" #n ")" ::: "memory")
; #define PG8_BAR __builtin_amdgcn_s_barrier()
; #define PG8_SCHED __builtin_amdgcn_sched_barrier(0)
; template <bool PERM, class Epi, class Sched>
; __device__ __forceinline__ void gemm_phase(LAS unsigned char* lds, const int K, const Sched& S, const Epi& E, const int wid0) {
;     ...
;             const bool last = (t == nt - 2);
;             const char* a1 = cA + (size_t)(t + 1) * kstep;
;             const char* a2 = last ? nA : cA + (size_t)(t + 2) * kstep; const char* b2 = last ? nB : cB + (size_t)(t + 2) * kstep;
;             const char* a3 = a2 + kstep; const char* b3 = b2 + kstep;
;             PG8_LDB(B0, 0, 0); PG8_LDB(B1, 0, 1); PG8_SCHED; PG8_LDA(At, 0, 0); PG8_STAGE(PG8_SA(1, 1), a1 + hstep);
;             PG8_WAIT_V(8); PG8_WAIT_L(0); PG8_BAR; PG8_MMA(0, 0, At, B0); PG8_MMA(0, 1, At, B1); PG8_BAR; PG8_SCHED;
;             PG8_LDA(At, 0, 1); PG8_STAGEB(PG8_SB(0, 0), b2); PG8_STAGEB(PG8_SB(0, 1), b2 + hstep); PG8_STAGE(PG8_SA(0, 0), a2);
.LBB0_635:
	s_add_u32 s6, s82, 0xfffc0080
	s_addc_u32 s7, s83, -1
	s_add_i32 s16, 0, 0x10000
	s_cmp_eq_u32 s92, 12
	s_cselect_b32 s23, s46, s7
	s_cselect_b32 s22, s48, s6
	v_add_u32_e32 v142, s16, v145
	s_cselect_b32 s7, s71, s81
	s_cselect_b32 s6, s73, s79
	s_add_i32 s58, 0, 0x14000
	ds_read_b128 v[138:141], v142
	ds_read_b128 v[148:151], v142 offset:1024
	ds_read_b128 v[152:155], v142 offset:2048
	ds_read_b128 v[156:159], v142 offset:3072
	v_add_u32_e32 v142, s58, v145
	ds_read_b128 v[160:163], v142
	ds_read_b128 v[164:167], v142 offset:1024
	ds_read_b128 v[168:171], v142 offset:2048
	ds_read_b128 v[172:175], v142 offset:3072
	v_lshl_add_u64 v[142:143], s[82:83], 0, v[134:135]
	s_add_i32 m0, s50, 0xc000
	ds_read_b128 v[176:179], v147
	ds_read_b128 v[180:183], v147 offset:1024
	ds_read_b128 v[186:189], v147 offset:2048
	ds_read_b128 v[190:193], v147 offset:3072
	ds_read_b128 v[194:197], v147 offset:4096
	ds_read_b128 v[222:225], v147 offset:5120
	ds_read_b128 v[226:229], v147 offset:6144
	ds_read_b128 v[230:233], v147 offset:7168
	global_load_lds_dwordx4 v[142:143], off
	v_lshl_add_u64 v[142:143], s[82:83], 0, v[136:137]
	s_add_i32 m0, s50, 0xe000
	s_nop 0
	global_load_lds_dwordx4 v[142:143], off
	s_waitcnt vmcnt(8)
	s_waitcnt lgkmcnt(0)
	s_barrier
	s_setprio 1
	s_waitcnt lgkmcnt(0)
	v_mfma_f32_16x16x32_bf16 v[124:127], v[138:141], v[176:179], v[124:127]
	v_mfma_f32_16x16x32_bf16 v[120:123], v[152:155], v[176:179], v[120:123]
	v_mfma_f32_16x16x32_bf16 v[108:111], v[138:141], v[186:189], v[108:111]
	v_mfma_f32_16x16x32_bf16 v[104:107], v[152:155], v[186:189], v[104:107]
	v_mfma_f32_16x16x32_bf16 v[92:95], v[138:141], v[194:197], v[92:95]
	v_mfma_f32_16x16x32_bf16 v[88:91], v[152:155], v[194:197], v[88:91]
	v_mfma_f32_16x16x32_bf16 v[76:79], v[138:141], v[226:229], v[76:79]
	v_mfma_f32_16x16x32_bf16 v[72:75], v[152:155], v[226:229], v[72:75]
	v_mfma_f32_16x16x32_bf16 v[124:127], v[148:151], v[180:183], v[124:127]
	v_mfma_f32_16x16x32_bf16 v[120:123], v[156:159], v[180:183], v[120:123]
	v_mfma_f32_16x16x32_bf16 v[108:111], v[148:151], v[190:193], v[108:111]
	v_mfma_f32_16x16x32_bf16 v[104:107], v[156:159], v[190:193], v[104:107]
	v_mfma_f32_16x16x32_bf16 v[92:95], v[148:151], v[222:225], v[92:95]
	v_mfma_f32_16x16x32_bf16 v[88:91], v[156:159], v[222:225], v[88:91]
	v_mfma_f32_16x16x32_bf16 v[76:79], v[148:151], v[230:233], v[76:79]
	v_mfma_f32_16x16x32_bf16 v[72:75], v[156:159], v[230:233], v[72:75]
	v_mfma_f32_16x16x32_bf16 v[116:119], v[160:163], v[176:179], v[116:119]
	v_mfma_f32_16x16x32_bf16 v[112:115], v[168:171], v[176:179], v[112:115]
	v_mfma_f32_16x16x32_bf16 v[100:103], v[160:163], v[186:189], v[100:103]
	v_mfma_f32_16x16x32_bf16 v[96:99], v[168:171], v[186:189], v[96:99]
	v_mfma_f32_16x16x32_bf16 v[84:87], v[160:163], v[194:197], v[84:87]
	v_mfma_f32_16x16x32_bf16 v[80:83], v[168:171], v[194:197], v[80:83]
	v_mfma_f32_16x16x32_bf16 v[68:71], v[160:163], v[226:229], v[68:71]
	v_mfma_f32_16x16x32_bf16 v[64:67], v[168:171], v[226:229], v[64:67]
	v_mfma_f32_16x16x32_bf16 v[116:119], v[164:167], v[180:183], v[116:119]
	v_mfma_f32_16x16x32_bf16 v[112:115], v[172:175], v[180:183], v[112:115]
	v_mfma_f32_16x16x32_bf16 v[100:103], v[164:167], v[190:193], v[100:103]
	v_mfma_f32_16x16x32_bf16 v[96:99], v[172:175], v[190:193], v[96:99]
	v_mfma_f32_16x16x32_bf16 v[84:87], v[164:167], v[222:225], v[84:87]
	v_mfma_f32_16x16x32_bf16 v[80:83], v[172:175], v[222:225], v[80:83]
	v_mfma_f32_16x16x32_bf16 v[68:71], v[164:167], v[230:233], v[68:71]
	v_mfma_f32_16x16x32_bf16 v[64:67], v[172:175], v[230:233], v[64:67]
	s_setprio 0
	s_barrier
	s_add_i32 s16, s16, s0
	v_lshl_add_u64 v[142:143], s[6:7], 0, v[184:185]
	s_mov_b32 m0, s16
	ds_read_b128 v[176:179], v147 offset:16384
	ds_read_b128 v[180:183], v147 offset:17408
	ds_read_b128 v[186:189], v147 offset:18432
	ds_read_b128 v[190:193], v147 offset:19456
	ds_read_b128 v[194:197], v147 offset:20480
	ds_read_b128 v[222:225], v147 offset:21504
	ds_read_b128 v[226:229], v147 offset:22528
	ds_read_b128 v[230:233], v147 offset:23552
	global_load_lds_dwordx4 v[142:143], off
	s_add_i32 m0, s16, 0x2000
	s_add_u32 s16, s6, 0x40000
	v_lshl_add_u64 v[234:235], s[6:7], 0, v[128:129]
	s_addc_u32 s17, s7, 0
	s_add_i32 s58, s58, s0
	global_load_lds_dwordx4 v[234:235], off
	v_lshl_add_u64 v[236:237], s[16:17], 0, v[184:185]
	s_mov_b32 m0, s58
	v_lshl_add_u64 v[238:239], s[22:23], 0, v[130:131]
	global_load_lds_dwordx4 v[236:237], off
	v_lshl_add_u64 v[236:237], s[16:17], 0, v[128:129]
	s_add_i32 m0, s58, 0x2000
	s_nop 0
	global_load_lds_dwordx4 v[236:237], off
	v_lshl_add_u64 v[236:237], s[22:23], 0, v[132:133]
	s_mov_b32 m0, s50
	s_nop 0
	global_load_lds_dwordx4 v[236:237], off
	s_mov_b32 m0, s52
	s_nop 0
	global_load_lds_dwordx4 v[238:239], off
	s_waitcnt vmcnt(8)
	s_waitcnt lgkmcnt(0)
	s_barrier
; #define PG8_STAGE(bufoff, gbase) PG8_STAGEV(bufoff, gbase, voff)
; #define PG8_STAGEB(bufoff, gbase) PG8_STAGEV(bufoff, gbase, voffB)
; #define PG8_LDA(dst, b, h) do { _Pragma("unroll") for (int m = 0; m < 4; ++m) _Pragma("unroll") for (int k = 0; k < 2; ++k) dst[m][k] = *(const LAS bf16x8*)(lds + PG8_SA(b, h) + aoff + m * 2048 + k * 1024); } while (0)
; #define PG8_LDB(dst, b, h) do { _Pragma("unroll") for (int n = 0; n < 2; ++n) _Pragma("unroll") for (int k = 0; k < 2; ++k) dst[n][k] = *(const LAS bf16x8*)(lds + PG8_SB(b, h) + boff + n * 2048 + k * 1024); } while (0)
; #define PG8_MMA(ai, bj, At, Bt) do { __builtin_amdgcn_s_setprio(1); _Pragma("unroll") for (int m = 0; m < 4; ++m) _Pragma("unroll") for (int n = 0; n < 2; ++n) _Pragma("unroll") for (int k = 0; k < 2; ++k) \
;         acc[ai][bj][m][n] = __builtin_amdgcn_mfma_f32_16x16x32_bf16(Bt[n][k], At[m][k], acc[ai][bj][m][n], 0, 0, 0); __builtin_amdgcn_s_setprio(0); } while (0)
; #define PG8_WAIT_V(n) asm volatile("s_waitcnt vmcnt(" #n ")" ::: "memory")
; #define PG8_WAIT_L(n) asm volatile("s_waitcnt lgkmcnt(" #n ")" ::: "memory")
; #define PG8_BAR __builtin_amdgcn_s_barrier()
; #define PG8_SCHED __builtin_amdgcn_sched_barrier(0)
; template <bool PERM, class Epi, class Sched>
; __device__ __forceinline__ void gemm_phase(LAS unsigned char* lds, const int K, const Sched& S, const Epi& E, const int wid0) {
;     ...
;             PG8_LDA(At, 0, 1); PG8_STAGEB(PG8_SB(0, 0), b2); PG8_STAGEB(PG8_SB(0, 1), b2 + hstep); PG8_STAGE(PG8_SA(0, 0), a2);
;             PG8_WAIT_V(8); PG8_WAIT_L(0); PG8_BAR; PG8_MMA(1, 0, At, B0); PG8_MMA(1, 1, At, B1); PG8_BAR; PG8_SCHED;
;             PG8_LDB(B0, 1, 0); PG8_LDB(B1, 1, 1); PG8_SCHED; PG8_LDA(At, 1, 0); PG8_STAGE(PG8_SA(0, 1), a2 + hstep);
;             PG8_WAIT_V(8); PG8_WAIT_L(0); PG8_BAR; PG8_MMA(0, 0, At, B0); PG8_MMA(0, 1, At, B1); PG8_BAR; PG8_SCHED;
	s_setprio 1
	s_waitcnt lgkmcnt(0)
	v_mfma_f32_16x16x32_bf16 v[60:63], v[138:141], v[176:179], v[60:63]
	v_mfma_f32_16x16x32_bf16 v[56:59], v[152:155], v[176:179], v[56:59]
	v_mfma_f32_16x16x32_bf16 v[44:47], v[138:141], v[186:189], v[44:47]
	v_mfma_f32_16x16x32_bf16 v[40:43], v[152:155], v[186:189], v[40:43]
	v_mfma_f32_16x16x32_bf16 v[28:31], v[138:141], v[194:197], v[28:31]
	v_mfma_f32_16x16x32_bf16 v[24:27], v[152:155], v[194:197], v[24:27]
	v_mfma_f32_16x16x32_bf16 v[12:15], v[138:141], v[226:229], v[12:15]
	v_mfma_f32_16x16x32_bf16 v[8:11], v[152:155], v[226:229], v[8:11]
	v_mfma_f32_16x16x32_bf16 v[60:63], v[148:151], v[180:183], v[60:63]
	v_mfma_f32_16x16x32_bf16 v[56:59], v[156:159], v[180:183], v[56:59]
	v_mfma_f32_16x16x32_bf16 v[44:47], v[148:151], v[190:193], v[44:47]
	v_mfma_f32_16x16x32_bf16 v[40:43], v[156:159], v[190:193], v[40:43]
	v_mfma_f32_16x16x32_bf16 v[28:31], v[148:151], v[222:225], v[28:31]
	v_mfma_f32_16x16x32_bf16 v[24:27], v[156:159], v[222:225], v[24:27]
	v_mfma_f32_16x16x32_bf16 v[12:15], v[148:151], v[230:233], v[12:15]
	v_mfma_f32_16x16x32_bf16 v[8:11], v[156:159], v[230:233], v[8:11]
	v_mfma_f32_16x16x32_bf16 v[52:55], v[160:163], v[176:179], v[52:55]
	v_mfma_f32_16x16x32_bf16 v[48:51], v[168:171], v[176:179], v[48:51]
	v_mfma_f32_16x16x32_bf16 v[36:39], v[160:163], v[186:189], v[36:39]
	v_mfma_f32_16x16x32_bf16 v[32:35], v[168:171], v[186:189], v[32:35]
	v_mfma_f32_16x16x32_bf16 v[20:23], v[160:163], v[194:197], v[20:23]
	v_mfma_f32_16x16x32_bf16 v[16:19], v[168:171], v[194:197], v[16:19]
	v_mfma_f32_16x16x32_bf16 v[4:7], v[160:163], v[226:229], v[4:7]
	v_mfma_f32_16x16x32_bf16 v[0:3], v[168:171], v[226:229], v[0:3]
	v_mfma_f32_16x16x32_bf16 v[52:55], v[164:167], v[180:183], v[52:55]
	v_mfma_f32_16x16x32_bf16 v[48:51], v[172:175], v[180:183], v[48:51]
	v_mfma_f32_16x16x32_bf16 v[36:39], v[164:167], v[190:193], v[36:39]
	v_mfma_f32_16x16x32_bf16 v[32:35], v[172:175], v[190:193], v[32:35]
	v_mfma_f32_16x16x32_bf16 v[20:23], v[164:167], v[222:225], v[20:23]
	v_mfma_f32_16x16x32_bf16 v[16:19], v[172:175], v[222:225], v[16:19]
	v_mfma_f32_16x16x32_bf16 v[4:7], v[164:167], v[230:233], v[4:7]
	v_mfma_f32_16x16x32_bf16 v[0:3], v[172:175], v[230:233], v[0:3]
	s_setprio 0
	s_barrier
	s_add_i32 s58, 0, 0x18000
	s_add_i32 s59, 0, 0x1c000
	v_add_u32_e32 v156, s58, v145
	v_add_u32_e32 v172, s59, v145
	ds_read_b128 v[138:141], v156
	ds_read_b128 v[148:151], v156 offset:1024
	ds_read_b128 v[152:155], v156 offset:2048
	ds_read_b128 v[156:159], v156 offset:3072
	ds_read_b128 v[160:163], v172
	ds_read_b128 v[164:167], v172 offset:1024
	ds_read_b128 v[168:171], v172 offset:2048
	ds_read_b128 v[172:175], v172 offset:3072
	s_add_u32 s16, s22, 0x40000
	s_addc_u32 s17, s23, 0
	s_mov_b32 m0, s53
	v_lshl_add_u64 v[240:241], s[16:17], 0, v[132:133]
	ds_read_b128 v[176:179], v147 offset:32768
	ds_read_b128 v[180:183], v147 offset:33792
	ds_read_b128 v[186:189], v147 offset:34816
	ds_read_b128 v[190:193], v147 offset:35840
	ds_read_b128 v[194:197], v147 offset:36864
	ds_read_b128 v[222:225], v147 offset:37888
	ds_read_b128 v[226:229], v147 offset:38912
	ds_read_b128 v[230:233], v147 offset:39936
	global_load_lds_dwordx4 v[240:241], off
	v_lshl_add_u64 v[240:241], s[16:17], 0, v[130:131]
	s_mov_b32 m0, s54
	s_nop 0
	global_load_lds_dwordx4 v[240:241], off
	s_waitcnt vmcnt(8)
	s_waitcnt lgkmcnt(0)
	s_barrier
	s_setprio 1
	s_waitcnt lgkmcnt(0)
	v_mfma_f32_16x16x32_bf16 v[124:127], v[138:141], v[176:179], v[124:127]
	v_mfma_f32_16x16x32_bf16 v[120:123], v[152:155], v[176:179], v[120:123]
	v_mfma_f32_16x16x32_bf16 v[108:111], v[138:141], v[186:189], v[108:111]
	v_mfma_f32_16x16x32_bf16 v[104:107], v[152:155], v[186:189], v[104:107]
	v_mfma_f32_16x16x32_bf16 v[92:95], v[138:141], v[194:197], v[92:95]
	v_mfma_f32_16x16x32_bf16 v[88:91], v[152:155], v[194:197], v[88:91]
	v_mfma_f32_16x16x32_bf16 v[76:79], v[138:141], v[226:229], v[76:79]
	v_mfma_f32_16x16x32_bf16 v[72:75], v[152:155], v[226:229], v[72:75]
	v_mfma_f32_16x16x32_bf16 v[124:127], v[148:151], v[180:183], v[124:127]
	v_mfma_f32_16x16x32_bf16 v[120:123], v[156:159], v[180:183], v[120:123]
	v_mfma_f32_16x16x32_bf16 v[108:111], v[148:151], v[190:193], v[108:111]
	v_mfma_f32_16x16x32_bf16 v[104:107], v[156:159], v[190:193], v[104:107]
	v_mfma_f32_16x16x32_bf16 v[92:95], v[148:151], v[222:225], v[92:95]
	v_mfma_f32_16x16x32_bf16 v[88:91], v[156:159], v[222:225], v[88:91]
	v_mfma_f32_16x16x32_bf16 v[76:79], v[148:151], v[230:233], v[76:79]
	v_mfma_f32_16x16x32_bf16 v[72:75], v[156:159], v[230:233], v[72:75]
	v_mfma_f32_16x16x32_bf16 v[116:119], v[160:163], v[176:179], v[116:119]
	v_mfma_f32_16x16x32_bf16 v[112:115], v[168:171], v[176:179], v[112:115]
	v_mfma_f32_16x16x32_bf16 v[100:103], v[160:163], v[186:189], v[100:103]
	v_mfma_f32_16x16x32_bf16 v[96:99], v[168:171], v[186:189], v[96:99]
	v_mfma_f32_16x16x32_bf16 v[84:87], v[160:163], v[194:197], v[84:87]
	v_mfma_f32_16x16x32_bf16 v[80:83], v[168:171], v[194:197], v[80:83]
	v_mfma_f32_16x16x32_bf16 v[68:71], v[160:163], v[226:229], v[68:71]
	v_mfma_f32_16x16x32_bf16 v[64:67], v[168:171], v[226:229], v[64:67]
	v_mfma_f32_16x16x32_bf16 v[116:119], v[164:167], v[180:183], v[116:119]
	v_mfma_f32_16x16x32_bf16 v[112:115], v[172:175], v[180:183], v[112:115]
	v_mfma_f32_16x16x32_bf16 v[100:103], v[164:167], v[190:193], v[100:103]
	v_mfma_f32_16x16x32_bf16 v[96:99], v[172:175], v[190:193], v[96:99]
	v_mfma_f32_16x16x32_bf16 v[84:87], v[164:167], v[222:225], v[84:87]
	v_mfma_f32_16x16x32_bf16 v[80:83], v[172:175], v[222:225], v[80:83]
	v_mfma_f32_16x16x32_bf16 v[68:71], v[164:167], v[230:233], v[68:71]
	v_mfma_f32_16x16x32_bf16 v[64:67], v[172:175], v[230:233], v[64:67]
	s_setprio 0
	s_barrier
; #define PG8_STAGE(bufoff, gbase) PG8_STAGEV(bufoff, gbase, voff)
; #define PG8_STAGEB(bufoff, gbase) PG8_STAGEV(bufoff, gbase, voffB)
; #define PG8_LDA(dst, b, h) do { _Pragma("unroll") for (int m = 0; m < 4; ++m) _Pragma("unroll") for (int k = 0; k < 2; ++k) dst[m][k] = *(const LAS bf16x8*)(lds + PG8_SA(b, h) + aoff + m * 2048 + k * 1024); } while (0)
; #define PG8_MMA(ai, bj, At, Bt) do { __builtin_amdgcn_s_setprio(1); _Pragma("unroll") for (int m = 0; m < 4; ++m) _Pragma("unroll") for (int n = 0; n < 2; ++n) _Pragma("unroll") for (int k = 0; k < 2; ++k) \
;         acc[ai][bj][m][n] = __builtin_amdgcn_mfma_f32_16x16x32_bf16(Bt[n][k], At[m][k], acc[ai][bj][m][n], 0, 0, 0); __builtin_amdgcn_s_setprio(0); } while (0)
; #define PG8_WAIT_V(n) asm volatile("s_waitcnt vmcnt(" #n ")" ::: "memory")
; #define PG8_WAIT_L(n) asm volatile("s_waitcnt lgkmcnt(" #n ")" ::: "memory")
; #define PG8_BAR __builtin_amdgcn_s_barrier()
; #define PG8_SCHED __builtin_amdgcn_sched_barrier(0)
; template <bool PERM, class Epi, class Sched>
; __device__ __forceinline__ void gemm_phase(LAS unsigned char* lds, const int K, const Sched& S, const Epi& E, const int wid0) {
;     ...
;             PG8_WAIT_V(8); PG8_WAIT_L(0); PG8_BAR; PG8_MMA(0, 0, At, B0); PG8_MMA(0, 1, At, B1); PG8_BAR; PG8_SCHED;
;             PG8_LDA(At, 1, 1); PG8_STAGEB(PG8_SB(1, 0), b3); PG8_STAGEB(PG8_SB(1, 1), b3 + hstep); PG8_STAGE(PG8_SA(1, 0), a3);
;             PG8_WAIT_V(8); PG8_WAIT_L(0); PG8_BAR; PG8_MMA(1, 0, At, B0); PG8_MMA(1, 1, At, B1); PG8_BAR; PG8_SCHED;
;         }
	s_add_i32 s16, s58, s0
	v_lshl_add_u64 v[142:143], v[142:143], 0, s[42:43]
	s_mov_b32 m0, s16
	ds_read_b128 v[176:179], v147 offset:49152
	ds_read_b128 v[180:183], v147 offset:50176
	ds_read_b128 v[186:189], v147 offset:51200
	ds_read_b128 v[190:193], v147 offset:52224
	ds_read_b128 v[194:197], v147 offset:53248
	ds_read_b128 v[222:225], v147 offset:54272
	ds_read_b128 v[226:229], v147 offset:55296
	ds_read_b128 v[230:233], v147 offset:56320
	global_load_lds_dwordx4 v[142:143], off
	s_add_i32 m0, s16, 0x2000
	s_add_u32 s6, s6, 0x40080
	v_lshl_add_u64 v[142:143], v[234:235], 0, s[42:43]
	s_addc_u32 s7, s7, 0
	s_add_i32 s16, s59, s0
	global_load_lds_dwordx4 v[142:143], off
	v_lshl_add_u64 v[142:143], s[6:7], 0, v[184:185]
	s_mov_b32 m0, s16
	s_nop 0
	global_load_lds_dwordx4 v[142:143], off
	v_lshl_add_u64 v[142:143], s[6:7], 0, v[128:129]
	s_add_i32 m0, s16, 0x2000
	s_nop 0
	global_load_lds_dwordx4 v[142:143], off
	v_lshl_add_u64 v[142:143], v[236:237], 0, s[42:43]
	s_mov_b32 m0, s55
	s_nop 0
	global_load_lds_dwordx4 v[142:143], off
	v_lshl_add_u64 v[142:143], v[238:239], 0, s[42:43]
	s_mov_b32 m0, s66
	s_nop 0
	global_load_lds_dwordx4 v[142:143], off
	s_waitcnt vmcnt(8)
	s_waitcnt lgkmcnt(0)
	s_barrier
	s_setprio 1
	s_waitcnt lgkmcnt(0)
	v_mfma_f32_16x16x32_bf16 v[60:63], v[138:141], v[176:179], v[60:63]
	v_mfma_f32_16x16x32_bf16 v[56:59], v[152:155], v[176:179], v[56:59]
	v_mfma_f32_16x16x32_bf16 v[44:47], v[138:141], v[186:189], v[44:47]
	v_mfma_f32_16x16x32_bf16 v[40:43], v[152:155], v[186:189], v[40:43]
	v_mfma_f32_16x16x32_bf16 v[28:31], v[138:141], v[194:197], v[28:31]
	v_mfma_f32_16x16x32_bf16 v[24:27], v[152:155], v[194:197], v[24:27]
	v_mfma_f32_16x16x32_bf16 v[12:15], v[138:141], v[226:229], v[12:15]
	v_mfma_f32_16x16x32_bf16 v[8:11], v[152:155], v[226:229], v[8:11]
	v_mfma_f32_16x16x32_bf16 v[60:63], v[148:151], v[180:183], v[60:63]
	v_mfma_f32_16x16x32_bf16 v[56:59], v[156:159], v[180:183], v[56:59]
	v_mfma_f32_16x16x32_bf16 v[44:47], v[148:151], v[190:193], v[44:47]
	v_mfma_f32_16x16x32_bf16 v[40:43], v[156:159], v[190:193], v[40:43]
	v_mfma_f32_16x16x32_bf16 v[28:31], v[148:151], v[222:225], v[28:31]
	v_mfma_f32_16x16x32_bf16 v[24:27], v[156:159], v[222:225], v[24:27]
	v_mfma_f32_16x16x32_bf16 v[12:15], v[148:151], v[230:233], v[12:15]
	v_mfma_f32_16x16x32_bf16 v[8:11], v[156:159], v[230:233], v[8:11]
	v_mfma_f32_16x16x32_bf16 v[52:55], v[160:163], v[176:179], v[52:55]
	v_mfma_f32_16x16x32_bf16 v[48:51], v[168:171], v[176:179], v[48:51]
	v_mfma_f32_16x16x32_bf16 v[36:39], v[160:163], v[186:189], v[36:39]
	v_mfma_f32_16x16x32_bf16 v[32:35], v[168:171], v[186:189], v[32:35]
	v_mfma_f32_16x16x32_bf16 v[20:23], v[160:163], v[194:197], v[20:23]
	v_mfma_f32_16x16x32_bf16 v[16:19], v[168:171], v[194:197], v[16:19]
	v_mfma_f32_16x16x32_bf16 v[4:7], v[160:163], v[226:229], v[4:7]
	v_mfma_f32_16x16x32_bf16 v[0:3], v[168:171], v[226:229], v[0:3]
	v_mfma_f32_16x16x32_bf16 v[52:55], v[164:167], v[180:183], v[52:55]
	v_mfma_f32_16x16x32_bf16 v[48:51], v[172:175], v[180:183], v[48:51]
	v_mfma_f32_16x16x32_bf16 v[36:39], v[164:167], v[190:193], v[36:39]
	v_mfma_f32_16x16x32_bf16 v[32:35], v[172:175], v[190:193], v[32:35]
	v_mfma_f32_16x16x32_bf16 v[20:23], v[164:167], v[222:225], v[20:23]
	v_mfma_f32_16x16x32_bf16 v[16:19], v[172:175], v[222:225], v[16:19]
	v_mfma_f32_16x16x32_bf16 v[4:7], v[164:167], v[230:233], v[4:7]
	v_mfma_f32_16x16x32_bf16 v[0:3], v[172:175], v[230:233], v[0:3]
	s_setprio 0
	s_barrier
	s_add_i32 s92, s92, 2
	s_add_u32 s82, s82, 0x100
	s_addc_u32 s83, s83, 0
	s_add_u32 s79, s79, 0x100
	s_addc_u32 s81, s81, 0
	s_cmp_gt_u32 s92, 13
	s_cbranch_scc0 .LBB0_635
	s_and_b64 vcc, exec, s[68:69]
	s_cbranch_vccz .LBB0_638
	s_barrier

; #define PG8_STAGE(bufoff, gbase) PG8_STAGEV(bufoff, gbase, voff)
; #define PG8_STAGEB(bufoff, gbase) PG8_STAGEV(bufoff, gbase, voffB)
; #define PG8_LDA(dst, b, h) do { _Pragma("unroll") for (int m = 0; m < 4; ++m) _Pragma("unroll") for (int k = 0; k < 2; ++k) dst[m][k] = *(const LAS bf16x8*)(lds + PG8_SA(b, h) + aoff + m * 2048 + k * 1024); } while (0)
; #define PG8_LDB(dst, b, h) do { _Pragma("unroll") for (int n = 0; n < 2; ++n) _Pragma("unroll") for (int k = 0; k < 2; ++k) dst[n][k] = *(const LAS bf16x8*)(lds + PG8_SB(b, h) + boff + n * 2048 + k * 1024); } while (0)
; #define PG8_MMA(ai, bj, At, Bt) do { __builtin_amdgcn_s_setprio(1); _Pragma("unroll") for (int m = 0; m < 4; ++m) _Pragma("unroll") for (int n = 0; n < 2; ++n) _Pragma("unroll") for (int k = 0; k < 2; ++k) \
;         acc[ai][bj][m][n] = __builtin_amdgcn_mfma_f32_16x16x32_bf16(Bt[n][k], At[m][k], acc[ai][bj][m][n], 0, 0, 0); __builtin_amdgcn_s_setprio(0); } while (0)
; #define PG8_WAIT_V(n) asm volatile("s_waitcnt vmcnt(" #n ")" ::: "memory")
; #define PG8_WAIT_L(n) asm volatile("s_waitcnt lgkmcnt(" #n ")" ::: "memory")
; #define PG8_BAR __builtin_amdgcn_s_barrier()
; #define PG8_SCHED __builtin_amdgcn_sched_barrier(0)
; template <bool PERM, class Epi, class Sched>
; __device__ __forceinline__ void gemm_phase(LAS unsigned char* lds, const int K, const Sched& S, const Epi& E, const int wid0) {
;     ...
;             const bool last = (t == nt - 2);
;             const char* a1 = cA + (size_t)(t + 1) * kstep;
;             const char* a2 = last ? nA : cA + (size_t)(t + 2) * kstep; const char* b2 = last ? nB : cB + (size_t)(t + 2) * kstep;
;             const char* a3 = a2 + kstep; const char* b3 = b2 + kstep;
;             PG8_LDB(B0, 0, 0); PG8_LDB(B1, 0, 1); PG8_SCHED; PG8_LDA(At, 0, 0); PG8_STAGE(PG8_SA(1, 1), a1 + hstep);
;             PG8_WAIT_V(8); PG8_WAIT_L(0); PG8_BAR; PG8_MMA(0, 0, At, B0); PG8_MMA(0, 1, At, B1); PG8_BAR; PG8_SCHED;
;             PG8_LDA(At, 0, 1); PG8_STAGEB(PG8_SB(0, 0), b2); PG8_STAGEB(PG8_SB(0, 1), b2 + hstep); PG8_STAGE(PG8_SA(0, 0), a2);
.LBB0_651:
	s_add_u32 s6, s82, 0xfffc0080
	s_addc_u32 s7, s83, -1
	s_add_i32 s16, 0, 0x10000
	s_cmp_eq_u32 s92, 12
	s_cselect_b32 s23, s46, s7
	s_cselect_b32 s22, s48, s6
	s_cselect_b32 s7, s71, s81
	s_cselect_b32 s6, s73, s79
	s_add_i32 s58, 0, 0x14000
	v_add_u32_e32 v154, s16, v147
	v_add_u32_e32 v170, s58, v147
	ds_read_b128 v[138:141], v154
	ds_read_b128 v[142:145], v154 offset:1024
	ds_read_b128 v[150:153], v154 offset:2048
	ds_read_b128 v[154:157], v154 offset:3072
	ds_read_b128 v[158:161], v170
	ds_read_b128 v[162:165], v170 offset:1024
	ds_read_b128 v[166:169], v170 offset:2048
	ds_read_b128 v[170:173], v170 offset:3072
	v_lshl_add_u64 v[182:183], s[82:83], 0, v[134:135]
	s_add_i32 m0, s50, 0xc000
	ds_read_b128 v[174:177], v149
	ds_read_b128 v[178:181], v149 offset:1024
	ds_read_b128 v[186:189], v149 offset:2048
	ds_read_b128 v[190:193], v149 offset:3072
	ds_read_b128 v[194:197], v149 offset:4096
	ds_read_b128 v[222:225], v149 offset:5120
	ds_read_b128 v[226:229], v149 offset:6144
	ds_read_b128 v[230:233], v149 offset:7168
	global_load_lds_dwordx4 v[182:183], off
	v_lshl_add_u64 v[182:183], s[82:83], 0, v[136:137]
	s_add_i32 m0, s50, 0xe000
	s_nop 0
	global_load_lds_dwordx4 v[182:183], off
	s_waitcnt vmcnt(8)
	s_waitcnt lgkmcnt(0)
	s_barrier
	s_setprio 1
	s_waitcnt lgkmcnt(0)
	v_mfma_f32_16x16x32_bf16 v[124:127], v[138:141], v[174:177], v[124:127]
	v_mfma_f32_16x16x32_bf16 v[120:123], v[150:153], v[174:177], v[120:123]
	v_mfma_f32_16x16x32_bf16 v[108:111], v[138:141], v[186:189], v[108:111]
	v_mfma_f32_16x16x32_bf16 v[104:107], v[150:153], v[186:189], v[104:107]
	v_mfma_f32_16x16x32_bf16 v[92:95], v[138:141], v[194:197], v[92:95]
	v_mfma_f32_16x16x32_bf16 v[88:91], v[150:153], v[194:197], v[88:91]
	v_mfma_f32_16x16x32_bf16 v[76:79], v[138:141], v[226:229], v[76:79]
	v_mfma_f32_16x16x32_bf16 v[72:75], v[150:153], v[226:229], v[72:75]
	v_mfma_f32_16x16x32_bf16 v[124:127], v[142:145], v[178:181], v[124:127]
	v_mfma_f32_16x16x32_bf16 v[120:123], v[154:157], v[178:181], v[120:123]
	v_mfma_f32_16x16x32_bf16 v[108:111], v[142:145], v[190:193], v[108:111]
	v_mfma_f32_16x16x32_bf16 v[104:107], v[154:157], v[190:193], v[104:107]
	v_mfma_f32_16x16x32_bf16 v[92:95], v[142:145], v[222:225], v[92:95]
	v_mfma_f32_16x16x32_bf16 v[88:91], v[154:157], v[222:225], v[88:91]
	v_mfma_f32_16x16x32_bf16 v[76:79], v[142:145], v[230:233], v[76:79]
	v_mfma_f32_16x16x32_bf16 v[72:75], v[154:157], v[230:233], v[72:75]
	v_mfma_f32_16x16x32_bf16 v[116:119], v[158:161], v[174:177], v[116:119]
	v_mfma_f32_16x16x32_bf16 v[112:115], v[166:169], v[174:177], v[112:115]
	v_mfma_f32_16x16x32_bf16 v[100:103], v[158:161], v[186:189], v[100:103]
	v_mfma_f32_16x16x32_bf16 v[96:99], v[166:169], v[186:189], v[96:99]
	v_mfma_f32_16x16x32_bf16 v[84:87], v[158:161], v[194:197], v[84:87]
	v_mfma_f32_16x16x32_bf16 v[80:83], v[166:169], v[194:197], v[80:83]
	v_mfma_f32_16x16x32_bf16 v[68:71], v[158:161], v[226:229], v[68:71]
	v_mfma_f32_16x16x32_bf16 v[64:67], v[166:169], v[226:229], v[64:67]
	v_mfma_f32_16x16x32_bf16 v[116:119], v[162:165], v[178:181], v[116:119]
	v_mfma_f32_16x16x32_bf16 v[112:115], v[170:173], v[178:181], v[112:115]
	v_mfma_f32_16x16x32_bf16 v[100:103], v[162:165], v[190:193], v[100:103]
	v_mfma_f32_16x16x32_bf16 v[96:99], v[170:173], v[190:193], v[96:99]
	v_mfma_f32_16x16x32_bf16 v[84:87], v[162:165], v[222:225], v[84:87]
	v_mfma_f32_16x16x32_bf16 v[80:83], v[170:173], v[222:225], v[80:83]
	v_mfma_f32_16x16x32_bf16 v[68:71], v[162:165], v[230:233], v[68:71]
	v_mfma_f32_16x16x32_bf16 v[64:67], v[170:173], v[230:233], v[64:67]
	s_setprio 0
	s_barrier
	s_add_i32 s16, s16, s0
	v_lshl_add_u64 v[182:183], s[6:7], 0, v[184:185]
	s_mov_b32 m0, s16
	ds_read_b128 v[174:177], v149 offset:16384
	ds_read_b128 v[178:181], v149 offset:17408
	ds_read_b128 v[186:189], v149 offset:18432
	ds_read_b128 v[190:193], v149 offset:19456
	ds_read_b128 v[194:197], v149 offset:20480
	ds_read_b128 v[222:225], v149 offset:21504
	ds_read_b128 v[226:229], v149 offset:22528
	ds_read_b128 v[230:233], v149 offset:23552
	global_load_lds_dwordx4 v[182:183], off
	s_add_i32 m0, s16, 0x2000
	s_add_u32 s16, s6, 0x40000
	v_lshl_add_u64 v[234:235], s[6:7], 0, v[128:129]
	s_addc_u32 s17, s7, 0
	s_add_i32 s58, s58, s0
	global_load_lds_dwordx4 v[234:235], off
	v_lshl_add_u64 v[236:237], s[16:17], 0, v[184:185]
	s_mov_b32 m0, s58
	v_lshl_add_u64 v[238:239], s[22:23], 0, v[130:131]
	global_load_lds_dwordx4 v[236:237], off
	v_lshl_add_u64 v[236:237], s[16:17], 0, v[128:129]
	s_add_i32 m0, s58, 0x2000
	s_nop 0
	global_load_lds_dwordx4 v[236:237], off
	v_lshl_add_u64 v[236:237], s[22:23], 0, v[132:133]
	s_mov_b32 m0, s50
	s_nop 0
	global_load_lds_dwordx4 v[236:237], off
	s_mov_b32 m0, s52
	s_nop 0
	global_load_lds_dwordx4 v[238:239], off
	s_waitcnt vmcnt(8)
	s_waitcnt lgkmcnt(0)
	s_barrier
; #define PG8_STAGE(bufoff, gbase) PG8_STAGEV(bufoff, gbase, voff)
; #define PG8_STAGEB(bufoff, gbase) PG8_STAGEV(bufoff, gbase, voffB)
; #define PG8_LDA(dst, b, h) do { _Pragma("unroll") for (int m = 0; m < 4; ++m) _Pragma("unroll") for (int k = 0; k < 2; ++k) dst[m][k] = *(const LAS bf16x8*)(lds + PG8_SA(b, h) + aoff + m * 2048 + k * 1024); } while (0)
; #define PG8_LDB(dst, b, h) do { _Pragma("unroll") for (int n = 0; n < 2; ++n) _Pragma("unroll") for (int k = 0; k < 2; ++k) dst[n][k] = *(const LAS bf16x8*)(lds + PG8_SB(b, h) + boff + n * 2048 + k * 1024); } while (0)
; #define PG8_MMA(ai, bj, At, Bt) do { __builtin_amdgcn_s_setprio(1); _Pragma("unroll") for (int m = 0; m < 4; ++m) _Pragma("unroll") for (int n = 0; n < 2; ++n) _Pragma("unroll") for (int k = 0; k < 2; ++k) \
;         acc[ai][bj][m][n] = __builtin_amdgcn_mfma_f32_16x16x32_bf16(Bt[n][k], At[m][k], acc[ai][bj][m][n], 0, 0, 0); __builtin_amdgcn_s_setprio(0); } while (0)
; #define PG8_WAIT_V(n) asm volatile("s_waitcnt vmcnt(" #n ")" ::: "memory")
; #define PG8_WAIT_L(n) asm volatile("s_waitcnt lgkmcnt(" #n ")" ::: "memory")
; #define PG8_BAR __builtin_amdgcn_s_barrier()
; #define PG8_SCHED __builtin_amdgcn_sched_barrier(0)
; template <bool PERM, class Epi, class Sched>
; __device__ __forceinline__ void gemm_phase(LAS unsigned char* lds, const int K, const Sched& S, const Epi& E, const int wid0) {
;     ...
;             PG8_LDA(At, 0, 1); PG8_STAGEB(PG8_SB(0, 0), b2); PG8_STAGEB(PG8_SB(0, 1), b2 + hstep); PG8_STAGE(PG8_SA(0, 0), a2);
;             PG8_WAIT_V(8); PG8_WAIT_L(0); PG8_BAR; PG8_MMA(1, 0, At, B0); PG8_MMA(1, 1, At, B1); PG8_BAR; PG8_SCHED;
;             PG8_LDB(B0, 1, 0); PG8_LDB(B1, 1, 1); PG8_SCHED; PG8_LDA(At, 1, 0); PG8_STAGE(PG8_SA(0, 1), a2 + hstep);
;             PG8_WAIT_V(8); PG8_WAIT_L(0); PG8_BAR; PG8_MMA(0, 0, At, B0); PG8_MMA(0, 1, At, B1); PG8_BAR; PG8_SCHED;
	s_setprio 1
	s_waitcnt lgkmcnt(0)
	v_mfma_f32_16x16x32_bf16 v[60:63], v[138:141], v[174:177], v[60:63]
	v_mfma_f32_16x16x32_bf16 v[56:59], v[150:153], v[174:177], v[56:59]
	v_mfma_f32_16x16x32_bf16 v[44:47], v[138:141], v[186:189], v[44:47]
	v_mfma_f32_16x16x32_bf16 v[40:43], v[150:153], v[186:189], v[40:43]
	v_mfma_f32_16x16x32_bf16 v[28:31], v[138:141], v[194:197], v[28:31]
	v_mfma_f32_16x16x32_bf16 v[24:27], v[150:153], v[194:197], v[24:27]
	v_mfma_f32_16x16x32_bf16 v[12:15], v[138:141], v[226:229], v[12:15]
	v_mfma_f32_16x16x32_bf16 v[8:11], v[150:153], v[226:229], v[8:11]
	v_mfma_f32_16x16x32_bf16 v[60:63], v[142:145], v[178:181], v[60:63]
	v_mfma_f32_16x16x32_bf16 v[56:59], v[154:157], v[178:181], v[56:59]
	v_mfma_f32_16x16x32_bf16 v[44:47], v[142:145], v[190:193], v[44:47]
	v_mfma_f32_16x16x32_bf16 v[40:43], v[154:157], v[190:193], v[40:43]
	v_mfma_f32_16x16x32_bf16 v[28:31], v[142:145], v[222:225], v[28:31]
	v_mfma_f32_16x16x32_bf16 v[24:27], v[154:157], v[222:225], v[24:27]
	v_mfma_f32_16x16x32_bf16 v[12:15], v[142:145], v[230:233], v[12:15]
	v_mfma_f32_16x16x32_bf16 v[8:11], v[154:157], v[230:233], v[8:11]
	v_mfma_f32_16x16x32_bf16 v[52:55], v[158:161], v[174:177], v[52:55]
	v_mfma_f32_16x16x32_bf16 v[48:51], v[166:169], v[174:177], v[48:51]
	v_mfma_f32_16x16x32_bf16 v[36:39], v[158:161], v[186:189], v[36:39]
	v_mfma_f32_16x16x32_bf16 v[32:35], v[166:169], v[186:189], v[32:35]
	v_mfma_f32_16x16x32_bf16 v[20:23], v[158:161], v[194:197], v[20:23]
	v_mfma_f32_16x16x32_bf16 v[16:19], v[166:169], v[194:197], v[16:19]
	v_mfma_f32_16x16x32_bf16 v[4:7], v[158:161], v[226:229], v[4:7]
	v_mfma_f32_16x16x32_bf16 v[0:3], v[166:169], v[226:229], v[0:3]
	v_mfma_f32_16x16x32_bf16 v[52:55], v[162:165], v[178:181], v[52:55]
	v_mfma_f32_16x16x32_bf16 v[48:51], v[170:173], v[178:181], v[48:51]
	v_mfma_f32_16x16x32_bf16 v[36:39], v[162:165], v[190:193], v[36:39]
	v_mfma_f32_16x16x32_bf16 v[32:35], v[170:173], v[190:193], v[32:35]
	v_mfma_f32_16x16x32_bf16 v[20:23], v[162:165], v[222:225], v[20:23]
	v_mfma_f32_16x16x32_bf16 v[16:19], v[170:173], v[222:225], v[16:19]
	v_mfma_f32_16x16x32_bf16 v[4:7], v[162:165], v[230:233], v[4:7]
	v_mfma_f32_16x16x32_bf16 v[0:3], v[170:173], v[230:233], v[0:3]
	s_setprio 0
	s_barrier
	s_add_i32 s58, 0, 0x18000
	s_add_i32 s59, 0, 0x1c000
	v_add_u32_e32 v154, s58, v147
	v_add_u32_e32 v170, s59, v147
	ds_read_b128 v[138:141], v154
	ds_read_b128 v[142:145], v154 offset:1024
	ds_read_b128 v[150:153], v154 offset:2048
	ds_read_b128 v[154:157], v154 offset:3072
	ds_read_b128 v[158:161], v170
	ds_read_b128 v[162:165], v170 offset:1024
	ds_read_b128 v[166:169], v170 offset:2048
	ds_read_b128 v[170:173], v170 offset:3072
	s_add_u32 s16, s22, 0x40000
	s_addc_u32 s17, s23, 0
	s_mov_b32 m0, s53
	v_lshl_add_u64 v[240:241], s[16:17], 0, v[132:133]
	ds_read_b128 v[174:177], v149 offset:32768
	ds_read_b128 v[178:181], v149 offset:33792
	ds_read_b128 v[186:189], v149 offset:34816
	ds_read_b128 v[190:193], v149 offset:35840
	ds_read_b128 v[194:197], v149 offset:36864
	ds_read_b128 v[222:225], v149 offset:37888
	ds_read_b128 v[226:229], v149 offset:38912
	ds_read_b128 v[230:233], v149 offset:39936
	global_load_lds_dwordx4 v[240:241], off
	v_lshl_add_u64 v[240:241], s[16:17], 0, v[130:131]
	s_mov_b32 m0, s54
	s_nop 0
	global_load_lds_dwordx4 v[240:241], off
	s_waitcnt vmcnt(8)
	s_waitcnt lgkmcnt(0)
	s_barrier
	s_setprio 1
	s_waitcnt lgkmcnt(0)
	v_mfma_f32_16x16x32_bf16 v[124:127], v[138:141], v[174:177], v[124:127]
	v_mfma_f32_16x16x32_bf16 v[120:123], v[150:153], v[174:177], v[120:123]
	v_mfma_f32_16x16x32_bf16 v[108:111], v[138:141], v[186:189], v[108:111]
	v_mfma_f32_16x16x32_bf16 v[104:107], v[150:153], v[186:189], v[104:107]
	v_mfma_f32_16x16x32_bf16 v[92:95], v[138:141], v[194:197], v[92:95]
	v_mfma_f32_16x16x32_bf16 v[88:91], v[150:153], v[194:197], v[88:91]
	v_mfma_f32_16x16x32_bf16 v[76:79], v[138:141], v[226:229], v[76:79]
	v_mfma_f32_16x16x32_bf16 v[72:75], v[150:153], v[226:229], v[72:75]
	v_mfma_f32_16x16x32_bf16 v[124:127], v[142:145], v[178:181], v[124:127]
	v_mfma_f32_16x16x32_bf16 v[120:123], v[154:157], v[178:181], v[120:123]
	v_mfma_f32_16x16x32_bf16 v[108:111], v[142:145], v[190:193], v[108:111]
	v_mfma_f32_16x16x32_bf16 v[104:107], v[154:157], v[190:193], v[104:107]
	v_mfma_f32_16x16x32_bf16 v[92:95], v[142:145], v[222:225], v[92:95]
	v_mfma_f32_16x16x32_bf16 v[88:91], v[154:157], v[222:225], v[88:91]
	v_mfma_f32_16x16x32_bf16 v[76:79], v[142:145], v[230:233], v[76:79]
	v_mfma_f32_16x16x32_bf16 v[72:75], v[154:157], v[230:233], v[72:75]
	v_mfma_f32_16x16x32_bf16 v[116:119], v[158:161], v[174:177], v[116:119]
	v_mfma_f32_16x16x32_bf16 v[112:115], v[166:169], v[174:177], v[112:115]
	v_mfma_f32_16x16x32_bf16 v[100:103], v[158:161], v[186:189], v[100:103]
	v_mfma_f32_16x16x32_bf16 v[96:99], v[166:169], v[186:189], v[96:99]
	v_mfma_f32_16x16x32_bf16 v[84:87], v[158:161], v[194:197], v[84:87]
	v_mfma_f32_16x16x32_bf16 v[80:83], v[166:169], v[194:197], v[80:83]
	v_mfma_f32_16x16x32_bf16 v[68:71], v[158:161], v[226:229], v[68:71]
	v_mfma_f32_16x16x32_bf16 v[64:67], v[166:169], v[226:229], v[64:67]
	v_mfma_f32_16x16x32_bf16 v[116:119], v[162:165], v[178:181], v[116:119]
	v_mfma_f32_16x16x32_bf16 v[112:115], v[170:173], v[178:181], v[112:115]
	v_mfma_f32_16x16x32_bf16 v[100:103], v[162:165], v[190:193], v[100:103]
	v_mfma_f32_16x16x32_bf16 v[96:99], v[170:173], v[190:193], v[96:99]
	v_mfma_f32_16x16x32_bf16 v[84:87], v[162:165], v[222:225], v[84:87]
	v_mfma_f32_16x16x32_bf16 v[80:83], v[170:173], v[222:225], v[80:83]
	v_mfma_f32_16x16x32_bf16 v[68:71], v[162:165], v[230:233], v[68:71]
	v_mfma_f32_16x16x32_bf16 v[64:67], v[170:173], v[230:233], v[64:67]
	s_setprio 0
	s_barrier
; #define PG8_STAGE(bufoff, gbase) PG8_STAGEV(bufoff, gbase, voff)
; #define PG8_STAGEB(bufoff, gbase) PG8_STAGEV(bufoff, gbase, voffB)
; #define PG8_LDA(dst, b, h) do { _Pragma("unroll") for (int m = 0; m < 4; ++m) _Pragma("unroll") for (int k = 0; k < 2; ++k) dst[m][k] = *(const LAS bf16x8*)(lds + PG8_SA(b, h) + aoff + m * 2048 + k * 1024); } while (0)
; #define PG8_MMA(ai, bj, At, Bt) do { __builtin_amdgcn_s_setprio(1); _Pragma("unroll") for (int m = 0; m < 4; ++m) _Pragma("unroll") for (int n = 0; n < 2; ++n) _Pragma("unroll") for (int k = 0; k < 2; ++k) \
;         acc[ai][bj][m][n] = __builtin_amdgcn_mfma_f32_16x16x32_bf16(Bt[n][k], At[m][k], acc[ai][bj][m][n], 0, 0, 0); __builtin_amdgcn_s_setprio(0); } while (0)
; #define PG8_WAIT_V(n) asm volatile("s_waitcnt vmcnt(" #n ")" ::: "memory")
; #define PG8_WAIT_L(n) asm volatile("s_waitcnt lgkmcnt(" #n ")" ::: "memory")
; #define PG8_BAR __builtin_amdgcn_s_barrier()
; #define PG8_SCHED __builtin_amdgcn_sched_barrier(0)
; template <bool PERM, class Epi, class Sched>
; __device__ __forceinline__ void gemm_phase(LAS unsigned char* lds, const int K, const Sched& S, const Epi& E, const int wid0) {
;     ...
;             PG8_WAIT_V(8); PG8_WAIT_L(0); PG8_BAR; PG8_MMA(0, 0, At, B0); PG8_MMA(0, 1, At, B1); PG8_BAR; PG8_SCHED;
;             PG8_LDA(At, 1, 1); PG8_STAGEB(PG8_SB(1, 0), b3); PG8_STAGEB(PG8_SB(1, 1), b3 + hstep); PG8_STAGE(PG8_SA(1, 0), a3);
;             PG8_WAIT_V(8); PG8_WAIT_L(0); PG8_BAR; PG8_MMA(1, 0, At, B0); PG8_MMA(1, 1, At, B1); PG8_BAR; PG8_SCHED;
;         }
	s_add_i32 s16, s58, s0
	v_lshl_add_u64 v[182:183], v[182:183], 0, s[42:43]
	s_mov_b32 m0, s16
	ds_read_b128 v[174:177], v149 offset:49152
	ds_read_b128 v[178:181], v149 offset:50176
	ds_read_b128 v[186:189], v149 offset:51200
	ds_read_b128 v[190:193], v149 offset:52224
	ds_read_b128 v[194:197], v149 offset:53248
	ds_read_b128 v[222:225], v149 offset:54272
	ds_read_b128 v[226:229], v149 offset:55296
	ds_read_b128 v[230:233], v149 offset:56320
	global_load_lds_dwordx4 v[182:183], off
	s_add_i32 m0, s16, 0x2000
	s_add_u32 s6, s6, 0x40080
	v_lshl_add_u64 v[182:183], v[234:235], 0, s[42:43]
	s_addc_u32 s7, s7, 0
	s_add_i32 s16, s59, s0
	global_load_lds_dwordx4 v[182:183], off
	v_lshl_add_u64 v[182:183], s[6:7], 0, v[184:185]
	s_mov_b32 m0, s16
	s_nop 0
	global_load_lds_dwordx4 v[182:183], off
	v_lshl_add_u64 v[182:183], s[6:7], 0, v[128:129]
	s_add_i32 m0, s16, 0x2000
	s_nop 0
	global_load_lds_dwordx4 v[182:183], off
	v_lshl_add_u64 v[182:183], v[236:237], 0, s[42:43]
	s_mov_b32 m0, s55
	s_nop 0
	global_load_lds_dwordx4 v[182:183], off
	v_lshl_add_u64 v[182:183], v[238:239], 0, s[42:43]
	s_mov_b32 m0, s66
	s_nop 0
	global_load_lds_dwordx4 v[182:183], off
	s_waitcnt vmcnt(8)
	s_waitcnt lgkmcnt(0)
	s_barrier
	s_setprio 1
	s_waitcnt lgkmcnt(0)
	v_mfma_f32_16x16x32_bf16 v[60:63], v[138:141], v[174:177], v[60:63]
	v_mfma_f32_16x16x32_bf16 v[56:59], v[150:153], v[174:177], v[56:59]
	v_mfma_f32_16x16x32_bf16 v[44:47], v[138:141], v[186:189], v[44:47]
	v_mfma_f32_16x16x32_bf16 v[40:43], v[150:153], v[186:189], v[40:43]
	v_mfma_f32_16x16x32_bf16 v[28:31], v[138:141], v[194:197], v[28:31]
	v_mfma_f32_16x16x32_bf16 v[24:27], v[150:153], v[194:197], v[24:27]
	v_mfma_f32_16x16x32_bf16 v[12:15], v[138:141], v[226:229], v[12:15]
	v_mfma_f32_16x16x32_bf16 v[8:11], v[150:153], v[226:229], v[8:11]
	v_mfma_f32_16x16x32_bf16 v[60:63], v[142:145], v[178:181], v[60:63]
	v_mfma_f32_16x16x32_bf16 v[56:59], v[154:157], v[178:181], v[56:59]
	v_mfma_f32_16x16x32_bf16 v[44:47], v[142:145], v[190:193], v[44:47]
	v_mfma_f32_16x16x32_bf16 v[40:43], v[154:157], v[190:193], v[40:43]
	v_mfma_f32_16x16x32_bf16 v[28:31], v[142:145], v[222:225], v[28:31]
	v_mfma_f32_16x16x32_bf16 v[24:27], v[154:157], v[222:225], v[24:27]
	v_mfma_f32_16x16x32_bf16 v[12:15], v[142:145], v[230:233], v[12:15]
	v_mfma_f32_16x16x32_bf16 v[8:11], v[154:157], v[230:233], v[8:11]
	v_mfma_f32_16x16x32_bf16 v[52:55], v[158:161], v[174:177], v[52:55]
	v_mfma_f32_16x16x32_bf16 v[48:51], v[166:169], v[174:177], v[48:51]
	v_mfma_f32_16x16x32_bf16 v[36:39], v[158:161], v[186:189], v[36:39]
	v_mfma_f32_16x16x32_bf16 v[32:35], v[166:169], v[186:189], v[32:35]
	v_mfma_f32_16x16x32_bf16 v[20:23], v[158:161], v[194:197], v[20:23]
	v_mfma_f32_16x16x32_bf16 v[16:19], v[166:169], v[194:197], v[16:19]
	v_mfma_f32_16x16x32_bf16 v[4:7], v[158:161], v[226:229], v[4:7]
	v_mfma_f32_16x16x32_bf16 v[0:3], v[166:169], v[226:229], v[0:3]
	v_mfma_f32_16x16x32_bf16 v[52:55], v[162:165], v[178:181], v[52:55]
	v_mfma_f32_16x16x32_bf16 v[48:51], v[170:173], v[178:181], v[48:51]
	v_mfma_f32_16x16x32_bf16 v[36:39], v[162:165], v[190:193], v[36:39]
	v_mfma_f32_16x16x32_bf16 v[32:35], v[170:173], v[190:193], v[32:35]
	v_mfma_f32_16x16x32_bf16 v[20:23], v[162:165], v[222:225], v[20:23]
	v_mfma_f32_16x16x32_bf16 v[16:19], v[170:173], v[222:225], v[16:19]
	v_mfma_f32_16x16x32_bf16 v[4:7], v[162:165], v[230:233], v[4:7]
	v_mfma_f32_16x16x32_bf16 v[0:3], v[170:173], v[230:233], v[0:3]
	s_setprio 0
	s_barrier
	s_add_i32 s92, s92, 2
	s_add_u32 s82, s82, 0x100
	s_addc_u32 s83, s83, 0
	s_add_u32 s79, s79, 0x100
	s_addc_u32 s81, s81, 0
	s_cmp_gt_u32 s92, 13
	s_cbranch_scc0 .LBB0_651
	s_and_b64 vcc, exec, s[68:69]
	s_cbranch_vccz .LBB0_654
	s_barrier

; #define PG8_STAGE(bufoff, gbase) PG8_STAGEV(bufoff, gbase, voff)
; #define PG8_STAGEB(bufoff, gbase) PG8_STAGEV(bufoff, gbase, voffB)
; #define PG8_LDA(dst, b, h) do { _Pragma("unroll") for (int m = 0; m < 4; ++m) _Pragma("unroll") for (int k = 0; k < 2; ++k) dst[m][k] = *(const LAS bf16x8*)(lds + PG8_SA(b, h) + aoff + m * 2048 + k * 1024); } while (0)
; #define PG8_LDB(dst, b, h) do { _Pragma("unroll") for (int n = 0; n < 2; ++n) _Pragma("unroll") for (int k = 0; k < 2; ++k) dst[n][k] = *(const LAS bf16x8*)(lds + PG8_SB(b, h) + boff + n * 2048 + k * 1024); } while (0)
; #define PG8_MMA(ai, bj, At, Bt) do { __builtin_amdgcn_s_setprio(1); _Pragma("unroll") for (int m = 0; m < 4; ++m) _Pragma("unroll") for (int n = 0; n < 2; ++n) _Pragma("unroll") for (int k = 0; k < 2; ++k) \
;         acc[ai][bj][m][n] = __builtin_amdgcn_mfma_f32_16x16x32_bf16(Bt[n][k], At[m][k], acc[ai][bj][m][n], 0, 0, 0); __builtin_amdgcn_s_setprio(0); } while (0)
; #define PG8_WAIT_V(n) asm volatile("s_waitcnt vmcnt(" #n ")" ::: "memory")
; #define PG8_WAIT_L(n) asm volatile("s_waitcnt lgkmcnt(" #n ")" ::: "memory")
; #define PG8_BAR __builtin_amdgcn_s_barrier()
; #define PG8_SCHED __builtin_amdgcn_sched_barrier(0)
; template <bool PERM, class Epi, class Sched>
; __device__ __forceinline__ void gemm_phase(LAS unsigned char* lds, const int K, const Sched& S, const Epi& E, const int wid0) {
;     ...
;             const bool last = (t == nt - 2);
;             const char* a1 = cA + (size_t)(t + 1) * kstep;
;             const char* a2 = last ? nA : cA + (size_t)(t + 2) * kstep; const char* b2 = last ? nB : cB + (size_t)(t + 2) * kstep;
;             const char* a3 = a2 + kstep; const char* b3 = b2 + kstep;
;             PG8_LDB(B0, 0, 0); PG8_LDB(B1, 0, 1); PG8_SCHED; PG8_LDA(At, 0, 0); PG8_STAGE(PG8_SA(1, 1), a1 + hstep);
;             PG8_WAIT_V(8); PG8_WAIT_L(0); PG8_BAR; PG8_MMA(0, 0, At, B0); PG8_MMA(0, 1, At, B1); PG8_BAR; PG8_SCHED;
;             PG8_LDA(At, 0, 1); PG8_STAGEB(PG8_SB(0, 0), b2); PG8_STAGEB(PG8_SB(0, 1), b2 + hstep); PG8_STAGE(PG8_SA(0, 0), a2);
.LBB0_667:
	s_add_u32 s6, s82, 0xfff80080
	s_addc_u32 s7, s83, -1
	s_add_i32 s16, 0, 0x10000
	s_cmp_eq_u32 s92, 28
	s_cselect_b32 s23, s46, s7
	s_cselect_b32 s22, s48, s6
	s_cselect_b32 s7, s71, s81
	s_cselect_b32 s6, s73, s79
	s_add_i32 s58, 0, 0x14000
	v_add_u32_e32 v154, s16, v147
	v_add_u32_e32 v170, s58, v147
	ds_read_b128 v[138:141], v154
	ds_read_b128 v[142:145], v154 offset:1024
	ds_read_b128 v[150:153], v154 offset:2048
	ds_read_b128 v[154:157], v154 offset:3072
	ds_read_b128 v[158:161], v170
	ds_read_b128 v[162:165], v170 offset:1024
	ds_read_b128 v[166:169], v170 offset:2048
	ds_read_b128 v[170:173], v170 offset:3072
	v_lshl_add_u64 v[182:183], s[82:83], 0, v[134:135]
	s_add_i32 m0, s50, 0xc000
	ds_read_b128 v[174:177], v149
	ds_read_b128 v[178:181], v149 offset:1024
	ds_read_b128 v[186:189], v149 offset:2048
	ds_read_b128 v[190:193], v149 offset:3072
	ds_read_b128 v[194:197], v149 offset:4096
	ds_read_b128 v[222:225], v149 offset:5120
	ds_read_b128 v[226:229], v149 offset:6144
	ds_read_b128 v[230:233], v149 offset:7168
	global_load_lds_dwordx4 v[182:183], off
	v_lshl_add_u64 v[182:183], s[82:83], 0, v[136:137]
	s_add_i32 m0, s50, 0xe000
	s_nop 0
	global_load_lds_dwordx4 v[182:183], off
	s_waitcnt vmcnt(8)
	s_waitcnt lgkmcnt(0)
	s_barrier
	s_setprio 1
	s_waitcnt lgkmcnt(0)
	v_mfma_f32_16x16x32_bf16 v[124:127], v[138:141], v[174:177], v[124:127]
	v_mfma_f32_16x16x32_bf16 v[120:123], v[150:153], v[174:177], v[120:123]
	v_mfma_f32_16x16x32_bf16 v[108:111], v[138:141], v[186:189], v[108:111]
	v_mfma_f32_16x16x32_bf16 v[104:107], v[150:153], v[186:189], v[104:107]
	v_mfma_f32_16x16x32_bf16 v[92:95], v[138:141], v[194:197], v[92:95]
	v_mfma_f32_16x16x32_bf16 v[88:91], v[150:153], v[194:197], v[88:91]
	v_mfma_f32_16x16x32_bf16 v[76:79], v[138:141], v[226:229], v[76:79]
	v_mfma_f32_16x16x32_bf16 v[72:75], v[150:153], v[226:229], v[72:75]
	v_mfma_f32_16x16x32_bf16 v[124:127], v[142:145], v[178:181], v[124:127]
	v_mfma_f32_16x16x32_bf16 v[120:123], v[154:157], v[178:181], v[120:123]
	v_mfma_f32_16x16x32_bf16 v[108:111], v[142:145], v[190:193], v[108:111]
	v_mfma_f32_16x16x32_bf16 v[104:107], v[154:157], v[190:193], v[104:107]
	v_mfma_f32_16x16x32_bf16 v[92:95], v[142:145], v[222:225], v[92:95]
	v_mfma_f32_16x16x32_bf16 v[88:91], v[154:157], v[222:225], v[88:91]
	v_mfma_f32_16x16x32_bf16 v[76:79], v[142:145], v[230:233], v[76:79]
	v_mfma_f32_16x16x32_bf16 v[72:75], v[154:157], v[230:233], v[72:75]
	v_mfma_f32_16x16x32_bf16 v[116:119], v[158:161], v[174:177], v[116:119]
	v_mfma_f32_16x16x32_bf16 v[112:115], v[166:169], v[174:177], v[112:115]
	v_mfma_f32_16x16x32_bf16 v[100:103], v[158:161], v[186:189], v[100:103]
	v_mfma_f32_16x16x32_bf16 v[96:99], v[166:169], v[186:189], v[96:99]
	v_mfma_f32_16x16x32_bf16 v[84:87], v[158:161], v[194:197], v[84:87]
	v_mfma_f32_16x16x32_bf16 v[80:83], v[166:169], v[194:197], v[80:83]
	v_mfma_f32_16x16x32_bf16 v[68:71], v[158:161], v[226:229], v[68:71]
	v_mfma_f32_16x16x32_bf16 v[64:67], v[166:169], v[226:229], v[64:67]
	v_mfma_f32_16x16x32_bf16 v[116:119], v[162:165], v[178:181], v[116:119]
	v_mfma_f32_16x16x32_bf16 v[112:115], v[170:173], v[178:181], v[112:115]
	v_mfma_f32_16x16x32_bf16 v[100:103], v[162:165], v[190:193], v[100:103]
	v_mfma_f32_16x16x32_bf16 v[96:99], v[170:173], v[190:193], v[96:99]
	v_mfma_f32_16x16x32_bf16 v[84:87], v[162:165], v[222:225], v[84:87]
	v_mfma_f32_16x16x32_bf16 v[80:83], v[170:173], v[222:225], v[80:83]
	v_mfma_f32_16x16x32_bf16 v[68:71], v[162:165], v[230:233], v[68:71]
	v_mfma_f32_16x16x32_bf16 v[64:67], v[170:173], v[230:233], v[64:67]
	s_setprio 0
	s_barrier
	s_add_i32 s16, s16, s0
	v_lshl_add_u64 v[182:183], s[6:7], 0, v[184:185]
	s_mov_b32 m0, s16
	ds_read_b128 v[174:177], v149 offset:16384
	ds_read_b128 v[178:181], v149 offset:17408
	ds_read_b128 v[186:189], v149 offset:18432
	ds_read_b128 v[190:193], v149 offset:19456
	ds_read_b128 v[194:197], v149 offset:20480
	ds_read_b128 v[222:225], v149 offset:21504
	ds_read_b128 v[226:229], v149 offset:22528
	ds_read_b128 v[230:233], v149 offset:23552
	global_load_lds_dwordx4 v[182:183], off
	s_add_i32 m0, s16, 0x2000
	s_add_u32 s16, s6, 0x80000
	v_lshl_add_u64 v[234:235], s[6:7], 0, v[128:129]
	s_addc_u32 s17, s7, 0
	s_add_i32 s58, s58, s0
	global_load_lds_dwordx4 v[234:235], off
	v_lshl_add_u64 v[236:237], s[16:17], 0, v[184:185]
	s_mov_b32 m0, s58
	v_lshl_add_u64 v[238:239], s[22:23], 0, v[130:131]
	global_load_lds_dwordx4 v[236:237], off
	v_lshl_add_u64 v[236:237], s[16:17], 0, v[128:129]
	s_add_i32 m0, s58, 0x2000
	s_nop 0
	global_load_lds_dwordx4 v[236:237], off
	v_lshl_add_u64 v[236:237], s[22:23], 0, v[132:133]
	s_mov_b32 m0, s50
	s_nop 0
	global_load_lds_dwordx4 v[236:237], off
	s_mov_b32 m0, s52
	s_nop 0
	global_load_lds_dwordx4 v[238:239], off
	s_waitcnt vmcnt(8)
	s_waitcnt lgkmcnt(0)
	s_barrier
; #define PG8_STAGE(bufoff, gbase) PG8_STAGEV(bufoff, gbase, voff)
; #define PG8_LDA(dst, b, h) do { _Pragma("unroll") for (int m = 0; m < 4; ++m) _Pragma("unroll") for (int k = 0; k < 2; ++k) dst[m][k] = *(const LAS bf16x8*)(lds + PG8_SA(b, h) + aoff + m * 2048 + k * 1024); } while (0)
; #define PG8_LDB(dst, b, h) do { _Pragma("unroll") for (int n = 0; n < 2; ++n) _Pragma("unroll") for (int k = 0; k < 2; ++k) dst[n][k] = *(const LAS bf16x8*)(lds + PG8_SB(b, h) + boff + n * 2048 + k * 1024); } while (0)
; #define PG8_MMA(ai, bj, At, Bt) do { __builtin_amdgcn_s_setprio(1); _Pragma("unroll") for (int m = 0; m < 4; ++m) _Pragma("unroll") for (int n = 0; n < 2; ++n) _Pragma("unroll") for (int k = 0; k < 2; ++k) \
;         acc[ai][bj][m][n] = __builtin_amdgcn_mfma_f32_16x16x32_bf16(Bt[n][k], At[m][k], acc[ai][bj][m][n], 0, 0, 0); __builtin_amdgcn_s_setprio(0); } while (0)
; #define PG8_WAIT_V(n) asm volatile("s_waitcnt vmcnt(" #n ")" ::: "memory")
; #define PG8_WAIT_L(n) asm volatile("s_waitcnt lgkmcnt(" #n ")" ::: "memory")
; #define PG8_BAR __builtin_amdgcn_s_barrier()
; #define PG8_SCHED __builtin_amdgcn_sched_barrier(0)
; template <bool PERM, class Epi, class Sched>
; __device__ __forceinline__ void gemm_phase(LAS unsigned char* lds, const int K, const Sched& S, const Epi& E, const int wid0) {
;     ...
;             PG8_WAIT_V(8); PG8_WAIT_L(0); PG8_BAR; PG8_MMA(1, 0, At, B0); PG8_MMA(1, 1, At, B1); PG8_BAR; PG8_SCHED;
;             PG8_LDB(B0, 1, 0); PG8_LDB(B1, 1, 1); PG8_SCHED; PG8_LDA(At, 1, 0); PG8_STAGE(PG8_SA(0, 1), a2 + hstep);
;             PG8_WAIT_V(8); PG8_WAIT_L(0); PG8_BAR; PG8_MMA(0, 0, At, B0); PG8_MMA(0, 1, At, B1); PG8_BAR; PG8_SCHED;
	s_setprio 1
	s_waitcnt lgkmcnt(0)
	v_mfma_f32_16x16x32_bf16 v[60:63], v[138:141], v[174:177], v[60:63]
	v_mfma_f32_16x16x32_bf16 v[56:59], v[150:153], v[174:177], v[56:59]
	v_mfma_f32_16x16x32_bf16 v[44:47], v[138:141], v[186:189], v[44:47]
	v_mfma_f32_16x16x32_bf16 v[40:43], v[150:153], v[186:189], v[40:43]
	v_mfma_f32_16x16x32_bf16 v[28:31], v[138:141], v[194:197], v[28:31]
	v_mfma_f32_16x16x32_bf16 v[24:27], v[150:153], v[194:197], v[24:27]
	v_mfma_f32_16x16x32_bf16 v[12:15], v[138:141], v[226:229], v[12:15]
	v_mfma_f32_16x16x32_bf16 v[8:11], v[150:153], v[226:229], v[8:11]
	v_mfma_f32_16x16x32_bf16 v[60:63], v[142:145], v[178:181], v[60:63]
	v_mfma_f32_16x16x32_bf16 v[56:59], v[154:157], v[178:181], v[56:59]
	v_mfma_f32_16x16x32_bf16 v[44:47], v[142:145], v[190:193], v[44:47]
	v_mfma_f32_16x16x32_bf16 v[40:43], v[154:157], v[190:193], v[40:43]
	v_mfma_f32_16x16x32_bf16 v[28:31], v[142:145], v[222:225], v[28:31]
	v_mfma_f32_16x16x32_bf16 v[24:27], v[154:157], v[222:225], v[24:27]
	v_mfma_f32_16x16x32_bf16 v[12:15], v[142:145], v[230:233], v[12:15]
	v_mfma_f32_16x16x32_bf16 v[8:11], v[154:157], v[230:233], v[8:11]
	v_mfma_f32_16x16x32_bf16 v[52:55], v[158:161], v[174:177], v[52:55]
	v_mfma_f32_16x16x32_bf16 v[48:51], v[166:169], v[174:177], v[48:51]
	v_mfma_f32_16x16x32_bf16 v[36:39], v[158:161], v[186:189], v[36:39]
	v_mfma_f32_16x16x32_bf16 v[32:35], v[166:169], v[186:189], v[32:35]
	v_mfma_f32_16x16x32_bf16 v[20:23], v[158:161], v[194:197], v[20:23]
	v_mfma_f32_16x16x32_bf16 v[16:19], v[166:169], v[194:197], v[16:19]
	v_mfma_f32_16x16x32_bf16 v[4:7], v[158:161], v[226:229], v[4:7]
	v_mfma_f32_16x16x32_bf16 v[0:3], v[166:169], v[226:229], v[0:3]
	v_mfma_f32_16x16x32_bf16 v[52:55], v[162:165], v[178:181], v[52:55]
	v_mfma_f32_16x16x32_bf16 v[48:51], v[170:173], v[178:181], v[48:51]
	v_mfma_f32_16x16x32_bf16 v[36:39], v[162:165], v[190:193], v[36:39]
	v_mfma_f32_16x16x32_bf16 v[32:35], v[170:173], v[190:193], v[32:35]
	v_mfma_f32_16x16x32_bf16 v[20:23], v[162:165], v[222:225], v[20:23]
	v_mfma_f32_16x16x32_bf16 v[16:19], v[170:173], v[222:225], v[16:19]
	v_mfma_f32_16x16x32_bf16 v[4:7], v[162:165], v[230:233], v[4:7]
	v_mfma_f32_16x16x32_bf16 v[0:3], v[170:173], v[230:233], v[0:3]
	s_setprio 0
	s_barrier
	s_add_i32 s58, 0, 0x18000
	s_add_i32 s59, 0, 0x1c000
	v_add_u32_e32 v154, s58, v147
	v_add_u32_e32 v170, s59, v147
	ds_read_b128 v[138:141], v154
	ds_read_b128 v[142:145], v154 offset:1024
	ds_read_b128 v[150:153], v154 offset:2048
	ds_read_b128 v[154:157], v154 offset:3072
	ds_read_b128 v[158:161], v170
	ds_read_b128 v[162:165], v170 offset:1024
	ds_read_b128 v[166:169], v170 offset:2048
	ds_read_b128 v[170:173], v170 offset:3072
	s_add_u32 s16, s22, 0x80000
	s_addc_u32 s17, s23, 0
	s_mov_b32 m0, s53
	v_lshl_add_u64 v[240:241], s[16:17], 0, v[132:133]
	ds_read_b128 v[174:177], v149 offset:32768
	ds_read_b128 v[178:181], v149 offset:33792
	ds_read_b128 v[186:189], v149 offset:34816
	ds_read_b128 v[190:193], v149 offset:35840
	ds_read_b128 v[194:197], v149 offset:36864
	ds_read_b128 v[222:225], v149 offset:37888
	ds_read_b128 v[226:229], v149 offset:38912
	ds_read_b128 v[230:233], v149 offset:39936
	global_load_lds_dwordx4 v[240:241], off
	v_lshl_add_u64 v[240:241], s[16:17], 0, v[130:131]
	s_mov_b32 m0, s54
	s_nop 0
	global_load_lds_dwordx4 v[240:241], off
	s_waitcnt vmcnt(8)
	s_waitcnt lgkmcnt(0)
	s_barrier
	s_setprio 1
	s_waitcnt lgkmcnt(0)
	v_mfma_f32_16x16x32_bf16 v[124:127], v[138:141], v[174:177], v[124:127]
	v_mfma_f32_16x16x32_bf16 v[120:123], v[150:153], v[174:177], v[120:123]
	v_mfma_f32_16x16x32_bf16 v[108:111], v[138:141], v[186:189], v[108:111]
	v_mfma_f32_16x16x32_bf16 v[104:107], v[150:153], v[186:189], v[104:107]
	v_mfma_f32_16x16x32_bf16 v[92:95], v[138:141], v[194:197], v[92:95]
	v_mfma_f32_16x16x32_bf16 v[88:91], v[150:153], v[194:197], v[88:91]
	v_mfma_f32_16x16x32_bf16 v[76:79], v[138:141], v[226:229], v[76:79]
	v_mfma_f32_16x16x32_bf16 v[72:75], v[150:153], v[226:229], v[72:75]
	v_mfma_f32_16x16x32_bf16 v[124:127], v[142:145], v[178:181], v[124:127]
	v_mfma_f32_16x16x32_bf16 v[120:123], v[154:157], v[178:181], v[120:123]
	v_mfma_f32_16x16x32_bf16 v[108:111], v[142:145], v[190:193], v[108:111]
	v_mfma_f32_16x16x32_bf16 v[104:107], v[154:157], v[190:193], v[104:107]
	v_mfma_f32_16x16x32_bf16 v[92:95], v[142:145], v[222:225], v[92:95]
	v_mfma_f32_16x16x32_bf16 v[88:91], v[154:157], v[222:225], v[88:91]
	v_mfma_f32_16x16x32_bf16 v[76:79], v[142:145], v[230:233], v[76:79]
	v_mfma_f32_16x16x32_bf16 v[72:75], v[154:157], v[230:233], v[72:75]
	v_mfma_f32_16x16x32_bf16 v[116:119], v[158:161], v[174:177], v[116:119]
	v_mfma_f32_16x16x32_bf16 v[112:115], v[166:169], v[174:177], v[112:115]
	v_mfma_f32_16x16x32_bf16 v[100:103], v[158:161], v[186:189], v[100:103]
	v_mfma_f32_16x16x32_bf16 v[96:99], v[166:169], v[186:189], v[96:99]
	v_mfma_f32_16x16x32_bf16 v[84:87], v[158:161], v[194:197], v[84:87]
	v_mfma_f32_16x16x32_bf16 v[80:83], v[166:169], v[194:197], v[80:83]
	v_mfma_f32_16x16x32_bf16 v[68:71], v[158:161], v[226:229], v[68:71]
	v_mfma_f32_16x16x32_bf16 v[64:67], v[166:169], v[226:229], v[64:67]
	v_mfma_f32_16x16x32_bf16 v[116:119], v[162:165], v[178:181], v[116:119]
	v_mfma_f32_16x16x32_bf16 v[112:115], v[170:173], v[178:181], v[112:115]
	v_mfma_f32_16x16x32_bf16 v[100:103], v[162:165], v[190:193], v[100:103]
	v_mfma_f32_16x16x32_bf16 v[96:99], v[170:173], v[190:193], v[96:99]
	v_mfma_f32_16x16x32_bf16 v[84:87], v[162:165], v[222:225], v[84:87]
	v_mfma_f32_16x16x32_bf16 v[80:83], v[170:173], v[222:225], v[80:83]
	v_mfma_f32_16x16x32_bf16 v[68:71], v[162:165], v[230:233], v[68:71]
	v_mfma_f32_16x16x32_bf16 v[64:67], v[170:173], v[230:233], v[64:67]
	s_setprio 0
	s_barrier
; #define PG8_STAGE(bufoff, gbase) PG8_STAGEV(bufoff, gbase, voff)
; #define PG8_STAGEB(bufoff, gbase) PG8_STAGEV(bufoff, gbase, voffB)
; #define PG8_LDA(dst, b, h) do { _Pragma("unroll") for (int m = 0; m < 4; ++m) _Pragma("unroll") for (int k = 0; k < 2; ++k) dst[m][k] = *(const LAS bf16x8*)(lds + PG8_SA(b, h) + aoff + m * 2048 + k * 1024); } while (0)
; #define PG8_MMA(ai, bj, At, Bt) do { __builtin_amdgcn_s_setprio(1); _Pragma("unroll") for (int m = 0; m < 4; ++m) _Pragma("unroll") for (int n = 0; n < 2; ++n) _Pragma("unroll") for (int k = 0; k < 2; ++k) \
;         acc[ai][bj][m][n] = __builtin_amdgcn_mfma_f32_16x16x32_bf16(Bt[n][k], At[m][k], acc[ai][bj][m][n], 0, 0, 0); __builtin_amdgcn_s_setprio(0); } while (0)
; #define PG8_WAIT_V(n) asm volatile("s_waitcnt vmcnt(" #n ")" ::: "memory")
; #define PG8_WAIT_L(n) asm volatile("s_waitcnt lgkmcnt(" #n ")" ::: "memory")
; #define PG8_BAR __builtin_amdgcn_s_barrier()
; #define PG8_SCHED __builtin_amdgcn_sched_barrier(0)
; template <bool PERM, class Epi, class Sched>
; __device__ __forceinline__ void gemm_phase(LAS unsigned char* lds, const int K, const Sched& S, const Epi& E, const int wid0) {
;     ...
;             PG8_LDA(At, 1, 1); PG8_STAGEB(PG8_SB(1, 0), b3); PG8_STAGEB(PG8_SB(1, 1), b3 + hstep); PG8_STAGE(PG8_SA(1, 0), a3);
;             PG8_WAIT_V(8); PG8_WAIT_L(0); PG8_BAR; PG8_MMA(1, 0, At, B0); PG8_MMA(1, 1, At, B1); PG8_BAR; PG8_SCHED;
;         }
;         if (wr == 0) PG8_BAR;
	s_add_i32 s16, s58, s0
	v_lshl_add_u64 v[182:183], v[182:183], 0, s[42:43]
	s_mov_b32 m0, s16
	ds_read_b128 v[174:177], v149 offset:49152
	ds_read_b128 v[178:181], v149 offset:50176
	ds_read_b128 v[186:189], v149 offset:51200
	ds_read_b128 v[190:193], v149 offset:52224
	ds_read_b128 v[194:197], v149 offset:53248
	ds_read_b128 v[222:225], v149 offset:54272
	ds_read_b128 v[226:229], v149 offset:55296
	ds_read_b128 v[230:233], v149 offset:56320
	global_load_lds_dwordx4 v[182:183], off
	s_add_i32 m0, s16, 0x2000
	s_add_u32 s6, s6, 0x80080
	v_lshl_add_u64 v[182:183], v[234:235], 0, s[42:43]
	s_addc_u32 s7, s7, 0
	s_add_i32 s16, s59, s0
	global_load_lds_dwordx4 v[182:183], off
	v_lshl_add_u64 v[182:183], s[6:7], 0, v[184:185]
	s_mov_b32 m0, s16
	s_nop 0
	global_load_lds_dwordx4 v[182:183], off
	v_lshl_add_u64 v[182:183], s[6:7], 0, v[128:129]
	s_add_i32 m0, s16, 0x2000
	s_nop 0
	global_load_lds_dwordx4 v[182:183], off
	v_lshl_add_u64 v[182:183], v[236:237], 0, s[42:43]
	s_mov_b32 m0, s55
	s_nop 0
	global_load_lds_dwordx4 v[182:183], off
	v_lshl_add_u64 v[182:183], v[238:239], 0, s[42:43]
	s_mov_b32 m0, s66
	s_nop 0
	global_load_lds_dwordx4 v[182:183], off
	s_waitcnt vmcnt(8)
	s_waitcnt lgkmcnt(0)
	s_barrier
	s_setprio 1
	s_waitcnt lgkmcnt(0)
	v_mfma_f32_16x16x32_bf16 v[60:63], v[138:141], v[174:177], v[60:63]
	v_mfma_f32_16x16x32_bf16 v[56:59], v[150:153], v[174:177], v[56:59]
	v_mfma_f32_16x16x32_bf16 v[44:47], v[138:141], v[186:189], v[44:47]
	v_mfma_f32_16x16x32_bf16 v[40:43], v[150:153], v[186:189], v[40:43]
	v_mfma_f32_16x16x32_bf16 v[28:31], v[138:141], v[194:197], v[28:31]
	v_mfma_f32_16x16x32_bf16 v[24:27], v[150:153], v[194:197], v[24:27]
	v_mfma_f32_16x16x32_bf16 v[12:15], v[138:141], v[226:229], v[12:15]
	v_mfma_f32_16x16x32_bf16 v[8:11], v[150:153], v[226:229], v[8:11]
	v_mfma_f32_16x16x32_bf16 v[60:63], v[142:145], v[178:181], v[60:63]
	v_mfma_f32_16x16x32_bf16 v[56:59], v[154:157], v[178:181], v[56:59]
	v_mfma_f32_16x16x32_bf16 v[44:47], v[142:145], v[190:193], v[44:47]
	v_mfma_f32_16x16x32_bf16 v[40:43], v[154:157], v[190:193], v[40:43]
	v_mfma_f32_16x16x32_bf16 v[28:31], v[142:145], v[222:225], v[28:31]
	v_mfma_f32_16x16x32_bf16 v[24:27], v[154:157], v[222:225], v[24:27]
	v_mfma_f32_16x16x32_bf16 v[12:15], v[142:145], v[230:233], v[12:15]
	v_mfma_f32_16x16x32_bf16 v[8:11], v[154:157], v[230:233], v[8:11]
	v_mfma_f32_16x16x32_bf16 v[52:55], v[158:161], v[174:177], v[52:55]
	v_mfma_f32_16x16x32_bf16 v[48:51], v[166:169], v[174:177], v[48:51]
	v_mfma_f32_16x16x32_bf16 v[36:39], v[158:161], v[186:189], v[36:39]
	v_mfma_f32_16x16x32_bf16 v[32:35], v[166:169], v[186:189], v[32:35]
	v_mfma_f32_16x16x32_bf16 v[20:23], v[158:161], v[194:197], v[20:23]
	v_mfma_f32_16x16x32_bf16 v[16:19], v[166:169], v[194:197], v[16:19]
	v_mfma_f32_16x16x32_bf16 v[4:7], v[158:161], v[226:229], v[4:7]
	v_mfma_f32_16x16x32_bf16 v[0:3], v[166:169], v[226:229], v[0:3]
	v_mfma_f32_16x16x32_bf16 v[52:55], v[162:165], v[178:181], v[52:55]
	v_mfma_f32_16x16x32_bf16 v[48:51], v[170:173], v[178:181], v[48:51]
	v_mfma_f32_16x16x32_bf16 v[36:39], v[162:165], v[190:193], v[36:39]
	v_mfma_f32_16x16x32_bf16 v[32:35], v[170:173], v[190:193], v[32:35]
	v_mfma_f32_16x16x32_bf16 v[20:23], v[162:165], v[222:225], v[20:23]
	v_mfma_f32_16x16x32_bf16 v[16:19], v[170:173], v[222:225], v[16:19]
	v_mfma_f32_16x16x32_bf16 v[4:7], v[162:165], v[230:233], v[4:7]
	v_mfma_f32_16x16x32_bf16 v[0:3], v[170:173], v[230:233], v[0:3]
	s_setprio 0
	s_barrier
	s_add_i32 s92, s92, 2
	s_add_u32 s82, s82, 0x100
	s_addc_u32 s83, s83, 0
	s_add_u32 s79, s79, 0x100
	s_addc_u32 s81, s81, 0
	s_cmp_gt_u32 s92, 29
	s_cbranch_scc0 .LBB0_667
	s_and_b64 vcc, exec, s[68:69]
	s_cbranch_vccz .LBB0_670
	s_barrier

; #define PG8_STAGE(bufoff, gbase) PG8_STAGEV(bufoff, gbase, voff)
; #define PG8_STAGEB(bufoff, gbase) PG8_STAGEV(bufoff, gbase, voffB)
; #define PG8_LDA(dst, b, h) do { _Pragma("unroll") for (int m = 0; m < 4; ++m) _Pragma("unroll") for (int k = 0; k < 2; ++k) dst[m][k] = *(const LAS bf16x8*)(lds + PG8_SA(b, h) + aoff + m * 2048 + k * 1024); } while (0)
; #define PG8_LDB(dst, b, h) do { _Pragma("unroll") for (int n = 0; n < 2; ++n) _Pragma("unroll") for (int k = 0; k < 2; ++k) dst[n][k] = *(const LAS bf16x8*)(lds + PG8_SB(b, h) + boff + n * 2048 + k * 1024); } while (0)
; #define PG8_MMA(ai, bj, At, Bt) do { __builtin_amdgcn_s_setprio(1); _Pragma("unroll") for (int m = 0; m < 4; ++m) _Pragma("unroll") for (int n = 0; n < 2; ++n) _Pragma("unroll") for (int k = 0; k < 2; ++k) \
;         acc[ai][bj][m][n] = __builtin_amdgcn_mfma_f32_16x16x32_bf16(Bt[n][k], At[m][k], acc[ai][bj][m][n], 0, 0, 0); __builtin_amdgcn_s_setprio(0); } while (0)
; #define PG8_WAIT_V(n) asm volatile("s_waitcnt vmcnt(" #n ")" ::: "memory")
; #define PG8_WAIT_L(n) asm volatile("s_waitcnt lgkmcnt(" #n ")" ::: "memory")
; #define PG8_BAR __builtin_amdgcn_s_barrier()
; #define PG8_SCHED __builtin_amdgcn_sched_barrier(0)
; template <bool PERM, class Epi, class Sched>
; __device__ __forceinline__ void gemm_phase(LAS unsigned char* lds, const int K, const Sched& S, const Epi& E, const int wid0) {
;     ...
;         for (int t = 0; t < nt; t += 2) {
;             const bool last = (t == nt - 2);
;             const char* a1 = cA + (size_t)(t + 1) * kstep;
;             const char* a2 = last ? nA : cA + (size_t)(t + 2) * kstep; const char* b2 = last ? nB : cB + (size_t)(t + 2) * kstep;
;             const char* a3 = a2 + kstep; const char* b3 = b2 + kstep;
;             PG8_LDB(B0, 0, 0); PG8_LDB(B1, 0, 1); PG8_SCHED; PG8_LDA(At, 0, 0); PG8_STAGE(PG8_SA(1, 1), a1 + hstep);
;             PG8_WAIT_V(8); PG8_WAIT_L(0); PG8_BAR; PG8_MMA(0, 0, At, B0); PG8_MMA(0, 1, At, B1); PG8_BAR; PG8_SCHED;
;             PG8_LDA(At, 0, 1); PG8_STAGEB(PG8_SB(0, 0), b2); PG8_STAGEB(PG8_SB(0, 1), b2 + hstep); PG8_STAGE(PG8_SA(0, 0), a2);
.LBB0_735:
	s_add_u32 s16, s82, 0xfff80080
	s_addc_u32 s17, s83, -1
	s_add_i32 s58, 0, 0x10000
	s_cmp_eq_u32 vcc_lo, 28
	s_cselect_b32 s77, s73, s17
	s_cselect_b32 s76, s79, s16
	s_cselect_b32 s23, s71, s93
	s_cselect_b32 s22, s81, s92
	s_add_i32 s59, 0, 0x14000
	v_add_u32_e32 v124, s58, v159
	v_add_u32_e32 v170, s59, v159
	ds_read_b128 v[112:115], v124
	ds_read_b128 v[116:119], v124 offset:1024
	ds_read_b128 v[120:123], v124 offset:2048
	ds_read_b128 v[124:127], v124 offset:3072
	ds_read_b128 v[154:157], v170
	ds_read_b128 v[162:165], v170 offset:1024
	ds_read_b128 v[166:169], v170 offset:2048
	ds_read_b128 v[170:173], v170 offset:3072
	v_lshl_add_u64 v[182:183], s[82:83], 0, v[150:151]
	s_add_i32 m0, s46, 0xc000
	ds_read_b128 v[174:177], v161
	ds_read_b128 v[178:181], v161 offset:1024
	ds_read_b128 v[186:189], v161 offset:2048
	ds_read_b128 v[190:193], v161 offset:3072
	ds_read_b128 v[194:197], v161 offset:4096
	ds_read_b128 v[222:225], v161 offset:5120
	ds_read_b128 v[226:229], v161 offset:6144
	ds_read_b128 v[230:233], v161 offset:7168
	global_load_lds_dwordx4 v[182:183], off
	v_lshl_add_u64 v[182:183], s[82:83], 0, v[152:153]
	s_add_i32 m0, s46, 0xe000
	s_nop 0
	global_load_lds_dwordx4 v[182:183], off
	s_waitcnt vmcnt(8)
	s_waitcnt lgkmcnt(0)
	s_barrier
	s_setprio 1
	s_waitcnt lgkmcnt(0)
	v_mfma_f32_16x16x32_bf16 v[140:143], v[112:115], v[174:177], v[140:143]
	v_mfma_f32_16x16x32_bf16 v[136:139], v[120:123], v[174:177], v[136:139]
	v_mfma_f32_16x16x32_bf16 v[108:111], v[112:115], v[186:189], v[108:111]
	v_mfma_f32_16x16x32_bf16 v[104:107], v[120:123], v[186:189], v[104:107]
	v_mfma_f32_16x16x32_bf16 v[92:95], v[112:115], v[194:197], v[92:95]
	v_mfma_f32_16x16x32_bf16 v[88:91], v[120:123], v[194:197], v[88:91]
	v_mfma_f32_16x16x32_bf16 v[76:79], v[112:115], v[226:229], v[76:79]
	v_mfma_f32_16x16x32_bf16 v[72:75], v[120:123], v[226:229], v[72:75]
	v_mfma_f32_16x16x32_bf16 v[140:143], v[116:119], v[178:181], v[140:143]
	v_mfma_f32_16x16x32_bf16 v[136:139], v[124:127], v[178:181], v[136:139]
	v_mfma_f32_16x16x32_bf16 v[108:111], v[116:119], v[190:193], v[108:111]
	v_mfma_f32_16x16x32_bf16 v[104:107], v[124:127], v[190:193], v[104:107]
	v_mfma_f32_16x16x32_bf16 v[92:95], v[116:119], v[222:225], v[92:95]
	v_mfma_f32_16x16x32_bf16 v[88:91], v[124:127], v[222:225], v[88:91]
	v_mfma_f32_16x16x32_bf16 v[76:79], v[116:119], v[230:233], v[76:79]
	v_mfma_f32_16x16x32_bf16 v[72:75], v[124:127], v[230:233], v[72:75]
	v_mfma_f32_16x16x32_bf16 v[132:135], v[154:157], v[174:177], v[132:135]
	v_mfma_f32_16x16x32_bf16 v[128:131], v[166:169], v[174:177], v[128:131]
	v_mfma_f32_16x16x32_bf16 v[100:103], v[154:157], v[186:189], v[100:103]
	v_mfma_f32_16x16x32_bf16 v[96:99], v[166:169], v[186:189], v[96:99]
	v_mfma_f32_16x16x32_bf16 v[84:87], v[154:157], v[194:197], v[84:87]
	v_mfma_f32_16x16x32_bf16 v[80:83], v[166:169], v[194:197], v[80:83]
	v_mfma_f32_16x16x32_bf16 v[68:71], v[154:157], v[226:229], v[68:71]
	v_mfma_f32_16x16x32_bf16 v[64:67], v[166:169], v[226:229], v[64:67]
	v_mfma_f32_16x16x32_bf16 v[132:135], v[162:165], v[178:181], v[132:135]
	v_mfma_f32_16x16x32_bf16 v[128:131], v[170:173], v[178:181], v[128:131]
	v_mfma_f32_16x16x32_bf16 v[100:103], v[162:165], v[190:193], v[100:103]
	v_mfma_f32_16x16x32_bf16 v[96:99], v[170:173], v[190:193], v[96:99]
	v_mfma_f32_16x16x32_bf16 v[84:87], v[162:165], v[222:225], v[84:87]
	v_mfma_f32_16x16x32_bf16 v[80:83], v[170:173], v[222:225], v[80:83]
	v_mfma_f32_16x16x32_bf16 v[68:71], v[162:165], v[230:233], v[68:71]
	v_mfma_f32_16x16x32_bf16 v[64:67], v[170:173], v[230:233], v[64:67]
	s_setprio 0
	s_barrier
	s_add_i32 s16, s58, s0
	v_lshl_add_u64 v[182:183], s[22:23], 0, v[184:185]
	s_mov_b32 m0, s16
	ds_read_b128 v[174:177], v161 offset:16384
	ds_read_b128 v[178:181], v161 offset:17408
	ds_read_b128 v[186:189], v161 offset:18432
	ds_read_b128 v[190:193], v161 offset:19456
	ds_read_b128 v[194:197], v161 offset:20480
	ds_read_b128 v[222:225], v161 offset:21504
	ds_read_b128 v[226:229], v161 offset:22528
	ds_read_b128 v[230:233], v161 offset:23552
	global_load_lds_dwordx4 v[182:183], off
	s_add_i32 m0, s16, 0x2000
	s_add_u32 s16, s22, 0x80000
	v_lshl_add_u64 v[234:235], s[22:23], 0, v[144:145]
	s_addc_u32 s17, s23, 0
	s_add_i32 s58, s59, s0
	global_load_lds_dwordx4 v[234:235], off
	v_lshl_add_u64 v[236:237], s[16:17], 0, v[184:185]
	s_mov_b32 m0, s58
	v_lshl_add_u64 v[238:239], s[76:77], 0, v[146:147]
	global_load_lds_dwordx4 v[236:237], off
	v_lshl_add_u64 v[236:237], s[16:17], 0, v[144:145]
	s_add_i32 m0, s58, 0x2000
	s_nop 0
	global_load_lds_dwordx4 v[236:237], off
	v_lshl_add_u64 v[236:237], s[76:77], 0, v[148:149]
	s_mov_b32 m0, s46
	s_nop 0
	global_load_lds_dwordx4 v[236:237], off
	s_mov_b32 m0, s48
	s_nop 0
	global_load_lds_dwordx4 v[238:239], off
	s_waitcnt vmcnt(8)
	s_waitcnt lgkmcnt(0)
	s_barrier
; #define PG8_STAGE(bufoff, gbase) PG8_STAGEV(bufoff, gbase, voff)
; #define PG8_LDA(dst, b, h) do { _Pragma("unroll") for (int m = 0; m < 4; ++m) _Pragma("unroll") for (int k = 0; k < 2; ++k) dst[m][k] = *(const LAS bf16x8*)(lds + PG8_SA(b, h) + aoff + m * 2048 + k * 1024); } while (0)
; #define PG8_LDB(dst, b, h) do { _Pragma("unroll") for (int n = 0; n < 2; ++n) _Pragma("unroll") for (int k = 0; k < 2; ++k) dst[n][k] = *(const LAS bf16x8*)(lds + PG8_SB(b, h) + boff + n * 2048 + k * 1024); } while (0)
; #define PG8_MMA(ai, bj, At, Bt) do { __builtin_amdgcn_s_setprio(1); _Pragma("unroll") for (int m = 0; m < 4; ++m) _Pragma("unroll") for (int n = 0; n < 2; ++n) _Pragma("unroll") for (int k = 0; k < 2; ++k) \
;         acc[ai][bj][m][n] = __builtin_amdgcn_mfma_f32_16x16x32_bf16(Bt[n][k], At[m][k], acc[ai][bj][m][n], 0, 0, 0); __builtin_amdgcn_s_setprio(0); } while (0)
; #define PG8_WAIT_V(n) asm volatile("s_waitcnt vmcnt(" #n ")" ::: "memory")
; #define PG8_WAIT_L(n) asm volatile("s_waitcnt lgkmcnt(" #n ")" ::: "memory")
; #define PG8_BAR __builtin_amdgcn_s_barrier()
; #define PG8_SCHED __builtin_amdgcn_sched_barrier(0)
; template <bool PERM, class Epi, class Sched>
; __device__ __forceinline__ void gemm_phase(LAS unsigned char* lds, const int K, const Sched& S, const Epi& E, const int wid0) {
;     ...
;             PG8_WAIT_V(8); PG8_WAIT_L(0); PG8_BAR; PG8_MMA(1, 0, At, B0); PG8_MMA(1, 1, At, B1); PG8_BAR; PG8_SCHED;
;             PG8_LDB(B0, 1, 0); PG8_LDB(B1, 1, 1); PG8_SCHED; PG8_LDA(At, 1, 0); PG8_STAGE(PG8_SA(0, 1), a2 + hstep);
;             PG8_WAIT_V(8); PG8_WAIT_L(0); PG8_BAR; PG8_MMA(0, 0, At, B0); PG8_MMA(0, 1, At, B1); PG8_BAR; PG8_SCHED;
	s_setprio 1
	s_waitcnt lgkmcnt(0)
	v_mfma_f32_16x16x32_bf16 v[60:63], v[112:115], v[174:177], v[60:63]
	v_mfma_f32_16x16x32_bf16 v[56:59], v[120:123], v[174:177], v[56:59]
	v_mfma_f32_16x16x32_bf16 v[52:55], v[112:115], v[186:189], v[52:55]
	v_mfma_f32_16x16x32_bf16 v[44:47], v[120:123], v[186:189], v[44:47]
	v_mfma_f32_16x16x32_bf16 v[36:39], v[112:115], v[194:197], v[36:39]
	v_mfma_f32_16x16x32_bf16 v[28:31], v[120:123], v[194:197], v[28:31]
	v_mfma_f32_16x16x32_bf16 v[20:23], v[112:115], v[226:229], v[20:23]
	v_mfma_f32_16x16x32_bf16 v[12:15], v[120:123], v[226:229], v[12:15]
	v_mfma_f32_16x16x32_bf16 v[60:63], v[116:119], v[178:181], v[60:63]
	v_mfma_f32_16x16x32_bf16 v[56:59], v[124:127], v[178:181], v[56:59]
	v_mfma_f32_16x16x32_bf16 v[52:55], v[116:119], v[190:193], v[52:55]
	v_mfma_f32_16x16x32_bf16 v[44:47], v[124:127], v[190:193], v[44:47]
	v_mfma_f32_16x16x32_bf16 v[36:39], v[116:119], v[222:225], v[36:39]
	v_mfma_f32_16x16x32_bf16 v[28:31], v[124:127], v[222:225], v[28:31]
	v_mfma_f32_16x16x32_bf16 v[20:23], v[116:119], v[230:233], v[20:23]
	v_mfma_f32_16x16x32_bf16 v[12:15], v[124:127], v[230:233], v[12:15]
	v_mfma_f32_16x16x32_bf16 v[48:51], v[154:157], v[174:177], v[48:51]
	v_mfma_f32_16x16x32_bf16 v[40:43], v[166:169], v[174:177], v[40:43]
	v_mfma_f32_16x16x32_bf16 v[32:35], v[154:157], v[186:189], v[32:35]
	v_mfma_f32_16x16x32_bf16 v[24:27], v[166:169], v[186:189], v[24:27]
	v_mfma_f32_16x16x32_bf16 v[16:19], v[154:157], v[194:197], v[16:19]
	v_mfma_f32_16x16x32_bf16 v[8:11], v[166:169], v[194:197], v[8:11]
	v_mfma_f32_16x16x32_bf16 v[4:7], v[154:157], v[226:229], v[4:7]
	v_mfma_f32_16x16x32_bf16 v[0:3], v[166:169], v[226:229], v[0:3]
	v_mfma_f32_16x16x32_bf16 v[48:51], v[162:165], v[178:181], v[48:51]
	v_mfma_f32_16x16x32_bf16 v[40:43], v[170:173], v[178:181], v[40:43]
	v_mfma_f32_16x16x32_bf16 v[32:35], v[162:165], v[190:193], v[32:35]
	v_mfma_f32_16x16x32_bf16 v[24:27], v[170:173], v[190:193], v[24:27]
	v_mfma_f32_16x16x32_bf16 v[16:19], v[162:165], v[222:225], v[16:19]
	v_mfma_f32_16x16x32_bf16 v[8:11], v[170:173], v[222:225], v[8:11]
	v_mfma_f32_16x16x32_bf16 v[4:7], v[162:165], v[230:233], v[4:7]
	v_mfma_f32_16x16x32_bf16 v[0:3], v[170:173], v[230:233], v[0:3]
	s_setprio 0
	s_barrier
	s_add_i32 s58, 0, 0x18000
	s_add_i32 s59, 0, 0x1c000
	v_add_u32_e32 v124, s58, v159
	v_add_u32_e32 v170, s59, v159
	ds_read_b128 v[112:115], v124
	ds_read_b128 v[116:119], v124 offset:1024
	ds_read_b128 v[120:123], v124 offset:2048
	ds_read_b128 v[124:127], v124 offset:3072
	ds_read_b128 v[154:157], v170
	ds_read_b128 v[162:165], v170 offset:1024
	ds_read_b128 v[166:169], v170 offset:2048
	ds_read_b128 v[170:173], v170 offset:3072
	s_add_u32 s16, s76, 0x80000
	s_addc_u32 s17, s77, 0
	s_mov_b32 m0, s50
	v_lshl_add_u64 v[240:241], s[16:17], 0, v[148:149]
	ds_read_b128 v[174:177], v161 offset:32768
	ds_read_b128 v[178:181], v161 offset:33792
	ds_read_b128 v[186:189], v161 offset:34816
	ds_read_b128 v[190:193], v161 offset:35840
	ds_read_b128 v[194:197], v161 offset:36864
	ds_read_b128 v[222:225], v161 offset:37888
	ds_read_b128 v[226:229], v161 offset:38912
	ds_read_b128 v[230:233], v161 offset:39936
	global_load_lds_dwordx4 v[240:241], off
	v_lshl_add_u64 v[240:241], s[16:17], 0, v[146:147]
	s_mov_b32 m0, s52
	s_nop 0
	global_load_lds_dwordx4 v[240:241], off
	s_waitcnt vmcnt(8)
	s_waitcnt lgkmcnt(0)
	s_barrier
	s_setprio 1
	s_waitcnt lgkmcnt(0)
	v_mfma_f32_16x16x32_bf16 v[140:143], v[112:115], v[174:177], v[140:143]
	v_mfma_f32_16x16x32_bf16 v[136:139], v[120:123], v[174:177], v[136:139]
	v_mfma_f32_16x16x32_bf16 v[108:111], v[112:115], v[186:189], v[108:111]
	v_mfma_f32_16x16x32_bf16 v[104:107], v[120:123], v[186:189], v[104:107]
	v_mfma_f32_16x16x32_bf16 v[92:95], v[112:115], v[194:197], v[92:95]
	v_mfma_f32_16x16x32_bf16 v[88:91], v[120:123], v[194:197], v[88:91]
	v_mfma_f32_16x16x32_bf16 v[76:79], v[112:115], v[226:229], v[76:79]
	v_mfma_f32_16x16x32_bf16 v[72:75], v[120:123], v[226:229], v[72:75]
	v_mfma_f32_16x16x32_bf16 v[140:143], v[116:119], v[178:181], v[140:143]
	v_mfma_f32_16x16x32_bf16 v[136:139], v[124:127], v[178:181], v[136:139]
	v_mfma_f32_16x16x32_bf16 v[108:111], v[116:119], v[190:193], v[108:111]
	v_mfma_f32_16x16x32_bf16 v[104:107], v[124:127], v[190:193], v[104:107]
	v_mfma_f32_16x16x32_bf16 v[92:95], v[116:119], v[222:225], v[92:95]
	v_mfma_f32_16x16x32_bf16 v[88:91], v[124:127], v[222:225], v[88:91]
	v_mfma_f32_16x16x32_bf16 v[76:79], v[116:119], v[230:233], v[76:79]
	v_mfma_f32_16x16x32_bf16 v[72:75], v[124:127], v[230:233], v[72:75]
	v_mfma_f32_16x16x32_bf16 v[132:135], v[154:157], v[174:177], v[132:135]
	v_mfma_f32_16x16x32_bf16 v[128:131], v[166:169], v[174:177], v[128:131]
	v_mfma_f32_16x16x32_bf16 v[100:103], v[154:157], v[186:189], v[100:103]
	v_mfma_f32_16x16x32_bf16 v[96:99], v[166:169], v[186:189], v[96:99]
	v_mfma_f32_16x16x32_bf16 v[84:87], v[154:157], v[194:197], v[84:87]
	v_mfma_f32_16x16x32_bf16 v[80:83], v[166:169], v[194:197], v[80:83]
	v_mfma_f32_16x16x32_bf16 v[68:71], v[154:157], v[226:229], v[68:71]
	v_mfma_f32_16x16x32_bf16 v[64:67], v[166:169], v[226:229], v[64:67]
	v_mfma_f32_16x16x32_bf16 v[132:135], v[162:165], v[178:181], v[132:135]
	v_mfma_f32_16x16x32_bf16 v[128:131], v[170:173], v[178:181], v[128:131]
	v_mfma_f32_16x16x32_bf16 v[100:103], v[162:165], v[190:193], v[100:103]
	v_mfma_f32_16x16x32_bf16 v[96:99], v[170:173], v[190:193], v[96:99]
	v_mfma_f32_16x16x32_bf16 v[84:87], v[162:165], v[222:225], v[84:87]
	v_mfma_f32_16x16x32_bf16 v[80:83], v[170:173], v[222:225], v[80:83]
	v_mfma_f32_16x16x32_bf16 v[68:71], v[162:165], v[230:233], v[68:71]
	v_mfma_f32_16x16x32_bf16 v[64:67], v[170:173], v[230:233], v[64:67]
	s_setprio 0
	s_barrier
; #define PG8_STAGE(bufoff, gbase) PG8_STAGEV(bufoff, gbase, voff)
; #define PG8_STAGEB(bufoff, gbase) PG8_STAGEV(bufoff, gbase, voffB)
; #define PG8_LDA(dst, b, h) do { _Pragma("unroll") for (int m = 0; m < 4; ++m) _Pragma("unroll") for (int k = 0; k < 2; ++k) dst[m][k] = *(const LAS bf16x8*)(lds + PG8_SA(b, h) + aoff + m * 2048 + k * 1024); } while (0)
; #define PG8_MMA(ai, bj, At, Bt) do { __builtin_amdgcn_s_setprio(1); _Pragma("unroll") for (int m = 0; m < 4; ++m) _Pragma("unroll") for (int n = 0; n < 2; ++n) _Pragma("unroll") for (int k = 0; k < 2; ++k) \
;         acc[ai][bj][m][n] = __builtin_amdgcn_mfma_f32_16x16x32_bf16(Bt[n][k], At[m][k], acc[ai][bj][m][n], 0, 0, 0); __builtin_amdgcn_s_setprio(0); } while (0)
; #define PG8_WAIT_V(n) asm volatile("s_waitcnt vmcnt(" #n ")" ::: "memory")
; #define PG8_WAIT_L(n) asm volatile("s_waitcnt lgkmcnt(" #n ")" ::: "memory")
; #define PG8_BAR __builtin_amdgcn_s_barrier()
; #define PG8_SCHED __builtin_amdgcn_sched_barrier(0)
; template <bool PERM, class Epi, class Sched>
; __device__ __forceinline__ void gemm_phase(LAS unsigned char* lds, const int K, const Sched& S, const Epi& E, const int wid0) {
;     ...
;             PG8_LDA(At, 1, 1); PG8_STAGEB(PG8_SB(1, 0), b3); PG8_STAGEB(PG8_SB(1, 1), b3 + hstep); PG8_STAGE(PG8_SA(1, 0), a3);
;             PG8_WAIT_V(8); PG8_WAIT_L(0); PG8_BAR; PG8_MMA(1, 0, At, B0); PG8_MMA(1, 1, At, B1); PG8_BAR; PG8_SCHED;
;         }
;         if (wr == 0) PG8_BAR;
	s_add_i32 s16, s58, s0
	v_lshl_add_u64 v[182:183], v[182:183], 0, s[42:43]
	s_mov_b32 m0, s16
	ds_read_b128 v[174:177], v161 offset:49152
	ds_read_b128 v[178:181], v161 offset:50176
	ds_read_b128 v[186:189], v161 offset:51200
	ds_read_b128 v[190:193], v161 offset:52224
	ds_read_b128 v[194:197], v161 offset:53248
	ds_read_b128 v[222:225], v161 offset:54272
	ds_read_b128 v[226:229], v161 offset:55296
	ds_read_b128 v[230:233], v161 offset:56320
	global_load_lds_dwordx4 v[182:183], off
	s_add_i32 m0, s16, 0x2000
	s_add_u32 s16, s22, 0x80080
	v_lshl_add_u64 v[182:183], v[234:235], 0, s[42:43]
	s_addc_u32 s17, s23, 0
	s_add_i32 s22, s59, s0
	global_load_lds_dwordx4 v[182:183], off
	v_lshl_add_u64 v[182:183], s[16:17], 0, v[184:185]
	s_mov_b32 m0, s22
	s_nop 0
	global_load_lds_dwordx4 v[182:183], off
	v_lshl_add_u64 v[182:183], s[16:17], 0, v[144:145]
	s_add_i32 m0, s22, 0x2000
	s_nop 0
	global_load_lds_dwordx4 v[182:183], off
	v_lshl_add_u64 v[182:183], v[236:237], 0, s[42:43]
	s_mov_b32 m0, s55
	s_nop 0
	global_load_lds_dwordx4 v[182:183], off
	v_lshl_add_u64 v[182:183], v[238:239], 0, s[42:43]
	s_mov_b32 m0, s66
	s_nop 0
	global_load_lds_dwordx4 v[182:183], off
	s_waitcnt vmcnt(8)
	s_waitcnt lgkmcnt(0)
	s_barrier
	s_setprio 1
	s_waitcnt lgkmcnt(0)
	v_mfma_f32_16x16x32_bf16 v[60:63], v[112:115], v[174:177], v[60:63]
	v_mfma_f32_16x16x32_bf16 v[56:59], v[120:123], v[174:177], v[56:59]
	v_mfma_f32_16x16x32_bf16 v[52:55], v[112:115], v[186:189], v[52:55]
	v_mfma_f32_16x16x32_bf16 v[44:47], v[120:123], v[186:189], v[44:47]
	v_mfma_f32_16x16x32_bf16 v[36:39], v[112:115], v[194:197], v[36:39]
	v_mfma_f32_16x16x32_bf16 v[28:31], v[120:123], v[194:197], v[28:31]
	v_mfma_f32_16x16x32_bf16 v[20:23], v[112:115], v[226:229], v[20:23]
	v_mfma_f32_16x16x32_bf16 v[12:15], v[120:123], v[226:229], v[12:15]
	v_mfma_f32_16x16x32_bf16 v[60:63], v[116:119], v[178:181], v[60:63]
	v_mfma_f32_16x16x32_bf16 v[56:59], v[124:127], v[178:181], v[56:59]
	v_mfma_f32_16x16x32_bf16 v[52:55], v[116:119], v[190:193], v[52:55]
	v_mfma_f32_16x16x32_bf16 v[44:47], v[124:127], v[190:193], v[44:47]
	v_mfma_f32_16x16x32_bf16 v[36:39], v[116:119], v[222:225], v[36:39]
	v_mfma_f32_16x16x32_bf16 v[28:31], v[124:127], v[222:225], v[28:31]
	v_mfma_f32_16x16x32_bf16 v[20:23], v[116:119], v[230:233], v[20:23]
	v_mfma_f32_16x16x32_bf16 v[12:15], v[124:127], v[230:233], v[12:15]
	v_mfma_f32_16x16x32_bf16 v[48:51], v[154:157], v[174:177], v[48:51]
	v_mfma_f32_16x16x32_bf16 v[40:43], v[166:169], v[174:177], v[40:43]
	v_mfma_f32_16x16x32_bf16 v[32:35], v[154:157], v[186:189], v[32:35]
	v_mfma_f32_16x16x32_bf16 v[24:27], v[166:169], v[186:189], v[24:27]
	v_mfma_f32_16x16x32_bf16 v[16:19], v[154:157], v[194:197], v[16:19]
	v_mfma_f32_16x16x32_bf16 v[8:11], v[166:169], v[194:197], v[8:11]
	v_mfma_f32_16x16x32_bf16 v[4:7], v[154:157], v[226:229], v[4:7]
	v_mfma_f32_16x16x32_bf16 v[0:3], v[166:169], v[226:229], v[0:3]
	v_mfma_f32_16x16x32_bf16 v[48:51], v[162:165], v[178:181], v[48:51]
	v_mfma_f32_16x16x32_bf16 v[40:43], v[170:173], v[178:181], v[40:43]
	v_mfma_f32_16x16x32_bf16 v[32:35], v[162:165], v[190:193], v[32:35]
	v_mfma_f32_16x16x32_bf16 v[24:27], v[170:173], v[190:193], v[24:27]
	v_mfma_f32_16x16x32_bf16 v[16:19], v[162:165], v[222:225], v[16:19]
	v_mfma_f32_16x16x32_bf16 v[8:11], v[170:173], v[222:225], v[8:11]
	v_mfma_f32_16x16x32_bf16 v[4:7], v[162:165], v[230:233], v[4:7]
	v_mfma_f32_16x16x32_bf16 v[0:3], v[170:173], v[230:233], v[0:3]
	s_setprio 0
	s_barrier
	s_add_i32 vcc_lo, vcc_lo, 2
	s_add_u32 s82, s82, 0x100
	s_addc_u32 s83, s83, 0
	s_add_u32 s92, s92, 0x100
	s_addc_u32 s93, s93, 0
	s_cmp_gt_u32 vcc_lo, 29
	s_cbranch_scc0 .LBB0_735
	s_and_b64 vcc, exec, s[68:69]
	s_cbranch_vccz .LBB0_738
	s_barrier

; #define PG8_STAGE(bufoff, gbase) PG8_STAGEV(bufoff, gbase, voff)
; #define PG8_STAGEB(bufoff, gbase) PG8_STAGEV(bufoff, gbase, voffB)
; #define PG8_LDA(dst, b, h) do { _Pragma("unroll") for (int m = 0; m < 4; ++m) _Pragma("unroll") for (int k = 0; k < 2; ++k) dst[m][k] = *(const LAS bf16x8*)(lds + PG8_SA(b, h) + aoff + m * 2048 + k * 1024); } while (0)
; #define PG8_LDB(dst, b, h) do { _Pragma("unroll") for (int n = 0; n < 2; ++n) _Pragma("unroll") for (int k = 0; k < 2; ++k) dst[n][k] = *(const LAS bf16x8*)(lds + PG8_SB(b, h) + boff + n * 2048 + k * 1024); } while (0)
; #define PG8_MMA(ai, bj, At, Bt) do { __builtin_amdgcn_s_setprio(1); _Pragma("unroll") for (int m = 0; m < 4; ++m) _Pragma("unroll") for (int n = 0; n < 2; ++n) _Pragma("unroll") for (int k = 0; k < 2; ++k) \
;         acc[ai][bj][m][n] = __builtin_amdgcn_mfma_f32_16x16x32_bf16(Bt[n][k], At[m][k], acc[ai][bj][m][n], 0, 0, 0); __builtin_amdgcn_s_setprio(0); } while (0)
; #define PG8_WAIT_V(n) asm volatile("s_waitcnt vmcnt(" #n ")" ::: "memory")
; #define PG8_WAIT_L(n) asm volatile("s_waitcnt lgkmcnt(" #n ")" ::: "memory")
; #define PG8_BAR __builtin_amdgcn_s_barrier()
; #define PG8_SCHED __builtin_amdgcn_sched_barrier(0)
; template <bool PERM, class Epi, class Sched>
; __device__ __forceinline__ void gemm_phase(LAS unsigned char* lds, const int K, const Sched& S, const Epi& E, const int wid0) {
;     ...
;         for (int t = 0; t < nt; t += 2) {
;             const bool last = (t == nt - 2);
;             const char* a1 = cA + (size_t)(t + 1) * kstep;
;             const char* a2 = last ? nA : cA + (size_t)(t + 2) * kstep; const char* b2 = last ? nB : cB + (size_t)(t + 2) * kstep;
;             const char* a3 = a2 + kstep; const char* b3 = b2 + kstep;
;             PG8_LDB(B0, 0, 0); PG8_LDB(B1, 0, 1); PG8_SCHED; PG8_LDA(At, 0, 0); PG8_STAGE(PG8_SA(1, 1), a1 + hstep);
;             PG8_WAIT_V(8); PG8_WAIT_L(0); PG8_BAR; PG8_MMA(0, 0, At, B0); PG8_MMA(0, 1, At, B1); PG8_BAR; PG8_SCHED;
;             PG8_LDA(At, 0, 1); PG8_STAGEB(PG8_SB(0, 0), b2); PG8_STAGEB(PG8_SB(0, 1), b2 + hstep); PG8_STAGE(PG8_SA(0, 0), a2);
.LBB0_866:
	s_add_u32 s6, vcc_lo, 0xfff80080
	s_addc_u32 s7, vcc_hi, -1
	s_add_i32 s17, 0, 0x10000
	s_cmp_eq_u32 s16, 28
	s_cselect_b32 s23, s75, s7
	s_cselect_b32 s22, s81, s6
	v_add_u32_e32 v140, s17, v143
	s_cselect_b32 s7, s73, s93
	s_cselect_b32 s6, s83, s92
	s_add_i32 s60, 0, 0x14000
	ds_read_b128 v[146:149], v140
	ds_read_b128 v[150:153], v140 offset:1024
	ds_read_b128 v[154:157], v140 offset:2048
	ds_read_b128 v[158:161], v140 offset:3072
	v_add_u32_e32 v140, s60, v143
	ds_read_b128 v[162:165], v140
	ds_read_b128 v[166:169], v140 offset:1024
	ds_read_b128 v[170:173], v140 offset:2048
	ds_read_b128 v[174:177], v140 offset:3072
	v_lshl_add_u64 v[140:141], vcc, 0, v[136:137]
	s_add_i32 m0, s50, 0xc000
	ds_read_b128 v[178:181], v144
	ds_read_b128 v[186:189], v144 offset:1024
	ds_read_b128 v[190:193], v144 offset:2048
	ds_read_b128 v[194:197], v144 offset:3072
	ds_read_b128 v[222:225], v144 offset:4096
	ds_read_b128 v[226:229], v144 offset:5120
	ds_read_b128 v[230:233], v144 offset:6144
	ds_read_b128 v[234:237], v144 offset:7168
	global_load_lds_dwordx4 v[140:141], off
	v_lshl_add_u64 v[140:141], vcc, 0, v[138:139]
	s_add_i32 m0, s50, 0xe000
	s_nop 0
	global_load_lds_dwordx4 v[140:141], off
	s_waitcnt vmcnt(8)
	s_waitcnt lgkmcnt(0)
	s_barrier
	s_setprio 1
	s_waitcnt lgkmcnt(0)
	v_mfma_f32_16x16x32_bf16 v[124:127], v[146:149], v[178:181], v[124:127]
	v_mfma_f32_16x16x32_bf16 v[120:123], v[154:157], v[178:181], v[120:123]
	v_mfma_f32_16x16x32_bf16 v[108:111], v[146:149], v[190:193], v[108:111]
	v_mfma_f32_16x16x32_bf16 v[104:107], v[154:157], v[190:193], v[104:107]
	v_mfma_f32_16x16x32_bf16 v[92:95], v[146:149], v[222:225], v[92:95]
	v_mfma_f32_16x16x32_bf16 v[88:91], v[154:157], v[222:225], v[88:91]
	v_mfma_f32_16x16x32_bf16 v[76:79], v[146:149], v[230:233], v[76:79]
	v_mfma_f32_16x16x32_bf16 v[72:75], v[154:157], v[230:233], v[72:75]
	v_mfma_f32_16x16x32_bf16 v[124:127], v[150:153], v[186:189], v[124:127]
	v_mfma_f32_16x16x32_bf16 v[120:123], v[158:161], v[186:189], v[120:123]
	v_mfma_f32_16x16x32_bf16 v[108:111], v[150:153], v[194:197], v[108:111]
	v_mfma_f32_16x16x32_bf16 v[104:107], v[158:161], v[194:197], v[104:107]
	v_mfma_f32_16x16x32_bf16 v[92:95], v[150:153], v[226:229], v[92:95]
	v_mfma_f32_16x16x32_bf16 v[88:91], v[158:161], v[226:229], v[88:91]
	v_mfma_f32_16x16x32_bf16 v[76:79], v[150:153], v[234:237], v[76:79]
	v_mfma_f32_16x16x32_bf16 v[72:75], v[158:161], v[234:237], v[72:75]
	v_mfma_f32_16x16x32_bf16 v[116:119], v[162:165], v[178:181], v[116:119]
	v_mfma_f32_16x16x32_bf16 v[112:115], v[170:173], v[178:181], v[112:115]
	v_mfma_f32_16x16x32_bf16 v[100:103], v[162:165], v[190:193], v[100:103]
	v_mfma_f32_16x16x32_bf16 v[96:99], v[170:173], v[190:193], v[96:99]
	v_mfma_f32_16x16x32_bf16 v[84:87], v[162:165], v[222:225], v[84:87]
	v_mfma_f32_16x16x32_bf16 v[80:83], v[170:173], v[222:225], v[80:83]
	v_mfma_f32_16x16x32_bf16 v[68:71], v[162:165], v[230:233], v[68:71]
	v_mfma_f32_16x16x32_bf16 v[64:67], v[170:173], v[230:233], v[64:67]
	v_mfma_f32_16x16x32_bf16 v[116:119], v[166:169], v[186:189], v[116:119]
	v_mfma_f32_16x16x32_bf16 v[112:115], v[174:177], v[186:189], v[112:115]
	v_mfma_f32_16x16x32_bf16 v[100:103], v[166:169], v[194:197], v[100:103]
	v_mfma_f32_16x16x32_bf16 v[96:99], v[174:177], v[194:197], v[96:99]
	v_mfma_f32_16x16x32_bf16 v[84:87], v[166:169], v[226:229], v[84:87]
	v_mfma_f32_16x16x32_bf16 v[80:83], v[174:177], v[226:229], v[80:83]
	v_mfma_f32_16x16x32_bf16 v[68:71], v[166:169], v[234:237], v[68:71]
	v_mfma_f32_16x16x32_bf16 v[64:67], v[174:177], v[234:237], v[64:67]
	s_setprio 0
	s_barrier
	s_add_i32 s17, s17, s11
	v_lshl_add_u64 v[140:141], s[6:7], 0, v[132:133]
	s_mov_b32 m0, s17
	ds_read_b128 v[178:181], v144 offset:16384
	ds_read_b128 v[186:189], v144 offset:17408
	ds_read_b128 v[190:193], v144 offset:18432
	ds_read_b128 v[194:197], v144 offset:19456
	ds_read_b128 v[222:225], v144 offset:20480
	ds_read_b128 v[226:229], v144 offset:21504
	ds_read_b128 v[230:233], v144 offset:22528
	ds_read_b128 v[234:237], v144 offset:23552
	global_load_lds_dwordx4 v[140:141], off
	s_add_i32 m0, s17, 0x2000
	s_add_u32 s58, s6, 0x80000
	v_lshl_add_u64 v[182:183], s[6:7], 0, v[128:129]
	s_addc_u32 s59, s7, 0
	s_add_i32 s17, s60, s11
	global_load_lds_dwordx4 v[182:183], off
	v_lshl_add_u64 v[238:239], s[58:59], 0, v[132:133]
	s_mov_b32 m0, s17
	v_lshl_add_u64 v[240:241], s[22:23], 0, v[130:131]
	global_load_lds_dwordx4 v[238:239], off
	v_lshl_add_u64 v[238:239], s[58:59], 0, v[128:129]
	s_add_i32 m0, s17, 0x2000
	s_nop 0
	global_load_lds_dwordx4 v[238:239], off
	v_lshl_add_u64 v[238:239], s[22:23], 0, v[134:135]
	s_mov_b32 m0, s50
	s_nop 0
	global_load_lds_dwordx4 v[238:239], off
	s_mov_b32 m0, s53
	s_nop 0
	global_load_lds_dwordx4 v[240:241], off
	s_waitcnt vmcnt(8)
	s_waitcnt lgkmcnt(0)
	s_barrier
; #define PG8_STAGE(bufoff, gbase) PG8_STAGEV(bufoff, gbase, voff)
; #define PG8_LDA(dst, b, h) do { _Pragma("unroll") for (int m = 0; m < 4; ++m) _Pragma("unroll") for (int k = 0; k < 2; ++k) dst[m][k] = *(const LAS bf16x8*)(lds + PG8_SA(b, h) + aoff + m * 2048 + k * 1024); } while (0)
; #define PG8_LDB(dst, b, h) do { _Pragma("unroll") for (int n = 0; n < 2; ++n) _Pragma("unroll") for (int k = 0; k < 2; ++k) dst[n][k] = *(const LAS bf16x8*)(lds + PG8_SB(b, h) + boff + n * 2048 + k * 1024); } while (0)
; #define PG8_MMA(ai, bj, At, Bt) do { __builtin_amdgcn_s_setprio(1); _Pragma("unroll") for (int m = 0; m < 4; ++m) _Pragma("unroll") for (int n = 0; n < 2; ++n) _Pragma("unroll") for (int k = 0; k < 2; ++k) \
;         acc[ai][bj][m][n] = __builtin_amdgcn_mfma_f32_16x16x32_bf16(Bt[n][k], At[m][k], acc[ai][bj][m][n], 0, 0, 0); __builtin_amdgcn_s_setprio(0); } while (0)
; #define PG8_WAIT_V(n) asm volatile("s_waitcnt vmcnt(" #n ")" ::: "memory")
; #define PG8_WAIT_L(n) asm volatile("s_waitcnt lgkmcnt(" #n ")" ::: "memory")
; #define PG8_BAR __builtin_amdgcn_s_barrier()
; #define PG8_SCHED __builtin_amdgcn_sched_barrier(0)
; template <bool PERM, class Epi, class Sched>
; __device__ __forceinline__ void gemm_phase(LAS unsigned char* lds, const int K, const Sched& S, const Epi& E, const int wid0) {
;     ...
;             PG8_WAIT_V(8); PG8_WAIT_L(0); PG8_BAR; PG8_MMA(1, 0, At, B0); PG8_MMA(1, 1, At, B1); PG8_BAR; PG8_SCHED;
;             PG8_LDB(B0, 1, 0); PG8_LDB(B1, 1, 1); PG8_SCHED; PG8_LDA(At, 1, 0); PG8_STAGE(PG8_SA(0, 1), a2 + hstep);
;             PG8_WAIT_V(8); PG8_WAIT_L(0); PG8_BAR; PG8_MMA(0, 0, At, B0); PG8_MMA(0, 1, At, B1); PG8_BAR; PG8_SCHED;
	s_setprio 1
	s_waitcnt lgkmcnt(0)
	v_mfma_f32_16x16x32_bf16 v[60:63], v[146:149], v[178:181], v[60:63]
	v_mfma_f32_16x16x32_bf16 v[56:59], v[154:157], v[178:181], v[56:59]
	v_mfma_f32_16x16x32_bf16 v[44:47], v[146:149], v[190:193], v[44:47]
	v_mfma_f32_16x16x32_bf16 v[40:43], v[154:157], v[190:193], v[40:43]
	v_mfma_f32_16x16x32_bf16 v[28:31], v[146:149], v[222:225], v[28:31]
	v_mfma_f32_16x16x32_bf16 v[24:27], v[154:157], v[222:225], v[24:27]
	v_mfma_f32_16x16x32_bf16 v[12:15], v[146:149], v[230:233], v[12:15]
	v_mfma_f32_16x16x32_bf16 v[8:11], v[154:157], v[230:233], v[8:11]
	v_mfma_f32_16x16x32_bf16 v[60:63], v[150:153], v[186:189], v[60:63]
	v_mfma_f32_16x16x32_bf16 v[56:59], v[158:161], v[186:189], v[56:59]
	v_mfma_f32_16x16x32_bf16 v[44:47], v[150:153], v[194:197], v[44:47]
	v_mfma_f32_16x16x32_bf16 v[40:43], v[158:161], v[194:197], v[40:43]
	v_mfma_f32_16x16x32_bf16 v[28:31], v[150:153], v[226:229], v[28:31]
	v_mfma_f32_16x16x32_bf16 v[24:27], v[158:161], v[226:229], v[24:27]
	v_mfma_f32_16x16x32_bf16 v[12:15], v[150:153], v[234:237], v[12:15]
	v_mfma_f32_16x16x32_bf16 v[8:11], v[158:161], v[234:237], v[8:11]
	v_mfma_f32_16x16x32_bf16 v[52:55], v[162:165], v[178:181], v[52:55]
	v_mfma_f32_16x16x32_bf16 v[48:51], v[170:173], v[178:181], v[48:51]
	v_mfma_f32_16x16x32_bf16 v[36:39], v[162:165], v[190:193], v[36:39]
	v_mfma_f32_16x16x32_bf16 v[32:35], v[170:173], v[190:193], v[32:35]
	v_mfma_f32_16x16x32_bf16 v[20:23], v[162:165], v[222:225], v[20:23]
	v_mfma_f32_16x16x32_bf16 v[16:19], v[170:173], v[222:225], v[16:19]
	v_mfma_f32_16x16x32_bf16 v[4:7], v[162:165], v[230:233], v[4:7]
	v_mfma_f32_16x16x32_bf16 v[0:3], v[170:173], v[230:233], v[0:3]
	v_mfma_f32_16x16x32_bf16 v[52:55], v[166:169], v[186:189], v[52:55]
	v_mfma_f32_16x16x32_bf16 v[48:51], v[174:177], v[186:189], v[48:51]
	v_mfma_f32_16x16x32_bf16 v[36:39], v[166:169], v[194:197], v[36:39]
	v_mfma_f32_16x16x32_bf16 v[32:35], v[174:177], v[194:197], v[32:35]
	v_mfma_f32_16x16x32_bf16 v[20:23], v[166:169], v[226:229], v[20:23]
	v_mfma_f32_16x16x32_bf16 v[16:19], v[174:177], v[226:229], v[16:19]
	v_mfma_f32_16x16x32_bf16 v[4:7], v[166:169], v[234:237], v[4:7]
	v_mfma_f32_16x16x32_bf16 v[0:3], v[174:177], v[234:237], v[0:3]
	s_setprio 0
	s_barrier
	s_add_i32 s17, 0, 0x18000
	v_add_u32_e32 v145, s17, v143
	s_add_i32 s58, 0, 0x1c000
	ds_read_b128 v[146:149], v145
	ds_read_b128 v[150:153], v145 offset:1024
	ds_read_b128 v[154:157], v145 offset:2048
	ds_read_b128 v[158:161], v145 offset:3072
	v_add_u32_e32 v145, s58, v143
	ds_read_b128 v[162:165], v145
	ds_read_b128 v[166:169], v145 offset:1024
	ds_read_b128 v[170:173], v145 offset:2048
	ds_read_b128 v[174:177], v145 offset:3072
	s_add_u32 s22, s22, 0x80000
	s_addc_u32 s23, s23, 0
	s_mov_b32 m0, s54
	v_lshl_add_u64 v[242:243], s[22:23], 0, v[134:135]
	ds_read_b128 v[178:181], v144 offset:32768
	ds_read_b128 v[186:189], v144 offset:33792
	ds_read_b128 v[190:193], v144 offset:34816
	ds_read_b128 v[194:197], v144 offset:35840
	ds_read_b128 v[222:225], v144 offset:36864
	ds_read_b128 v[226:229], v144 offset:37888
	ds_read_b128 v[230:233], v144 offset:38912
	ds_read_b128 v[234:237], v144 offset:39936
	global_load_lds_dwordx4 v[242:243], off
	v_lshl_add_u64 v[242:243], s[22:23], 0, v[130:131]
	s_mov_b32 m0, s55
	s_nop 0
	global_load_lds_dwordx4 v[242:243], off
	s_waitcnt vmcnt(8)
	s_waitcnt lgkmcnt(0)
	s_barrier
	s_setprio 1
	s_waitcnt lgkmcnt(0)
	v_mfma_f32_16x16x32_bf16 v[124:127], v[146:149], v[178:181], v[124:127]
	v_mfma_f32_16x16x32_bf16 v[120:123], v[154:157], v[178:181], v[120:123]
	v_mfma_f32_16x16x32_bf16 v[108:111], v[146:149], v[190:193], v[108:111]
	v_mfma_f32_16x16x32_bf16 v[104:107], v[154:157], v[190:193], v[104:107]
	v_mfma_f32_16x16x32_bf16 v[92:95], v[146:149], v[222:225], v[92:95]
	v_mfma_f32_16x16x32_bf16 v[88:91], v[154:157], v[222:225], v[88:91]
	v_mfma_f32_16x16x32_bf16 v[76:79], v[146:149], v[230:233], v[76:79]
	v_mfma_f32_16x16x32_bf16 v[72:75], v[154:157], v[230:233], v[72:75]
	v_mfma_f32_16x16x32_bf16 v[124:127], v[150:153], v[186:189], v[124:127]
	v_mfma_f32_16x16x32_bf16 v[120:123], v[158:161], v[186:189], v[120:123]
	v_mfma_f32_16x16x32_bf16 v[108:111], v[150:153], v[194:197], v[108:111]
	v_mfma_f32_16x16x32_bf16 v[104:107], v[158:161], v[194:197], v[104:107]
	v_mfma_f32_16x16x32_bf16 v[92:95], v[150:153], v[226:229], v[92:95]
	v_mfma_f32_16x16x32_bf16 v[88:91], v[158:161], v[226:229], v[88:91]
	v_mfma_f32_16x16x32_bf16 v[76:79], v[150:153], v[234:237], v[76:79]
	v_mfma_f32_16x16x32_bf16 v[72:75], v[158:161], v[234:237], v[72:75]
	v_mfma_f32_16x16x32_bf16 v[116:119], v[162:165], v[178:181], v[116:119]
	v_mfma_f32_16x16x32_bf16 v[112:115], v[170:173], v[178:181], v[112:115]
	v_mfma_f32_16x16x32_bf16 v[100:103], v[162:165], v[190:193], v[100:103]
	v_mfma_f32_16x16x32_bf16 v[96:99], v[170:173], v[190:193], v[96:99]
	v_mfma_f32_16x16x32_bf16 v[84:87], v[162:165], v[222:225], v[84:87]
	v_mfma_f32_16x16x32_bf16 v[80:83], v[170:173], v[222:225], v[80:83]
	v_mfma_f32_16x16x32_bf16 v[68:71], v[162:165], v[230:233], v[68:71]
	v_mfma_f32_16x16x32_bf16 v[64:67], v[170:173], v[230:233], v[64:67]
	v_mfma_f32_16x16x32_bf16 v[116:119], v[166:169], v[186:189], v[116:119]
	v_mfma_f32_16x16x32_bf16 v[112:115], v[174:177], v[186:189], v[112:115]
	v_mfma_f32_16x16x32_bf16 v[100:103], v[166:169], v[194:197], v[100:103]
	v_mfma_f32_16x16x32_bf16 v[96:99], v[174:177], v[194:197], v[96:99]
	v_mfma_f32_16x16x32_bf16 v[84:87], v[166:169], v[226:229], v[84:87]
	v_mfma_f32_16x16x32_bf16 v[80:83], v[174:177], v[226:229], v[80:83]
	v_mfma_f32_16x16x32_bf16 v[68:71], v[166:169], v[234:237], v[68:71]
	v_mfma_f32_16x16x32_bf16 v[64:67], v[174:177], v[234:237], v[64:67]
	s_setprio 0
	s_barrier
; #define PG8_STAGE(bufoff, gbase) PG8_STAGEV(bufoff, gbase, voff)
; #define PG8_STAGEB(bufoff, gbase) PG8_STAGEV(bufoff, gbase, voffB)
; #define PG8_LDA(dst, b, h) do { _Pragma("unroll") for (int m = 0; m < 4; ++m) _Pragma("unroll") for (int k = 0; k < 2; ++k) dst[m][k] = *(const LAS bf16x8*)(lds + PG8_SA(b, h) + aoff + m * 2048 + k * 1024); } while (0)
; #define PG8_MMA(ai, bj, At, Bt) do { __builtin_amdgcn_s_setprio(1); _Pragma("unroll") for (int m = 0; m < 4; ++m) _Pragma("unroll") for (int n = 0; n < 2; ++n) _Pragma("unroll") for (int k = 0; k < 2; ++k) \
;         acc[ai][bj][m][n] = __builtin_amdgcn_mfma_f32_16x16x32_bf16(Bt[n][k], At[m][k], acc[ai][bj][m][n], 0, 0, 0); __builtin_amdgcn_s_setprio(0); } while (0)
; #define PG8_WAIT_V(n) asm volatile("s_waitcnt vmcnt(" #n ")" ::: "memory")
; #define PG8_WAIT_L(n) asm volatile("s_waitcnt lgkmcnt(" #n ")" ::: "memory")
; #define PG8_BAR __builtin_amdgcn_s_barrier()
; #define PG8_SCHED __builtin_amdgcn_sched_barrier(0)
; template <bool PERM, class Epi, class Sched>
; __device__ __forceinline__ void gemm_phase(LAS unsigned char* lds, const int K, const Sched& S, const Epi& E, const int wid0) {
;     ...
;             PG8_LDA(At, 1, 1); PG8_STAGEB(PG8_SB(1, 0), b3); PG8_STAGEB(PG8_SB(1, 1), b3 + hstep); PG8_STAGE(PG8_SA(1, 0), a3);
;             PG8_WAIT_V(8); PG8_WAIT_L(0); PG8_BAR; PG8_MMA(1, 0, At, B0); PG8_MMA(1, 1, At, B1); PG8_BAR; PG8_SCHED;
;         }
;         if (wr == 0) PG8_BAR;
	s_add_i32 s17, s17, s11
	v_lshl_add_u64 v[140:141], v[140:141], 0, s[42:43]
	s_mov_b32 m0, s17
	ds_read_b128 v[178:181], v144 offset:49152
	ds_read_b128 v[186:189], v144 offset:50176
	ds_read_b128 v[190:193], v144 offset:51200
	ds_read_b128 v[194:197], v144 offset:52224
	ds_read_b128 v[222:225], v144 offset:53248
	ds_read_b128 v[226:229], v144 offset:54272
	ds_read_b128 v[230:233], v144 offset:55296
	ds_read_b128 v[234:237], v144 offset:56320
	global_load_lds_dwordx4 v[140:141], off
	s_add_i32 m0, s17, 0x2000
	s_add_u32 s6, s6, 0x80080
	v_lshl_add_u64 v[140:141], v[182:183], 0, s[42:43]
	s_addc_u32 s7, s7, 0
	s_add_i32 s17, s58, s11
	global_load_lds_dwordx4 v[140:141], off
	v_lshl_add_u64 v[140:141], s[6:7], 0, v[132:133]
	s_mov_b32 m0, s17
	s_nop 0
	global_load_lds_dwordx4 v[140:141], off
	v_lshl_add_u64 v[140:141], s[6:7], 0, v[128:129]
	s_add_i32 m0, s17, 0x2000
	s_nop 0
	global_load_lds_dwordx4 v[140:141], off
	v_lshl_add_u64 v[140:141], v[238:239], 0, s[42:43]
	s_mov_b32 m0, s56
	s_nop 0
	global_load_lds_dwordx4 v[140:141], off
	v_lshl_add_u64 v[140:141], v[240:241], 0, s[42:43]
	s_mov_b32 m0, s66
	s_nop 0
	global_load_lds_dwordx4 v[140:141], off
	s_waitcnt vmcnt(8)
	s_waitcnt lgkmcnt(0)
	s_barrier
	s_setprio 1
	s_waitcnt lgkmcnt(0)
	v_mfma_f32_16x16x32_bf16 v[60:63], v[146:149], v[178:181], v[60:63]
	v_mfma_f32_16x16x32_bf16 v[56:59], v[154:157], v[178:181], v[56:59]
	v_mfma_f32_16x16x32_bf16 v[44:47], v[146:149], v[190:193], v[44:47]
	v_mfma_f32_16x16x32_bf16 v[40:43], v[154:157], v[190:193], v[40:43]
	v_mfma_f32_16x16x32_bf16 v[28:31], v[146:149], v[222:225], v[28:31]
	v_mfma_f32_16x16x32_bf16 v[24:27], v[154:157], v[222:225], v[24:27]
	v_mfma_f32_16x16x32_bf16 v[12:15], v[146:149], v[230:233], v[12:15]
	v_mfma_f32_16x16x32_bf16 v[8:11], v[154:157], v[230:233], v[8:11]
	v_mfma_f32_16x16x32_bf16 v[60:63], v[150:153], v[186:189], v[60:63]
	v_mfma_f32_16x16x32_bf16 v[56:59], v[158:161], v[186:189], v[56:59]
	v_mfma_f32_16x16x32_bf16 v[44:47], v[150:153], v[194:197], v[44:47]
	v_mfma_f32_16x16x32_bf16 v[40:43], v[158:161], v[194:197], v[40:43]
	v_mfma_f32_16x16x32_bf16 v[28:31], v[150:153], v[226:229], v[28:31]
	v_mfma_f32_16x16x32_bf16 v[24:27], v[158:161], v[226:229], v[24:27]
	v_mfma_f32_16x16x32_bf16 v[12:15], v[150:153], v[234:237], v[12:15]
	v_mfma_f32_16x16x32_bf16 v[8:11], v[158:161], v[234:237], v[8:11]
	v_mfma_f32_16x16x32_bf16 v[52:55], v[162:165], v[178:181], v[52:55]
	v_mfma_f32_16x16x32_bf16 v[48:51], v[170:173], v[178:181], v[48:51]
	v_mfma_f32_16x16x32_bf16 v[36:39], v[162:165], v[190:193], v[36:39]
	v_mfma_f32_16x16x32_bf16 v[32:35], v[170:173], v[190:193], v[32:35]
	v_mfma_f32_16x16x32_bf16 v[20:23], v[162:165], v[222:225], v[20:23]
	v_mfma_f32_16x16x32_bf16 v[16:19], v[170:173], v[222:225], v[16:19]
	v_mfma_f32_16x16x32_bf16 v[4:7], v[162:165], v[230:233], v[4:7]
	v_mfma_f32_16x16x32_bf16 v[0:3], v[170:173], v[230:233], v[0:3]
	v_mfma_f32_16x16x32_bf16 v[52:55], v[166:169], v[186:189], v[52:55]
	v_mfma_f32_16x16x32_bf16 v[48:51], v[174:177], v[186:189], v[48:51]
	v_mfma_f32_16x16x32_bf16 v[36:39], v[166:169], v[194:197], v[36:39]
	v_mfma_f32_16x16x32_bf16 v[32:35], v[174:177], v[194:197], v[32:35]
	v_mfma_f32_16x16x32_bf16 v[20:23], v[166:169], v[226:229], v[20:23]
	v_mfma_f32_16x16x32_bf16 v[16:19], v[174:177], v[226:229], v[16:19]
	v_mfma_f32_16x16x32_bf16 v[4:7], v[166:169], v[234:237], v[4:7]
	v_mfma_f32_16x16x32_bf16 v[0:3], v[174:177], v[234:237], v[0:3]
	s_setprio 0
	s_barrier
	s_add_i32 s16, s16, 2
	s_add_u32 vcc_lo, vcc_lo, 0x100
	s_addc_u32 vcc_hi, vcc_hi, 0
	s_add_u32 s92, s92, 0x100
	s_addc_u32 s93, s93, 0
	s_cmp_gt_u32 s16, 29
	s_cbranch_scc0 .LBB0_866
	s_and_b64 vcc, exec, s[70:71]
	s_cbranch_vccz .LBB0_869
	s_barrier

; #define PG8_STAGE(bufoff, gbase) PG8_STAGEV(bufoff, gbase, voff)
; #define PG8_STAGEB(bufoff, gbase) PG8_STAGEV(bufoff, gbase, voffB)
; #define PG8_LDA(dst, b, h) do { _Pragma("unroll") for (int m = 0; m < 4; ++m) _Pragma("unroll") for (int k = 0; k < 2; ++k) dst[m][k] = *(const LAS bf16x8*)(lds + PG8_SA(b, h) + aoff + m * 2048 + k * 1024); } while (0)
; #define PG8_LDB(dst, b, h) do { _Pragma("unroll") for (int n = 0; n < 2; ++n) _Pragma("unroll") for (int k = 0; k < 2; ++k) dst[n][k] = *(const LAS bf16x8*)(lds + PG8_SB(b, h) + boff + n * 2048 + k * 1024); } while (0)
; #define PG8_MMA(ai, bj, At, Bt) do { __builtin_amdgcn_s_setprio(1); _Pragma("unroll") for (int m = 0; m < 4; ++m) _Pragma("unroll") for (int n = 0; n < 2; ++n) _Pragma("unroll") for (int k = 0; k < 2; ++k) \
;         acc[ai][bj][m][n] = __builtin_amdgcn_mfma_f32_16x16x32_bf16(Bt[n][k], At[m][k], acc[ai][bj][m][n], 0, 0, 0); __builtin_amdgcn_s_setprio(0); } while (0)
; #define PG8_WAIT_V(n) asm volatile("s_waitcnt vmcnt(" #n ")" ::: "memory")
; #define PG8_WAIT_L(n) asm volatile("s_waitcnt lgkmcnt(" #n ")" ::: "memory")
; #define PG8_BAR __builtin_amdgcn_s_barrier()
; #define PG8_SCHED __builtin_amdgcn_sched_barrier(0)
; template <bool PERM, class Epi, class Sched>
; __device__ __forceinline__ void gemm_phase(LAS unsigned char* lds, const int K, const Sched& S, const Epi& E, const int wid0) {
;     ...
;         for (int t = 0; t < nt; t += 2) {
;             const bool last = (t == nt - 2);
;             const char* a1 = cA + (size_t)(t + 1) * kstep;
;             const char* a2 = last ? nA : cA + (size_t)(t + 2) * kstep; const char* b2 = last ? nB : cB + (size_t)(t + 2) * kstep;
;             const char* a3 = a2 + kstep; const char* b3 = b2 + kstep;
;             PG8_LDB(B0, 0, 0); PG8_LDB(B1, 0, 1); PG8_SCHED; PG8_LDA(At, 0, 0); PG8_STAGE(PG8_SA(1, 1), a1 + hstep);
;             PG8_WAIT_V(8); PG8_WAIT_L(0); PG8_BAR; PG8_MMA(0, 0, At, B0); PG8_MMA(0, 1, At, B1); PG8_BAR; PG8_SCHED;
;             PG8_LDA(At, 0, 1); PG8_STAGEB(PG8_SB(0, 0), b2); PG8_STAGEB(PG8_SB(0, 1), b2 + hstep); PG8_STAGE(PG8_SA(0, 0), a2);
.LBB0_934:
	s_add_u32 s17, s78, 0xffe00080
	s_addc_u32 s22, s79, -1
	s_add_i32 s58, 0, 0x10000
	s_cmpk_eq_i32 s16, 0x7c
	s_cselect_b32 s81, s69, s22
	s_cselect_b32 s80, s77, s17
	s_cselect_b32 s23, s25, s92
	s_cselect_b32 s22, s82, s83
	s_add_i32 s17, 0, 0x14000
	v_add_u32_e32 v120, s58, v168
	v_add_u32_e32 v166, s17, v168
	ds_read_b128 v[56:59], v120
	ds_read_b128 v[108:111], v120 offset:1024
	ds_read_b128 v[112:115], v120 offset:2048
	ds_read_b128 v[120:123], v120 offset:3072
	ds_read_b128 v[172:175], v166
	ds_read_b128 v[176:179], v166 offset:1024
	ds_read_b128 v[180:183], v166 offset:2048
	ds_read_b128 v[186:189], v166 offset:3072
	v_lshl_add_u64 v[166:167], s[78:79], 0, v[162:163]
	s_add_i32 m0, s48, 0xc000
	ds_read_b128 v[190:193], v170
	ds_read_b128 v[194:197], v170 offset:1024
	ds_read_b128 v[222:225], v170 offset:2048
	ds_read_b128 v[226:229], v170 offset:3072
	ds_read_b128 v[230:233], v170 offset:4096
	ds_read_b128 v[234:237], v170 offset:5120
	ds_read_b128 v[238:241], v170 offset:6144
	ds_read_b128 v[242:245], v170 offset:7168
	global_load_lds_dwordx4 v[166:167], off
	v_lshl_add_u64 v[166:167], s[78:79], 0, v[164:165]
	s_add_i32 m0, s48, 0xe000
	s_nop 0
	global_load_lds_dwordx4 v[166:167], off
	s_waitcnt vmcnt(8)
	s_waitcnt lgkmcnt(0)
	s_barrier
	s_setprio 1
	s_waitcnt lgkmcnt(0)
	v_mfma_f32_16x16x32_bf16 v[140:143], v[56:59], v[190:193], v[140:143]
	v_mfma_f32_16x16x32_bf16 v[136:139], v[112:115], v[190:193], v[136:139]
	v_mfma_f32_16x16x32_bf16 v[128:131], v[56:59], v[222:225], v[128:131]
	v_mfma_f32_16x16x32_bf16 v[116:119], v[112:115], v[222:225], v[116:119]
	v_mfma_f32_16x16x32_bf16 v[100:103], v[56:59], v[230:233], v[100:103]
	v_mfma_f32_16x16x32_bf16 v[92:95], v[112:115], v[230:233], v[92:95]
	v_mfma_f32_16x16x32_bf16 v[84:87], v[56:59], v[238:241], v[84:87]
	v_mfma_f32_16x16x32_bf16 v[76:79], v[112:115], v[238:241], v[76:79]
	v_mfma_f32_16x16x32_bf16 v[140:143], v[108:111], v[194:197], v[140:143]
	v_mfma_f32_16x16x32_bf16 v[136:139], v[120:123], v[194:197], v[136:139]
	v_mfma_f32_16x16x32_bf16 v[128:131], v[108:111], v[226:229], v[128:131]
	v_mfma_f32_16x16x32_bf16 v[116:119], v[120:123], v[226:229], v[116:119]
	v_mfma_f32_16x16x32_bf16 v[100:103], v[108:111], v[234:237], v[100:103]
	v_mfma_f32_16x16x32_bf16 v[92:95], v[120:123], v[234:237], v[92:95]
	v_mfma_f32_16x16x32_bf16 v[84:87], v[108:111], v[242:245], v[84:87]
	v_mfma_f32_16x16x32_bf16 v[76:79], v[120:123], v[242:245], v[76:79]
	v_mfma_f32_16x16x32_bf16 v[132:135], v[172:175], v[190:193], v[132:135]
	v_mfma_f32_16x16x32_bf16 v[124:127], v[180:183], v[190:193], v[124:127]
	v_mfma_f32_16x16x32_bf16 v[104:107], v[172:175], v[222:225], v[104:107]
	v_mfma_f32_16x16x32_bf16 v[96:99], v[180:183], v[222:225], v[96:99]
	v_mfma_f32_16x16x32_bf16 v[88:91], v[172:175], v[230:233], v[88:91]
	v_mfma_f32_16x16x32_bf16 v[80:83], v[180:183], v[230:233], v[80:83]
	v_mfma_f32_16x16x32_bf16 v[72:75], v[172:175], v[238:241], v[72:75]
	v_mfma_f32_16x16x32_bf16 v[68:71], v[180:183], v[238:241], v[68:71]
	v_mfma_f32_16x16x32_bf16 v[132:135], v[176:179], v[194:197], v[132:135]
	v_mfma_f32_16x16x32_bf16 v[124:127], v[186:189], v[194:197], v[124:127]
	v_mfma_f32_16x16x32_bf16 v[104:107], v[176:179], v[226:229], v[104:107]
	v_mfma_f32_16x16x32_bf16 v[96:99], v[186:189], v[226:229], v[96:99]
	v_mfma_f32_16x16x32_bf16 v[88:91], v[176:179], v[234:237], v[88:91]
	v_mfma_f32_16x16x32_bf16 v[80:83], v[186:189], v[234:237], v[80:83]
	v_mfma_f32_16x16x32_bf16 v[72:75], v[176:179], v[242:245], v[72:75]
	v_mfma_f32_16x16x32_bf16 v[68:71], v[186:189], v[242:245], v[68:71]
	s_setprio 0
	s_barrier
	s_add_i32 s58, s58, s18
	v_lshl_add_u64 v[166:167], s[22:23], 0, v[184:185]
	s_mov_b32 m0, s58
	ds_read_b128 v[190:193], v170 offset:16384
	ds_read_b128 v[194:197], v170 offset:17408
	ds_read_b128 v[222:225], v170 offset:18432
	ds_read_b128 v[226:229], v170 offset:19456
	ds_read_b128 v[230:233], v170 offset:20480
	ds_read_b128 v[234:237], v170 offset:21504
	ds_read_b128 v[238:241], v170 offset:22528
	ds_read_b128 v[242:245], v170 offset:23552
	global_load_lds_dwordx4 v[166:167], off
	s_add_i32 m0, s58, 0x2000
	s_add_u32 s58, s22, 0x200000
	v_lshl_add_u64 v[246:247], s[22:23], 0, v[144:145]
	s_addc_u32 s59, s23, 0
	s_add_i32 s17, s17, s18
	global_load_lds_dwordx4 v[246:247], off
	v_lshl_add_u64 v[248:249], s[58:59], 0, v[184:185]
	s_mov_b32 m0, s17
	v_lshl_add_u64 v[250:251], s[80:81], 0, v[144:145]
	global_load_lds_dwordx4 v[248:249], off
	v_lshl_add_u64 v[248:249], s[58:59], 0, v[144:145]
	s_add_i32 m0, s17, 0x2000
	s_nop 0
	global_load_lds_dwordx4 v[248:249], off
	v_lshl_add_u64 v[248:249], s[80:81], 0, v[184:185]
	s_mov_b32 m0, s48
	s_nop 0
	global_load_lds_dwordx4 v[248:249], off
	s_mov_b32 m0, s50
	s_nop 0
	global_load_lds_dwordx4 v[250:251], off
	s_waitcnt vmcnt(8)
	s_waitcnt lgkmcnt(0)
	s_barrier
; #define PG8_STAGE(bufoff, gbase) PG8_STAGEV(bufoff, gbase, voff)
; #define PG8_LDA(dst, b, h) do { _Pragma("unroll") for (int m = 0; m < 4; ++m) _Pragma("unroll") for (int k = 0; k < 2; ++k) dst[m][k] = *(const LAS bf16x8*)(lds + PG8_SA(b, h) + aoff + m * 2048 + k * 1024); } while (0)
; #define PG8_LDB(dst, b, h) do { _Pragma("unroll") for (int n = 0; n < 2; ++n) _Pragma("unroll") for (int k = 0; k < 2; ++k) dst[n][k] = *(const LAS bf16x8*)(lds + PG8_SB(b, h) + boff + n * 2048 + k * 1024); } while (0)
; #define PG8_MMA(ai, bj, At, Bt) do { __builtin_amdgcn_s_setprio(1); _Pragma("unroll") for (int m = 0; m < 4; ++m) _Pragma("unroll") for (int n = 0; n < 2; ++n) _Pragma("unroll") for (int k = 0; k < 2; ++k) \
;         acc[ai][bj][m][n] = __builtin_amdgcn_mfma_f32_16x16x32_bf16(Bt[n][k], At[m][k], acc[ai][bj][m][n], 0, 0, 0); __builtin_amdgcn_s_setprio(0); } while (0)
; #define PG8_WAIT_V(n) asm volatile("s_waitcnt vmcnt(" #n ")" ::: "memory")
; #define PG8_WAIT_L(n) asm volatile("s_waitcnt lgkmcnt(" #n ")" ::: "memory")
; #define PG8_BAR __builtin_amdgcn_s_barrier()
; #define PG8_SCHED __builtin_amdgcn_sched_barrier(0)
; template <bool PERM, class Epi, class Sched>
; __device__ __forceinline__ void gemm_phase(LAS unsigned char* lds, const int K, const Sched& S, const Epi& E, const int wid0) {
;     ...
;             PG8_WAIT_V(8); PG8_WAIT_L(0); PG8_BAR; PG8_MMA(1, 0, At, B0); PG8_MMA(1, 1, At, B1); PG8_BAR; PG8_SCHED;
;             PG8_LDB(B0, 1, 0); PG8_LDB(B1, 1, 1); PG8_SCHED; PG8_LDA(At, 1, 0); PG8_STAGE(PG8_SA(0, 1), a2 + hstep);
;             PG8_WAIT_V(8); PG8_WAIT_L(0); PG8_BAR; PG8_MMA(0, 0, At, B0); PG8_MMA(0, 1, At, B1); PG8_BAR; PG8_SCHED;
	s_setprio 1
	s_waitcnt lgkmcnt(0)
	v_mfma_f32_16x16x32_bf16 v[64:67], v[56:59], v[190:193], v[64:67]
	v_mfma_f32_16x16x32_bf16 v[60:63], v[112:115], v[190:193], v[60:63]
	v_mfma_f32_16x16x32_bf16 v[44:47], v[56:59], v[222:225], v[44:47]
	v_mfma_f32_16x16x32_bf16 v[40:43], v[112:115], v[222:225], v[40:43]
	v_mfma_f32_16x16x32_bf16 v[28:31], v[56:59], v[230:233], v[28:31]
	v_mfma_f32_16x16x32_bf16 v[24:27], v[112:115], v[230:233], v[24:27]
	v_mfma_f32_16x16x32_bf16 v[12:15], v[56:59], v[238:241], v[12:15]
	v_mfma_f32_16x16x32_bf16 v[8:11], v[112:115], v[238:241], v[8:11]
	v_mfma_f32_16x16x32_bf16 v[64:67], v[108:111], v[194:197], v[64:67]
	v_mfma_f32_16x16x32_bf16 v[60:63], v[120:123], v[194:197], v[60:63]
	v_mfma_f32_16x16x32_bf16 v[44:47], v[108:111], v[226:229], v[44:47]
	v_mfma_f32_16x16x32_bf16 v[40:43], v[120:123], v[226:229], v[40:43]
	v_mfma_f32_16x16x32_bf16 v[28:31], v[108:111], v[234:237], v[28:31]
	v_mfma_f32_16x16x32_bf16 v[24:27], v[120:123], v[234:237], v[24:27]
	v_mfma_f32_16x16x32_bf16 v[12:15], v[108:111], v[242:245], v[12:15]
	v_mfma_f32_16x16x32_bf16 v[8:11], v[120:123], v[242:245], v[8:11]
	v_mfma_f32_16x16x32_bf16 v[52:55], v[172:175], v[190:193], v[52:55]
	v_mfma_f32_16x16x32_bf16 v[48:51], v[180:183], v[190:193], v[48:51]
	v_mfma_f32_16x16x32_bf16 v[36:39], v[172:175], v[222:225], v[36:39]
	v_mfma_f32_16x16x32_bf16 v[32:35], v[180:183], v[222:225], v[32:35]
	v_mfma_f32_16x16x32_bf16 v[20:23], v[172:175], v[230:233], v[20:23]
	v_mfma_f32_16x16x32_bf16 v[16:19], v[180:183], v[230:233], v[16:19]
	v_mfma_f32_16x16x32_bf16 v[4:7], v[172:175], v[238:241], v[4:7]
	v_mfma_f32_16x16x32_bf16 v[0:3], v[180:183], v[238:241], v[0:3]
	v_mfma_f32_16x16x32_bf16 v[52:55], v[176:179], v[194:197], v[52:55]
	v_mfma_f32_16x16x32_bf16 v[48:51], v[186:189], v[194:197], v[48:51]
	v_mfma_f32_16x16x32_bf16 v[36:39], v[176:179], v[226:229], v[36:39]
	v_mfma_f32_16x16x32_bf16 v[32:35], v[186:189], v[226:229], v[32:35]
	v_mfma_f32_16x16x32_bf16 v[20:23], v[176:179], v[234:237], v[20:23]
	v_mfma_f32_16x16x32_bf16 v[16:19], v[186:189], v[234:237], v[16:19]
	v_mfma_f32_16x16x32_bf16 v[4:7], v[176:179], v[242:245], v[4:7]
	v_mfma_f32_16x16x32_bf16 v[0:3], v[186:189], v[242:245], v[0:3]
	s_setprio 0
	s_barrier
	s_add_i32 s17, 0, 0x18000
	s_add_i32 s60, 0, 0x1c000
	v_add_u32_e32 v120, s17, v168
	v_add_u32_e32 v171, s60, v168
	ds_read_b128 v[56:59], v120
	ds_read_b128 v[108:111], v120 offset:1024
	ds_read_b128 v[112:115], v120 offset:2048
	ds_read_b128 v[120:123], v120 offset:3072
	ds_read_b128 v[172:175], v171
	ds_read_b128 v[176:179], v171 offset:1024
	ds_read_b128 v[180:183], v171 offset:2048
	ds_read_b128 v[186:189], v171 offset:3072
	s_add_u32 s58, s80, 0x200000
	s_addc_u32 s59, s81, 0
	s_mov_b32 m0, s53
	v_lshl_add_u64 v[218:219], s[58:59], 0, v[184:185]
	ds_read_b128 v[190:193], v170 offset:32768
	ds_read_b128 v[194:197], v170 offset:33792
	ds_read_b128 v[222:225], v170 offset:34816
	ds_read_b128 v[226:229], v170 offset:35840
	ds_read_b128 v[230:233], v170 offset:36864
	ds_read_b128 v[234:237], v170 offset:37888
	ds_read_b128 v[238:241], v170 offset:38912
	ds_read_b128 v[242:245], v170 offset:39936
	global_load_lds_dwordx4 v[218:219], off
	v_lshl_add_u64 v[218:219], s[58:59], 0, v[144:145]
	s_mov_b32 m0, s54
	s_nop 0
	global_load_lds_dwordx4 v[218:219], off
	s_waitcnt vmcnt(8)
	s_waitcnt lgkmcnt(0)
	s_barrier
	s_setprio 1
	s_waitcnt lgkmcnt(0)
	v_mfma_f32_16x16x32_bf16 v[140:143], v[56:59], v[190:193], v[140:143]
	v_mfma_f32_16x16x32_bf16 v[136:139], v[112:115], v[190:193], v[136:139]
	v_mfma_f32_16x16x32_bf16 v[128:131], v[56:59], v[222:225], v[128:131]
	v_mfma_f32_16x16x32_bf16 v[116:119], v[112:115], v[222:225], v[116:119]
	v_mfma_f32_16x16x32_bf16 v[100:103], v[56:59], v[230:233], v[100:103]
	v_mfma_f32_16x16x32_bf16 v[92:95], v[112:115], v[230:233], v[92:95]
	v_mfma_f32_16x16x32_bf16 v[84:87], v[56:59], v[238:241], v[84:87]
	v_mfma_f32_16x16x32_bf16 v[76:79], v[112:115], v[238:241], v[76:79]
	v_mfma_f32_16x16x32_bf16 v[140:143], v[108:111], v[194:197], v[140:143]
	v_mfma_f32_16x16x32_bf16 v[136:139], v[120:123], v[194:197], v[136:139]
	v_mfma_f32_16x16x32_bf16 v[128:131], v[108:111], v[226:229], v[128:131]
	v_mfma_f32_16x16x32_bf16 v[116:119], v[120:123], v[226:229], v[116:119]
	v_mfma_f32_16x16x32_bf16 v[100:103], v[108:111], v[234:237], v[100:103]
	v_mfma_f32_16x16x32_bf16 v[92:95], v[120:123], v[234:237], v[92:95]
	v_mfma_f32_16x16x32_bf16 v[84:87], v[108:111], v[242:245], v[84:87]
	v_mfma_f32_16x16x32_bf16 v[76:79], v[120:123], v[242:245], v[76:79]
	v_mfma_f32_16x16x32_bf16 v[132:135], v[172:175], v[190:193], v[132:135]
	v_mfma_f32_16x16x32_bf16 v[124:127], v[180:183], v[190:193], v[124:127]
	v_mfma_f32_16x16x32_bf16 v[104:107], v[172:175], v[222:225], v[104:107]
	v_mfma_f32_16x16x32_bf16 v[96:99], v[180:183], v[222:225], v[96:99]
	v_mfma_f32_16x16x32_bf16 v[88:91], v[172:175], v[230:233], v[88:91]
	v_mfma_f32_16x16x32_bf16 v[80:83], v[180:183], v[230:233], v[80:83]
	v_mfma_f32_16x16x32_bf16 v[72:75], v[172:175], v[238:241], v[72:75]
	v_mfma_f32_16x16x32_bf16 v[68:71], v[180:183], v[238:241], v[68:71]
	v_mfma_f32_16x16x32_bf16 v[132:135], v[176:179], v[194:197], v[132:135]
	v_mfma_f32_16x16x32_bf16 v[124:127], v[186:189], v[194:197], v[124:127]
	v_mfma_f32_16x16x32_bf16 v[104:107], v[176:179], v[226:229], v[104:107]
	v_mfma_f32_16x16x32_bf16 v[96:99], v[186:189], v[226:229], v[96:99]
	v_mfma_f32_16x16x32_bf16 v[88:91], v[176:179], v[234:237], v[88:91]
	v_mfma_f32_16x16x32_bf16 v[80:83], v[186:189], v[234:237], v[80:83]
	v_mfma_f32_16x16x32_bf16 v[72:75], v[176:179], v[242:245], v[72:75]
	v_mfma_f32_16x16x32_bf16 v[68:71], v[186:189], v[242:245], v[68:71]
	s_setprio 0
	s_barrier
; #define PG8_STAGE(bufoff, gbase) PG8_STAGEV(bufoff, gbase, voff)
; #define PG8_STAGEB(bufoff, gbase) PG8_STAGEV(bufoff, gbase, voffB)
; #define PG8_LDA(dst, b, h) do { _Pragma("unroll") for (int m = 0; m < 4; ++m) _Pragma("unroll") for (int k = 0; k < 2; ++k) dst[m][k] = *(const LAS bf16x8*)(lds + PG8_SA(b, h) + aoff + m * 2048 + k * 1024); } while (0)
; #define PG8_MMA(ai, bj, At, Bt) do { __builtin_amdgcn_s_setprio(1); _Pragma("unroll") for (int m = 0; m < 4; ++m) _Pragma("unroll") for (int n = 0; n < 2; ++n) _Pragma("unroll") for (int k = 0; k < 2; ++k) \
;         acc[ai][bj][m][n] = __builtin_amdgcn_mfma_f32_16x16x32_bf16(Bt[n][k], At[m][k], acc[ai][bj][m][n], 0, 0, 0); __builtin_amdgcn_s_setprio(0); } while (0)
; #define PG8_WAIT_V(n) asm volatile("s_waitcnt vmcnt(" #n ")" ::: "memory")
; #define PG8_WAIT_L(n) asm volatile("s_waitcnt lgkmcnt(" #n ")" ::: "memory")
; #define PG8_BAR __builtin_amdgcn_s_barrier()
; #define PG8_SCHED __builtin_amdgcn_sched_barrier(0)
; template <bool PERM, class Epi, class Sched>
; __device__ __forceinline__ void gemm_phase(LAS unsigned char* lds, const int K, const Sched& S, const Epi& E, const int wid0) {
;     ...
;             PG8_LDA(At, 1, 1); PG8_STAGEB(PG8_SB(1, 0), b3); PG8_STAGEB(PG8_SB(1, 1), b3 + hstep); PG8_STAGE(PG8_SA(1, 0), a3);
;             PG8_WAIT_V(8); PG8_WAIT_L(0); PG8_BAR; PG8_MMA(1, 0, At, B0); PG8_MMA(1, 1, At, B1); PG8_BAR; PG8_SCHED;
;         }
;         if (wr == 0) PG8_BAR;
	s_add_i32 s17, s17, s18
	v_lshl_add_u64 v[166:167], v[166:167], 0, s[42:43]
	s_mov_b32 m0, s17
	ds_read_b128 v[190:193], v170 offset:49152
	ds_read_b128 v[194:197], v170 offset:50176
	ds_read_b128 v[222:225], v170 offset:51200
	ds_read_b128 v[226:229], v170 offset:52224
	ds_read_b128 v[230:233], v170 offset:53248
	ds_read_b128 v[234:237], v170 offset:54272
	ds_read_b128 v[238:241], v170 offset:55296
	ds_read_b128 v[242:245], v170 offset:56320
	global_load_lds_dwordx4 v[166:167], off
	s_add_i32 m0, s17, 0x2000
	s_add_u32 s22, s22, 0x200080
	v_lshl_add_u64 v[166:167], v[246:247], 0, s[42:43]
	s_addc_u32 s23, s23, 0
	s_add_i32 s17, s60, s18
	global_load_lds_dwordx4 v[166:167], off
	v_lshl_add_u64 v[166:167], s[22:23], 0, v[184:185]
	s_mov_b32 m0, s17
	s_nop 0
	global_load_lds_dwordx4 v[166:167], off
	v_lshl_add_u64 v[166:167], s[22:23], 0, v[144:145]
	s_add_i32 m0, s17, 0x2000
	s_nop 0
	global_load_lds_dwordx4 v[166:167], off
	v_lshl_add_u64 v[166:167], v[248:249], 0, s[42:43]
	s_mov_b32 m0, s66
	s_nop 0
	global_load_lds_dwordx4 v[166:167], off
	v_lshl_add_u64 v[166:167], v[250:251], 0, s[42:43]
	s_mov_b32 m0, s67
	s_nop 0
	global_load_lds_dwordx4 v[166:167], off
	s_waitcnt vmcnt(8)
	s_waitcnt lgkmcnt(0)
	s_barrier
	s_setprio 1
	s_waitcnt lgkmcnt(0)
	v_mfma_f32_16x16x32_bf16 v[64:67], v[56:59], v[190:193], v[64:67]
	v_mfma_f32_16x16x32_bf16 v[60:63], v[112:115], v[190:193], v[60:63]
	v_mfma_f32_16x16x32_bf16 v[44:47], v[56:59], v[222:225], v[44:47]
	v_mfma_f32_16x16x32_bf16 v[40:43], v[112:115], v[222:225], v[40:43]
	v_mfma_f32_16x16x32_bf16 v[28:31], v[56:59], v[230:233], v[28:31]
	v_mfma_f32_16x16x32_bf16 v[24:27], v[112:115], v[230:233], v[24:27]
	v_mfma_f32_16x16x32_bf16 v[12:15], v[56:59], v[238:241], v[12:15]
	v_mfma_f32_16x16x32_bf16 v[8:11], v[112:115], v[238:241], v[8:11]
	v_mfma_f32_16x16x32_bf16 v[64:67], v[108:111], v[194:197], v[64:67]
	v_mfma_f32_16x16x32_bf16 v[60:63], v[120:123], v[194:197], v[60:63]
	v_mfma_f32_16x16x32_bf16 v[44:47], v[108:111], v[226:229], v[44:47]
	v_mfma_f32_16x16x32_bf16 v[40:43], v[120:123], v[226:229], v[40:43]
	v_mfma_f32_16x16x32_bf16 v[28:31], v[108:111], v[234:237], v[28:31]
	v_mfma_f32_16x16x32_bf16 v[24:27], v[120:123], v[234:237], v[24:27]
	v_mfma_f32_16x16x32_bf16 v[12:15], v[108:111], v[242:245], v[12:15]
	v_mfma_f32_16x16x32_bf16 v[8:11], v[120:123], v[242:245], v[8:11]
	v_mfma_f32_16x16x32_bf16 v[52:55], v[172:175], v[190:193], v[52:55]
	v_mfma_f32_16x16x32_bf16 v[48:51], v[180:183], v[190:193], v[48:51]
	v_mfma_f32_16x16x32_bf16 v[36:39], v[172:175], v[222:225], v[36:39]
	v_mfma_f32_16x16x32_bf16 v[32:35], v[180:183], v[222:225], v[32:35]
	v_mfma_f32_16x16x32_bf16 v[20:23], v[172:175], v[230:233], v[20:23]
	v_mfma_f32_16x16x32_bf16 v[16:19], v[180:183], v[230:233], v[16:19]
	v_mfma_f32_16x16x32_bf16 v[4:7], v[172:175], v[238:241], v[4:7]
	v_mfma_f32_16x16x32_bf16 v[0:3], v[180:183], v[238:241], v[0:3]
	v_mfma_f32_16x16x32_bf16 v[52:55], v[176:179], v[194:197], v[52:55]
	v_mfma_f32_16x16x32_bf16 v[48:51], v[186:189], v[194:197], v[48:51]
	v_mfma_f32_16x16x32_bf16 v[36:39], v[176:179], v[226:229], v[36:39]
	v_mfma_f32_16x16x32_bf16 v[32:35], v[186:189], v[226:229], v[32:35]
	v_mfma_f32_16x16x32_bf16 v[20:23], v[176:179], v[234:237], v[20:23]
	v_mfma_f32_16x16x32_bf16 v[16:19], v[186:189], v[234:237], v[16:19]
	v_mfma_f32_16x16x32_bf16 v[4:7], v[176:179], v[242:245], v[4:7]
	v_mfma_f32_16x16x32_bf16 v[0:3], v[186:189], v[242:245], v[0:3]
	s_setprio 0
	s_barrier
	s_add_i32 s16, s16, 2
	s_add_u32 s78, s78, 0x100
	s_addc_u32 s79, s79, 0
	s_add_u32 s83, s83, 0x100
	s_addc_u32 s92, s92, 0
	s_cmpk_gt_u32 s16, 0x7d
	s_cbranch_scc0 .LBB0_934
	s_and_b64 vcc, exec, s[8:9]
	s_cbranch_vccz .LBB0_937
	s_barrier
